# norm1/norm2 phases: three rows (x plus shift/scale vectors) in flight per wave, scalar row addressing, DPP wave sum
# baseline (speedup 1.0000x reference)
; DI void modnorm_rows(const Params& p, int l, int which  , bool from_inputs, bool skip_ctx, int w0, int wstride, int lane) {
;   const float* g = (which ? p.norm2_g : p.norm1_g) + l * DM;
;   f32x4 gg[4];
; #pragma unroll
;   for (int i = 0; i < 4; ++i) gg[i] = *(const f32x4*)(g + i * 256 + lane * 4);
;   const int nrows = skip_ctx ? 8 * NLAT : T_TOK;
;   auto rowof = [&](int i) -> int { return skip_ctx ? (i / NLAT) * TB + NCTX + (i % NLAT) : i; };
;   int i = w0;
;   if (i >= nrows) return;
;   f32x4 vn[4];
;   {
;     const int row = rowof(i); const float* src = xsrc_row(p, from_inputs, row / TB, row % TB);
; #pragma unroll
;     for (int q = 0; q < 4; ++q) vn[q] = *(const f32x4*)(src + q * 256 + lane * 4);
;   }
;   for (; i < nrows; i += wstride) {
;     const int row = rowof(i); const int b = row / TB, s = row % TB;
;     f32x4 v[4];
; #pragma unroll
;     for (int q = 0; q < 4; ++q) v[q] = vn[q];
;     if (i + wstride < nrows) {
;       const int rn = rowof(i + wstride); const float* src = xsrc_row(p, from_inputs, rn / TB, rn % TB);
; #pragma unroll
;       for (int q = 0; q < 4; ++q) vn[q] = *(const f32x4*)(src + q * 256 + lane * 4);
;     }
;     const float* mod = p.MOD + (size_t)(l * 9 + (s < NCTX ? 8 : b)) * 6144 + (which ? 3 * 1024 : 0);
.LBB0_228:
	s_andn2_b64 vcc, exec, s[0:1]
	s_cbranch_vccnz .LBB0_249
	v_readlane_b32 s0, v252, 9
	s_nop 1
	v_add_u32_e32 v1, s0, v158
	v_readlane_b32 s0, v250, 4
	v_readlane_b32 s1, v250, 5
	s_and_b64 s[0:1], s[0:1], exec
	s_movk_i32 s0, 0x4800
	s_cselect_b32 s26, 0x4000, s0
	v_cmp_gt_i32_e32 vcc, s26, v1
	s_and_saveexec_b64 s[2:3], vcc
	s_cbranch_execz .LBB0_248
	v_readlane_b32 s0, v252, 9
	v_lshlrev_b32_e32 v244, 4, v115
	v_lshlrev_b32_e32 v245, 3, v115
	v_add_u32_e32 v1, s0, v158
	s_nop 1
	v_readfirstlane_b32 s20, v1
	v_readlane_b32 s4, v254, 42
	v_readlane_b32 s5, v254, 43
	v_readlane_b32 s12, v254, 28
	v_readlane_b32 s13, v254, 29
	v_readlane_b32 s14, v254, 32
	v_readlane_b32 s15, v254, 33
	v_readlane_b32 s16, v253, 40
	v_readlane_b32 s17, v253, 41
	v_readlane_b32 s18, v250, 4
	v_readlane_b32 s19, v250, 5
	s_nop 3
	s_lshl_b32 s0, s49, 12
	s_add_u32 s4, s4, s0
	s_addc_u32 s5, s5, 0
	global_load_dwordx4 v[2:5], v244, s[4:5]
	global_load_dwordx4 v[6:9], v244, s[4:5] offset:1024
	global_load_dwordx4 v[10:13], v244, s[4:5] offset:2048
	global_load_dwordx4 v[14:17], v244, s[4:5] offset:3072
	s_mov_b32 s12, s56
	s_mov_b32 s13, s57
	s_mov_b32 s14, s64
	s_mov_b32 s15, s65
	s_cmp_lg_u64 s[18:19], 0
	s_cbranch_scc1 .Lnorm2_last
	s_add_i32 s21, s20, 0
	s_mul_hi_u32 s7, s21, 0x38e38e39
	s_lshr_b32 s7, s7, 9
	s_mul_i32 s8, s7, 0x900
	s_sub_i32 s8, s21, s8
	s_lshl_b32 s9, s7, 11
	s_add_i32 s9, s9, s8
	s_add_i32 s9, s9, 0xffffff00
	s_lshl_b32 s10, s7, 8
	s_add_i32 s10, s10, s8
	s_cmpk_gt_i32 s8, 0xff
	s_cselect_b32 s9, s9, s10
	s_cselect_b32 s26, s12, s14
	s_cselect_b32 s27, s13, s15
	s_cselect_b32 s10, s7, 8
	s_lshl_b32 s9, s9, 12
	s_add_u32 s26, s26, s9
	s_addc_u32 s27, s27, 0
	s_add_i32 s10, s10, s82
	s_mul_i32 s10, s10, s24
	s_add_u32 s28, s58, s10
	s_addc_u32 s29, s59, 0
	s_add_u32 s28, s28, 0x3000
	s_addc_u32 s29, s29, 0
	s_add_u32 s0, s28, 0x1000
	s_addc_u32 s1, s29, 0
	global_load_dwordx4 v[18:21], v244, s[26:27]
	global_load_dwordx4 v[22:25], v244, s[26:27] offset:1024
	global_load_dwordx4 v[26:29], v244, s[26:27] offset:2048
	global_load_dwordx4 v[30:33], v244, s[26:27] offset:3072
	global_load_dwordx4 v[34:37], v244, s[28:29]
	global_load_dwordx4 v[38:41], v244, s[28:29] offset:1024
	global_load_dwordx4 v[42:45], v244, s[28:29] offset:2048
	global_load_dwordx4 v[46:49], v244, s[28:29] offset:3072
	global_load_dwordx4 v[50:53], v244, s[0:1]
	global_load_dwordx4 v[54:57], v244, s[0:1] offset:1024
	global_load_dwordx4 v[58:61], v244, s[0:1] offset:2048
	global_load_dwordx4 v[62:65], v244, s[0:1] offset:3072
	s_add_i32 s21, s20, 2048
	s_mul_hi_u32 s7, s21, 0x38e38e39
	s_lshr_b32 s7, s7, 9
	s_mul_i32 s8, s7, 0x900
	s_sub_i32 s8, s21, s8
	s_lshl_b32 s9, s7, 11
	s_add_i32 s9, s9, s8
	s_add_i32 s9, s9, 0xffffff00
	s_lshl_b32 s10, s7, 8
	s_add_i32 s10, s10, s8
	s_cmpk_gt_i32 s8, 0xff
	s_cselect_b32 s9, s9, s10
	s_cselect_b32 s26, s12, s14
	s_cselect_b32 s27, s13, s15
	s_cselect_b32 s10, s7, 8
	s_lshl_b32 s9, s9, 12
	s_add_u32 s26, s26, s9
	s_addc_u32 s27, s27, 0
	s_add_i32 s10, s10, s82
	s_mul_i32 s10, s10, s24
	s_add_u32 s28, s58, s10
	s_addc_u32 s29, s59, 0
	s_add_u32 s28, s28, 0x3000
	s_addc_u32 s29, s29, 0
	s_add_u32 s0, s28, 0x1000
	s_addc_u32 s1, s29, 0
	global_load_dwordx4 v[66:69], v244, s[26:27]
	global_load_dwordx4 v[70:73], v244, s[26:27] offset:1024
	global_load_dwordx4 v[74:77], v244, s[26:27] offset:2048
	global_load_dwordx4 v[78:81], v244, s[26:27] offset:3072
	global_load_dwordx4 v[82:85], v244, s[28:29]
	global_load_dwordx4 v[86:89], v244, s[28:29] offset:1024
	global_load_dwordx4 v[90:93], v244, s[28:29] offset:2048
	global_load_dwordx4 v[94:97], v244, s[28:29] offset:3072
	global_load_dwordx4 v[98:101], v244, s[0:1]
	global_load_dwordx4 v[102:105], v244, s[0:1] offset:1024
	global_load_dwordx4 v[106:109], v244, s[0:1] offset:2048
	global_load_dwordx4 v[118:121], v244, s[0:1] offset:3072
	s_add_i32 s21, s20, 4096
	s_mul_hi_u32 s7, s21, 0x38e38e39
	s_lshr_b32 s7, s7, 9
	s_mul_i32 s8, s7, 0x900
	s_sub_i32 s8, s21, s8
	s_lshl_b32 s9, s7, 11
	s_add_i32 s9, s9, s8
	s_add_i32 s9, s9, 0xffffff00
	s_lshl_b32 s10, s7, 8
	s_add_i32 s10, s10, s8
	s_cmpk_gt_i32 s8, 0xff
	s_cselect_b32 s9, s9, s10
	s_cselect_b32 s26, s12, s14
	s_cselect_b32 s27, s13, s15
	s_cselect_b32 s10, s7, 8
	s_lshl_b32 s9, s9, 12
	s_add_u32 s26, s26, s9
	s_addc_u32 s27, s27, 0
	s_add_i32 s10, s10, s82
	s_mul_i32 s10, s10, s24
	s_add_u32 s28, s58, s10
	s_addc_u32 s29, s59, 0
	s_add_u32 s28, s28, 0x3000
	s_addc_u32 s29, s29, 0
	s_add_u32 s0, s28, 0x1000
	s_addc_u32 s1, s29, 0
	global_load_dwordx4 v[122:125], v244, s[26:27]
	global_load_dwordx4 v[126:129], v244, s[26:27] offset:1024
	global_load_dwordx4 v[130:133], v244, s[26:27] offset:2048
	global_load_dwordx4 v[134:137], v244, s[26:27] offset:3072
	global_load_dwordx4 v[160:163], v244, s[28:29]
	global_load_dwordx4 v[164:167], v244, s[28:29] offset:1024
	global_load_dwordx4 v[168:171], v244, s[28:29] offset:2048
	global_load_dwordx4 v[172:175], v244, s[28:29] offset:3072
	global_load_dwordx4 v[176:179], v244, s[0:1]
	global_load_dwordx4 v[180:183], v244, s[0:1] offset:1024
	global_load_dwordx4 v[184:187], v244, s[0:1] offset:2048
	global_load_dwordx4 v[188:191], v244, s[0:1] offset:3072
	s_waitcnt vmcnt(24)
; DI unsigned pk_bf16(float lo, float hi) { f32x2 v = {lo, hi}; bf16v2 b = __builtin_convertvector(v, bf16v2); return __builtin_bit_cast(unsigned, b); }
; DI float red64(float x) { for (int o = 32; o > 0; o >>= 1) x += __shfl_xor(x, o); return x; }
; DI void modnorm_rows(const Params& p, int l, int which  , bool from_inputs, bool skip_ctx, int w0, int wstride, int lane) {
;     ...
;   for (; i < nrows; i += wstride) {
;     const int row = rowof(i); const int b = row / TB, s = row % TB;
;     f32x4 v[4];
; #pragma unroll
;     for (int q = 0; q < 4; ++q) v[q] = vn[q];
;     if (i + wstride < nrows) {
;       const int rn = rowof(i + wstride); const float* src = xsrc_row(p, from_inputs, rn / TB, rn % TB);
; #pragma unroll
;       for (int q = 0; q < 4; ++q) vn[q] = *(const f32x4*)(src + q * 256 + lane * 4);
;     }
;     const float* mod = p.MOD + (size_t)(l * 9 + (s < NCTX ? 8 : b)) * 6144 + (which ? 3 * 1024 : 0);
;     f32x4 sh[4], sc[4];
; #pragma unroll
;     for (int q = 0; q < 4; ++q) { sh[q] = *(const f32x4*)(mod + q * 256 + lane * 4); sc[q] = *(const f32x4*)(mod + 1024 + q * 256 + lane * 4); }
;     float ss = 0.f;
; #pragma unroll
;     for (int q = 0; q < 4; ++q) ss += v[q][0] * v[q][0] + v[q][1] * v[q][1] + v[q][2] * v[q][2] + v[q][3] * v[q][3];
;     ss = red64(ss);
;     const float rs = rsqrtf(ss * (1.f / 1024.f) + EPSF);
;     bf16_t* dst = p.HY + (size_t)row * DM;
; #pragma unroll
;     for (int q = 0; q < 4; ++q) {
;       float o[4];
; #pragma unroll
;       for (int j = 0; j < 4; ++j) o[j] = (v[q][j] * rs * gg[q][j]) * (1.f + sc[q][j]) + sh[q][j];
;       u32x2 w = {pk_bf16(o[0], o[1]), pk_bf16(o[2], o[3])};
;       *(u32x2*)(dst + q * 256 + lane * 4) = w;
;     }
	v_pk_mul_f32 v[246:247], v[18:19], v[18:19]
	v_pk_fma_f32 v[246:247], v[20:21], v[20:21], v[246:247]
	v_pk_fma_f32 v[246:247], v[22:23], v[22:23], v[246:247]
	v_pk_fma_f32 v[246:247], v[24:25], v[24:25], v[246:247]
	v_pk_fma_f32 v[246:247], v[26:27], v[26:27], v[246:247]
	v_pk_fma_f32 v[246:247], v[28:29], v[28:29], v[246:247]
	v_pk_fma_f32 v[246:247], v[30:31], v[30:31], v[246:247]
	v_pk_fma_f32 v[246:247], v[32:33], v[32:33], v[246:247]
	s_nop 0
	v_add_f32_e32 v246, v246, v247
	s_nop 1
	v_add_f32_dpp v246, v246, v246 quad_perm:[1,0,3,2] row_mask:0xf bank_mask:0xf
	s_nop 1
	v_add_f32_dpp v246, v246, v246 quad_perm:[2,3,0,1] row_mask:0xf bank_mask:0xf
	s_nop 1
	v_add_f32_dpp v246, v246, v246 row_half_mirror row_mask:0xf bank_mask:0xf
	s_nop 1
	v_add_f32_dpp v246, v246, v246 row_mirror row_mask:0xf bank_mask:0xf
	s_nop 1
	v_add_f32_dpp v246, v246, v246 row_bcast:15 row_mask:0xa bank_mask:0xf
	s_nop 1
	v_add_f32_dpp v246, v246, v246 row_bcast:31 row_mask:0xc bank_mask:0xf
	s_nop 1
	v_readlane_b32 s0, v246, 63
	s_add_i32 s21, s20, 0
	s_lshl_b32 s21, s21, 11
	s_add_u32 s10, s16, s21
	s_addc_u32 s11, s17, 0
	v_mov_b32_e32 v248, s0
	v_fmamk_f32 v248, v248, 0x3a800000, v143
	v_rsq_f32_e32 v248, v248
	s_nop 0
	v_pk_mul_f32 v[18:19], v[18:19], v[248:249] op_sel_hi:[1,0]
	v_pk_add_f32 v[50:51], v[50:51], 1.0 op_sel_hi:[1,0]
	v_pk_mul_f32 v[18:19], v[2:3], v[18:19]
	v_pk_fma_f32 v[18:19], v[50:51], v[18:19], v[34:35]
	v_pk_mul_f32 v[20:21], v[20:21], v[248:249] op_sel_hi:[1,0]
	v_pk_add_f32 v[52:53], v[52:53], 1.0 op_sel_hi:[1,0]
	v_pk_mul_f32 v[20:21], v[4:5], v[20:21]
	v_pk_fma_f32 v[20:21], v[52:53], v[20:21], v[36:37]
	v_cvt_pk_bf16_f32 v34, v18, v19
	v_cvt_pk_bf16_f32 v35, v20, v21
	global_store_dwordx2 v245, v[34:35], s[10:11]
	v_pk_mul_f32 v[22:23], v[22:23], v[248:249] op_sel_hi:[1,0]
	v_pk_add_f32 v[54:55], v[54:55], 1.0 op_sel_hi:[1,0]
	v_pk_mul_f32 v[22:23], v[6:7], v[22:23]
	v_pk_fma_f32 v[22:23], v[54:55], v[22:23], v[38:39]
	v_pk_mul_f32 v[24:25], v[24:25], v[248:249] op_sel_hi:[1,0]
	v_pk_add_f32 v[56:57], v[56:57], 1.0 op_sel_hi:[1,0]
	v_pk_mul_f32 v[24:25], v[8:9], v[24:25]
	v_pk_fma_f32 v[24:25], v[56:57], v[24:25], v[40:41]
	v_cvt_pk_bf16_f32 v38, v22, v23
	v_cvt_pk_bf16_f32 v39, v24, v25
	global_store_dwordx2 v245, v[38:39], s[10:11] offset:512
	v_pk_mul_f32 v[26:27], v[26:27], v[248:249] op_sel_hi:[1,0]
	v_pk_add_f32 v[58:59], v[58:59], 1.0 op_sel_hi:[1,0]
	v_pk_mul_f32 v[26:27], v[10:11], v[26:27]
	v_pk_fma_f32 v[26:27], v[58:59], v[26:27], v[42:43]
	v_pk_mul_f32 v[28:29], v[28:29], v[248:249] op_sel_hi:[1,0]
	v_pk_add_f32 v[60:61], v[60:61], 1.0 op_sel_hi:[1,0]
	v_pk_mul_f32 v[28:29], v[12:13], v[28:29]
	v_pk_fma_f32 v[28:29], v[60:61], v[28:29], v[44:45]
	v_cvt_pk_bf16_f32 v42, v26, v27
	v_cvt_pk_bf16_f32 v43, v28, v29
	global_store_dwordx2 v245, v[42:43], s[10:11] offset:1024
	v_pk_mul_f32 v[30:31], v[30:31], v[248:249] op_sel_hi:[1,0]
	v_pk_add_f32 v[62:63], v[62:63], 1.0 op_sel_hi:[1,0]
	v_pk_mul_f32 v[30:31], v[14:15], v[30:31]
	v_pk_fma_f32 v[30:31], v[62:63], v[30:31], v[46:47]
	v_pk_mul_f32 v[32:33], v[32:33], v[248:249] op_sel_hi:[1,0]
	v_pk_add_f32 v[64:65], v[64:65], 1.0 op_sel_hi:[1,0]
	v_pk_mul_f32 v[32:33], v[16:17], v[32:33]
	v_pk_fma_f32 v[32:33], v[64:65], v[32:33], v[48:49]
	v_cvt_pk_bf16_f32 v46, v30, v31
	v_cvt_pk_bf16_f32 v47, v32, v33
	global_store_dwordx2 v245, v[46:47], s[10:11] offset:1536
	s_add_i32 s21, s20, 6144
	s_mul_hi_u32 s7, s21, 0x38e38e39
	s_lshr_b32 s7, s7, 9
	s_mul_i32 s8, s7, 0x900
	s_sub_i32 s8, s21, s8
	s_lshl_b32 s9, s7, 11
	s_add_i32 s9, s9, s8
	s_add_i32 s9, s9, 0xffffff00
	s_lshl_b32 s10, s7, 8
	s_add_i32 s10, s10, s8
	s_cmpk_gt_i32 s8, 0xff
	s_cselect_b32 s9, s9, s10
	s_cselect_b32 s26, s12, s14
	s_cselect_b32 s27, s13, s15
	s_cselect_b32 s10, s7, 8
	s_lshl_b32 s9, s9, 12
	s_add_u32 s26, s26, s9
	s_addc_u32 s27, s27, 0
	s_add_i32 s10, s10, s82
	s_mul_i32 s10, s10, s24
	s_add_u32 s28, s58, s10
	s_addc_u32 s29, s59, 0
	s_add_u32 s28, s28, 0x3000
	s_addc_u32 s29, s29, 0
	s_add_u32 s0, s28, 0x1000
	s_addc_u32 s1, s29, 0
	global_load_dwordx4 v[18:21], v244, s[26:27]
	global_load_dwordx4 v[22:25], v244, s[26:27] offset:1024
	global_load_dwordx4 v[26:29], v244, s[26:27] offset:2048
	global_load_dwordx4 v[30:33], v244, s[26:27] offset:3072
	global_load_dwordx4 v[34:37], v244, s[28:29]
	global_load_dwordx4 v[38:41], v244, s[28:29] offset:1024
	global_load_dwordx4 v[42:45], v244, s[28:29] offset:2048
	global_load_dwordx4 v[46:49], v244, s[28:29] offset:3072
	global_load_dwordx4 v[50:53], v244, s[0:1]
	global_load_dwordx4 v[54:57], v244, s[0:1] offset:1024
	global_load_dwordx4 v[58:61], v244, s[0:1] offset:2048
	global_load_dwordx4 v[62:65], v244, s[0:1] offset:3072
	s_waitcnt vmcnt(28)
; DI unsigned pk_bf16(float lo, float hi) { f32x2 v = {lo, hi}; bf16v2 b = __builtin_convertvector(v, bf16v2); return __builtin_bit_cast(unsigned, b); }
; DI float red64(float x) { for (int o = 32; o > 0; o >>= 1) x += __shfl_xor(x, o); return x; }
; DI void modnorm_rows(const Params& p, int l, int which  , bool from_inputs, bool skip_ctx, int w0, int wstride, int lane) {
;     ...
;   for (; i < nrows; i += wstride) {
;     const int row = rowof(i); const int b = row / TB, s = row % TB;
;     f32x4 v[4];
; #pragma unroll
;     for (int q = 0; q < 4; ++q) v[q] = vn[q];
;     if (i + wstride < nrows) {
;       const int rn = rowof(i + wstride); const float* src = xsrc_row(p, from_inputs, rn / TB, rn % TB);
; #pragma unroll
;       for (int q = 0; q < 4; ++q) vn[q] = *(const f32x4*)(src + q * 256 + lane * 4);
;     }
;     const float* mod = p.MOD + (size_t)(l * 9 + (s < NCTX ? 8 : b)) * 6144 + (which ? 3 * 1024 : 0);
;     f32x4 sh[4], sc[4];
; #pragma unroll
;     for (int q = 0; q < 4; ++q) { sh[q] = *(const f32x4*)(mod + q * 256 + lane * 4); sc[q] = *(const f32x4*)(mod + 1024 + q * 256 + lane * 4); }
;     float ss = 0.f;
; #pragma unroll
;     for (int q = 0; q < 4; ++q) ss += v[q][0] * v[q][0] + v[q][1] * v[q][1] + v[q][2] * v[q][2] + v[q][3] * v[q][3];
;     ss = red64(ss);
;     const float rs = rsqrtf(ss * (1.f / 1024.f) + EPSF);
;     bf16_t* dst = p.HY + (size_t)row * DM;
; #pragma unroll
;     for (int q = 0; q < 4; ++q) {
;       float o[4];
; #pragma unroll
;       for (int j = 0; j < 4; ++j) o[j] = (v[q][j] * rs * gg[q][j]) * (1.f + sc[q][j]) + sh[q][j];
;       u32x2 w = {pk_bf16(o[0], o[1]), pk_bf16(o[2], o[3])};
;       *(u32x2*)(dst + q * 256 + lane * 4) = w;
;     }
	v_pk_mul_f32 v[246:247], v[66:67], v[66:67]
	v_pk_fma_f32 v[246:247], v[68:69], v[68:69], v[246:247]
	v_pk_fma_f32 v[246:247], v[70:71], v[70:71], v[246:247]
	v_pk_fma_f32 v[246:247], v[72:73], v[72:73], v[246:247]
	v_pk_fma_f32 v[246:247], v[74:75], v[74:75], v[246:247]
	v_pk_fma_f32 v[246:247], v[76:77], v[76:77], v[246:247]
	v_pk_fma_f32 v[246:247], v[78:79], v[78:79], v[246:247]
	v_pk_fma_f32 v[246:247], v[80:81], v[80:81], v[246:247]
	s_nop 0
	v_add_f32_e32 v246, v246, v247
	s_nop 1
	v_add_f32_dpp v246, v246, v246 quad_perm:[1,0,3,2] row_mask:0xf bank_mask:0xf
	s_nop 1
	v_add_f32_dpp v246, v246, v246 quad_perm:[2,3,0,1] row_mask:0xf bank_mask:0xf
	s_nop 1
	v_add_f32_dpp v246, v246, v246 row_half_mirror row_mask:0xf bank_mask:0xf
	s_nop 1
	v_add_f32_dpp v246, v246, v246 row_mirror row_mask:0xf bank_mask:0xf
	s_nop 1
	v_add_f32_dpp v246, v246, v246 row_bcast:15 row_mask:0xa bank_mask:0xf
	s_nop 1
	v_add_f32_dpp v246, v246, v246 row_bcast:31 row_mask:0xc bank_mask:0xf
	s_nop 1
	v_readlane_b32 s0, v246, 63
	s_add_i32 s21, s20, 2048
	s_lshl_b32 s21, s21, 11
	s_add_u32 s10, s16, s21
	s_addc_u32 s11, s17, 0
	v_mov_b32_e32 v248, s0
	v_fmamk_f32 v248, v248, 0x3a800000, v143
	v_rsq_f32_e32 v248, v248
	s_nop 0
	v_pk_mul_f32 v[66:67], v[66:67], v[248:249] op_sel_hi:[1,0]
	v_pk_add_f32 v[98:99], v[98:99], 1.0 op_sel_hi:[1,0]
	v_pk_mul_f32 v[66:67], v[2:3], v[66:67]
	v_pk_fma_f32 v[66:67], v[98:99], v[66:67], v[82:83]
	v_pk_mul_f32 v[68:69], v[68:69], v[248:249] op_sel_hi:[1,0]
	v_pk_add_f32 v[100:101], v[100:101], 1.0 op_sel_hi:[1,0]
	v_pk_mul_f32 v[68:69], v[4:5], v[68:69]
	v_pk_fma_f32 v[68:69], v[100:101], v[68:69], v[84:85]
	v_cvt_pk_bf16_f32 v82, v66, v67
	v_cvt_pk_bf16_f32 v83, v68, v69
	global_store_dwordx2 v245, v[82:83], s[10:11]
	v_pk_mul_f32 v[70:71], v[70:71], v[248:249] op_sel_hi:[1,0]
	v_pk_add_f32 v[102:103], v[102:103], 1.0 op_sel_hi:[1,0]
	v_pk_mul_f32 v[70:71], v[6:7], v[70:71]
	v_pk_fma_f32 v[70:71], v[102:103], v[70:71], v[86:87]
	v_pk_mul_f32 v[72:73], v[72:73], v[248:249] op_sel_hi:[1,0]
	v_pk_add_f32 v[104:105], v[104:105], 1.0 op_sel_hi:[1,0]
	v_pk_mul_f32 v[72:73], v[8:9], v[72:73]
	v_pk_fma_f32 v[72:73], v[104:105], v[72:73], v[88:89]
	v_cvt_pk_bf16_f32 v86, v70, v71
	v_cvt_pk_bf16_f32 v87, v72, v73
	global_store_dwordx2 v245, v[86:87], s[10:11] offset:512
	v_pk_mul_f32 v[74:75], v[74:75], v[248:249] op_sel_hi:[1,0]
	v_pk_add_f32 v[106:107], v[106:107], 1.0 op_sel_hi:[1,0]
	v_pk_mul_f32 v[74:75], v[10:11], v[74:75]
	v_pk_fma_f32 v[74:75], v[106:107], v[74:75], v[90:91]
	v_pk_mul_f32 v[76:77], v[76:77], v[248:249] op_sel_hi:[1,0]
	v_pk_add_f32 v[108:109], v[108:109], 1.0 op_sel_hi:[1,0]
	v_pk_mul_f32 v[76:77], v[12:13], v[76:77]
	v_pk_fma_f32 v[76:77], v[108:109], v[76:77], v[92:93]
	v_cvt_pk_bf16_f32 v90, v74, v75
	v_cvt_pk_bf16_f32 v91, v76, v77
	global_store_dwordx2 v245, v[90:91], s[10:11] offset:1024
	v_pk_mul_f32 v[78:79], v[78:79], v[248:249] op_sel_hi:[1,0]
	v_pk_add_f32 v[118:119], v[118:119], 1.0 op_sel_hi:[1,0]
	v_pk_mul_f32 v[78:79], v[14:15], v[78:79]
	v_pk_fma_f32 v[78:79], v[118:119], v[78:79], v[94:95]
	v_pk_mul_f32 v[80:81], v[80:81], v[248:249] op_sel_hi:[1,0]
	v_pk_add_f32 v[120:121], v[120:121], 1.0 op_sel_hi:[1,0]
	v_pk_mul_f32 v[80:81], v[16:17], v[80:81]
	v_pk_fma_f32 v[80:81], v[120:121], v[80:81], v[96:97]
	v_cvt_pk_bf16_f32 v94, v78, v79
	v_cvt_pk_bf16_f32 v95, v80, v81
	global_store_dwordx2 v245, v[94:95], s[10:11] offset:1536
	s_add_i32 s21, s20, 8192
	s_mul_hi_u32 s7, s21, 0x38e38e39
	s_lshr_b32 s7, s7, 9
	s_mul_i32 s8, s7, 0x900
	s_sub_i32 s8, s21, s8
	s_lshl_b32 s9, s7, 11
	s_add_i32 s9, s9, s8
	s_add_i32 s9, s9, 0xffffff00
	s_lshl_b32 s10, s7, 8
	s_add_i32 s10, s10, s8
	s_cmpk_gt_i32 s8, 0xff
	s_cselect_b32 s9, s9, s10
	s_cselect_b32 s26, s12, s14
	s_cselect_b32 s27, s13, s15
	s_cselect_b32 s10, s7, 8
	s_lshl_b32 s9, s9, 12
	s_add_u32 s26, s26, s9
	s_addc_u32 s27, s27, 0
	s_add_i32 s10, s10, s82
	s_mul_i32 s10, s10, s24
	s_add_u32 s28, s58, s10
	s_addc_u32 s29, s59, 0
	s_add_u32 s28, s28, 0x3000
	s_addc_u32 s29, s29, 0
	s_add_u32 s0, s28, 0x1000
	s_addc_u32 s1, s29, 0
	global_load_dwordx4 v[66:69], v244, s[26:27]
	global_load_dwordx4 v[70:73], v244, s[26:27] offset:1024
	global_load_dwordx4 v[74:77], v244, s[26:27] offset:2048
	global_load_dwordx4 v[78:81], v244, s[26:27] offset:3072
	global_load_dwordx4 v[82:85], v244, s[28:29]
	global_load_dwordx4 v[86:89], v244, s[28:29] offset:1024
	global_load_dwordx4 v[90:93], v244, s[28:29] offset:2048
	global_load_dwordx4 v[94:97], v244, s[28:29] offset:3072
	global_load_dwordx4 v[98:101], v244, s[0:1]
	global_load_dwordx4 v[102:105], v244, s[0:1] offset:1024
	global_load_dwordx4 v[106:109], v244, s[0:1] offset:2048
	global_load_dwordx4 v[118:121], v244, s[0:1] offset:3072
	s_waitcnt vmcnt(32)
; DI unsigned pk_bf16(float lo, float hi) { f32x2 v = {lo, hi}; bf16v2 b = __builtin_convertvector(v, bf16v2); return __builtin_bit_cast(unsigned, b); }
; DI float red64(float x) { for (int o = 32; o > 0; o >>= 1) x += __shfl_xor(x, o); return x; }
; DI void modnorm_rows(const Params& p, int l, int which  , bool from_inputs, bool skip_ctx, int w0, int wstride, int lane) {
;     ...
;   for (; i < nrows; i += wstride) {
;     const int row = rowof(i); const int b = row / TB, s = row % TB;
;     f32x4 v[4];
; #pragma unroll
;     for (int q = 0; q < 4; ++q) v[q] = vn[q];
;     if (i + wstride < nrows) {
;       const int rn = rowof(i + wstride); const float* src = xsrc_row(p, from_inputs, rn / TB, rn % TB);
; #pragma unroll
;       for (int q = 0; q < 4; ++q) vn[q] = *(const f32x4*)(src + q * 256 + lane * 4);
;     }
;     const float* mod = p.MOD + (size_t)(l * 9 + (s < NCTX ? 8 : b)) * 6144 + (which ? 3 * 1024 : 0);
;     f32x4 sh[4], sc[4];
; #pragma unroll
;     for (int q = 0; q < 4; ++q) { sh[q] = *(const f32x4*)(mod + q * 256 + lane * 4); sc[q] = *(const f32x4*)(mod + 1024 + q * 256 + lane * 4); }
;     float ss = 0.f;
; #pragma unroll
;     for (int q = 0; q < 4; ++q) ss += v[q][0] * v[q][0] + v[q][1] * v[q][1] + v[q][2] * v[q][2] + v[q][3] * v[q][3];
;     ss = red64(ss);
;     const float rs = rsqrtf(ss * (1.f / 1024.f) + EPSF);
;     bf16_t* dst = p.HY + (size_t)row * DM;
; #pragma unroll
;     for (int q = 0; q < 4; ++q) {
;       float o[4];
; #pragma unroll
;       for (int j = 0; j < 4; ++j) o[j] = (v[q][j] * rs * gg[q][j]) * (1.f + sc[q][j]) + sh[q][j];
;       u32x2 w = {pk_bf16(o[0], o[1]), pk_bf16(o[2], o[3])};
;       *(u32x2*)(dst + q * 256 + lane * 4) = w;
;     }
	v_pk_mul_f32 v[246:247], v[122:123], v[122:123]
	v_pk_fma_f32 v[246:247], v[124:125], v[124:125], v[246:247]
	v_pk_fma_f32 v[246:247], v[126:127], v[126:127], v[246:247]
	v_pk_fma_f32 v[246:247], v[128:129], v[128:129], v[246:247]
	v_pk_fma_f32 v[246:247], v[130:131], v[130:131], v[246:247]
	v_pk_fma_f32 v[246:247], v[132:133], v[132:133], v[246:247]
	v_pk_fma_f32 v[246:247], v[134:135], v[134:135], v[246:247]
	v_pk_fma_f32 v[246:247], v[136:137], v[136:137], v[246:247]
	s_nop 0
	v_add_f32_e32 v246, v246, v247
	s_nop 1
	v_add_f32_dpp v246, v246, v246 quad_perm:[1,0,3,2] row_mask:0xf bank_mask:0xf
	s_nop 1
	v_add_f32_dpp v246, v246, v246 quad_perm:[2,3,0,1] row_mask:0xf bank_mask:0xf
	s_nop 1
	v_add_f32_dpp v246, v246, v246 row_half_mirror row_mask:0xf bank_mask:0xf
	s_nop 1
	v_add_f32_dpp v246, v246, v246 row_mirror row_mask:0xf bank_mask:0xf
	s_nop 1
	v_add_f32_dpp v246, v246, v246 row_bcast:15 row_mask:0xa bank_mask:0xf
	s_nop 1
	v_add_f32_dpp v246, v246, v246 row_bcast:31 row_mask:0xc bank_mask:0xf
	s_nop 1
	v_readlane_b32 s0, v246, 63
	s_add_i32 s21, s20, 4096
	s_lshl_b32 s21, s21, 11
	s_add_u32 s10, s16, s21
	s_addc_u32 s11, s17, 0
	v_mov_b32_e32 v248, s0
	v_fmamk_f32 v248, v248, 0x3a800000, v143
	v_rsq_f32_e32 v248, v248
	s_nop 0
	v_pk_mul_f32 v[122:123], v[122:123], v[248:249] op_sel_hi:[1,0]
	v_pk_add_f32 v[176:177], v[176:177], 1.0 op_sel_hi:[1,0]
	v_pk_mul_f32 v[122:123], v[2:3], v[122:123]
	v_pk_fma_f32 v[122:123], v[176:177], v[122:123], v[160:161]
	v_pk_mul_f32 v[124:125], v[124:125], v[248:249] op_sel_hi:[1,0]
	v_pk_add_f32 v[178:179], v[178:179], 1.0 op_sel_hi:[1,0]
	v_pk_mul_f32 v[124:125], v[4:5], v[124:125]
	v_pk_fma_f32 v[124:125], v[178:179], v[124:125], v[162:163]
	v_cvt_pk_bf16_f32 v160, v122, v123
	v_cvt_pk_bf16_f32 v161, v124, v125
	global_store_dwordx2 v245, v[160:161], s[10:11]
	v_pk_mul_f32 v[126:127], v[126:127], v[248:249] op_sel_hi:[1,0]
	v_pk_add_f32 v[180:181], v[180:181], 1.0 op_sel_hi:[1,0]
	v_pk_mul_f32 v[126:127], v[6:7], v[126:127]
	v_pk_fma_f32 v[126:127], v[180:181], v[126:127], v[164:165]
	v_pk_mul_f32 v[128:129], v[128:129], v[248:249] op_sel_hi:[1,0]
	v_pk_add_f32 v[182:183], v[182:183], 1.0 op_sel_hi:[1,0]
	v_pk_mul_f32 v[128:129], v[8:9], v[128:129]
	v_pk_fma_f32 v[128:129], v[182:183], v[128:129], v[166:167]
	v_cvt_pk_bf16_f32 v164, v126, v127
	v_cvt_pk_bf16_f32 v165, v128, v129
	global_store_dwordx2 v245, v[164:165], s[10:11] offset:512
	v_pk_mul_f32 v[130:131], v[130:131], v[248:249] op_sel_hi:[1,0]
	v_pk_add_f32 v[184:185], v[184:185], 1.0 op_sel_hi:[1,0]
	v_pk_mul_f32 v[130:131], v[10:11], v[130:131]
	v_pk_fma_f32 v[130:131], v[184:185], v[130:131], v[168:169]
	v_pk_mul_f32 v[132:133], v[132:133], v[248:249] op_sel_hi:[1,0]
	v_pk_add_f32 v[186:187], v[186:187], 1.0 op_sel_hi:[1,0]
	v_pk_mul_f32 v[132:133], v[12:13], v[132:133]
	v_pk_fma_f32 v[132:133], v[186:187], v[132:133], v[170:171]
	v_cvt_pk_bf16_f32 v168, v130, v131
	v_cvt_pk_bf16_f32 v169, v132, v133
	global_store_dwordx2 v245, v[168:169], s[10:11] offset:1024
	v_pk_mul_f32 v[134:135], v[134:135], v[248:249] op_sel_hi:[1,0]
	v_pk_add_f32 v[188:189], v[188:189], 1.0 op_sel_hi:[1,0]
	v_pk_mul_f32 v[134:135], v[14:15], v[134:135]
	v_pk_fma_f32 v[134:135], v[188:189], v[134:135], v[172:173]
	v_pk_mul_f32 v[136:137], v[136:137], v[248:249] op_sel_hi:[1,0]
	v_pk_add_f32 v[190:191], v[190:191], 1.0 op_sel_hi:[1,0]
	v_pk_mul_f32 v[136:137], v[16:17], v[136:137]
	v_pk_fma_f32 v[136:137], v[190:191], v[136:137], v[174:175]
	v_cvt_pk_bf16_f32 v172, v134, v135
	v_cvt_pk_bf16_f32 v173, v136, v137
	global_store_dwordx2 v245, v[172:173], s[10:11] offset:1536
	s_add_i32 s21, s20, 10240
	s_mul_hi_u32 s7, s21, 0x38e38e39
	s_lshr_b32 s7, s7, 9
	s_mul_i32 s8, s7, 0x900
	s_sub_i32 s8, s21, s8
	s_lshl_b32 s9, s7, 11
	s_add_i32 s9, s9, s8
	s_add_i32 s9, s9, 0xffffff00
	s_lshl_b32 s10, s7, 8
	s_add_i32 s10, s10, s8
	s_cmpk_gt_i32 s8, 0xff
	s_cselect_b32 s9, s9, s10
	s_cselect_b32 s26, s12, s14
	s_cselect_b32 s27, s13, s15
	s_cselect_b32 s10, s7, 8
	s_lshl_b32 s9, s9, 12
	s_add_u32 s26, s26, s9
	s_addc_u32 s27, s27, 0
	s_add_i32 s10, s10, s82
	s_mul_i32 s10, s10, s24
	s_add_u32 s28, s58, s10
	s_addc_u32 s29, s59, 0
	s_add_u32 s28, s28, 0x3000
	s_addc_u32 s29, s29, 0
	s_add_u32 s0, s28, 0x1000
	s_addc_u32 s1, s29, 0
	global_load_dwordx4 v[122:125], v244, s[26:27]
	global_load_dwordx4 v[126:129], v244, s[26:27] offset:1024
	global_load_dwordx4 v[130:133], v244, s[26:27] offset:2048
	global_load_dwordx4 v[134:137], v244, s[26:27] offset:3072
	global_load_dwordx4 v[160:163], v244, s[28:29]
	global_load_dwordx4 v[164:167], v244, s[28:29] offset:1024
	global_load_dwordx4 v[168:171], v244, s[28:29] offset:2048
	global_load_dwordx4 v[172:175], v244, s[28:29] offset:3072
	global_load_dwordx4 v[176:179], v244, s[0:1]
	global_load_dwordx4 v[180:183], v244, s[0:1] offset:1024
	global_load_dwordx4 v[184:187], v244, s[0:1] offset:2048
	global_load_dwordx4 v[188:191], v244, s[0:1] offset:3072
	s_waitcnt vmcnt(32)
; DI unsigned pk_bf16(float lo, float hi) { f32x2 v = {lo, hi}; bf16v2 b = __builtin_convertvector(v, bf16v2); return __builtin_bit_cast(unsigned, b); }
; DI float red64(float x) { for (int o = 32; o > 0; o >>= 1) x += __shfl_xor(x, o); return x; }
; DI void modnorm_rows(const Params& p, int l, int which  , bool from_inputs, bool skip_ctx, int w0, int wstride, int lane) {
;     ...
;   for (; i < nrows; i += wstride) {
;     const int row = rowof(i); const int b = row / TB, s = row % TB;
;     f32x4 v[4];
; #pragma unroll
;     for (int q = 0; q < 4; ++q) v[q] = vn[q];
;     if (i + wstride < nrows) {
;       const int rn = rowof(i + wstride); const float* src = xsrc_row(p, from_inputs, rn / TB, rn % TB);
; #pragma unroll
;       for (int q = 0; q < 4; ++q) vn[q] = *(const f32x4*)(src + q * 256 + lane * 4);
;     }
;     const float* mod = p.MOD + (size_t)(l * 9 + (s < NCTX ? 8 : b)) * 6144 + (which ? 3 * 1024 : 0);
;     f32x4 sh[4], sc[4];
; #pragma unroll
;     for (int q = 0; q < 4; ++q) { sh[q] = *(const f32x4*)(mod + q * 256 + lane * 4); sc[q] = *(const f32x4*)(mod + 1024 + q * 256 + lane * 4); }
;     float ss = 0.f;
; #pragma unroll
;     for (int q = 0; q < 4; ++q) ss += v[q][0] * v[q][0] + v[q][1] * v[q][1] + v[q][2] * v[q][2] + v[q][3] * v[q][3];
;     ss = red64(ss);
;     const float rs = rsqrtf(ss * (1.f / 1024.f) + EPSF);
;     bf16_t* dst = p.HY + (size_t)row * DM;
; #pragma unroll
;     for (int q = 0; q < 4; ++q) {
;       float o[4];
; #pragma unroll
;       for (int j = 0; j < 4; ++j) o[j] = (v[q][j] * rs * gg[q][j]) * (1.f + sc[q][j]) + sh[q][j];
;       u32x2 w = {pk_bf16(o[0], o[1]), pk_bf16(o[2], o[3])};
;       *(u32x2*)(dst + q * 256 + lane * 4) = w;
;     }
	v_pk_mul_f32 v[246:247], v[18:19], v[18:19]
	v_pk_fma_f32 v[246:247], v[20:21], v[20:21], v[246:247]
	v_pk_fma_f32 v[246:247], v[22:23], v[22:23], v[246:247]
	v_pk_fma_f32 v[246:247], v[24:25], v[24:25], v[246:247]
	v_pk_fma_f32 v[246:247], v[26:27], v[26:27], v[246:247]
	v_pk_fma_f32 v[246:247], v[28:29], v[28:29], v[246:247]
	v_pk_fma_f32 v[246:247], v[30:31], v[30:31], v[246:247]
	v_pk_fma_f32 v[246:247], v[32:33], v[32:33], v[246:247]
	s_nop 0
	v_add_f32_e32 v246, v246, v247
	s_nop 1
	v_add_f32_dpp v246, v246, v246 quad_perm:[1,0,3,2] row_mask:0xf bank_mask:0xf
	s_nop 1
	v_add_f32_dpp v246, v246, v246 quad_perm:[2,3,0,1] row_mask:0xf bank_mask:0xf
	s_nop 1
	v_add_f32_dpp v246, v246, v246 row_half_mirror row_mask:0xf bank_mask:0xf
	s_nop 1
	v_add_f32_dpp v246, v246, v246 row_mirror row_mask:0xf bank_mask:0xf
	s_nop 1
	v_add_f32_dpp v246, v246, v246 row_bcast:15 row_mask:0xa bank_mask:0xf
	s_nop 1
	v_add_f32_dpp v246, v246, v246 row_bcast:31 row_mask:0xc bank_mask:0xf
	s_nop 1
	v_readlane_b32 s0, v246, 63
	s_add_i32 s21, s20, 6144
	s_lshl_b32 s21, s21, 11
	s_add_u32 s10, s16, s21
	s_addc_u32 s11, s17, 0
	v_mov_b32_e32 v248, s0
	v_fmamk_f32 v248, v248, 0x3a800000, v143
	v_rsq_f32_e32 v248, v248
	s_nop 0
	v_pk_mul_f32 v[18:19], v[18:19], v[248:249] op_sel_hi:[1,0]
	v_pk_add_f32 v[50:51], v[50:51], 1.0 op_sel_hi:[1,0]
	v_pk_mul_f32 v[18:19], v[2:3], v[18:19]
	v_pk_fma_f32 v[18:19], v[50:51], v[18:19], v[34:35]
	v_pk_mul_f32 v[20:21], v[20:21], v[248:249] op_sel_hi:[1,0]
	v_pk_add_f32 v[52:53], v[52:53], 1.0 op_sel_hi:[1,0]
	v_pk_mul_f32 v[20:21], v[4:5], v[20:21]
	v_pk_fma_f32 v[20:21], v[52:53], v[20:21], v[36:37]
	v_cvt_pk_bf16_f32 v34, v18, v19
	v_cvt_pk_bf16_f32 v35, v20, v21
	global_store_dwordx2 v245, v[34:35], s[10:11]
	v_pk_mul_f32 v[22:23], v[22:23], v[248:249] op_sel_hi:[1,0]
	v_pk_add_f32 v[54:55], v[54:55], 1.0 op_sel_hi:[1,0]
	v_pk_mul_f32 v[22:23], v[6:7], v[22:23]
	v_pk_fma_f32 v[22:23], v[54:55], v[22:23], v[38:39]
	v_pk_mul_f32 v[24:25], v[24:25], v[248:249] op_sel_hi:[1,0]
	v_pk_add_f32 v[56:57], v[56:57], 1.0 op_sel_hi:[1,0]
	v_pk_mul_f32 v[24:25], v[8:9], v[24:25]
	v_pk_fma_f32 v[24:25], v[56:57], v[24:25], v[40:41]
	v_cvt_pk_bf16_f32 v38, v22, v23
	v_cvt_pk_bf16_f32 v39, v24, v25
	global_store_dwordx2 v245, v[38:39], s[10:11] offset:512
	v_pk_mul_f32 v[26:27], v[26:27], v[248:249] op_sel_hi:[1,0]
	v_pk_add_f32 v[58:59], v[58:59], 1.0 op_sel_hi:[1,0]
	v_pk_mul_f32 v[26:27], v[10:11], v[26:27]
	v_pk_fma_f32 v[26:27], v[58:59], v[26:27], v[42:43]
	v_pk_mul_f32 v[28:29], v[28:29], v[248:249] op_sel_hi:[1,0]
	v_pk_add_f32 v[60:61], v[60:61], 1.0 op_sel_hi:[1,0]
	v_pk_mul_f32 v[28:29], v[12:13], v[28:29]
	v_pk_fma_f32 v[28:29], v[60:61], v[28:29], v[44:45]
	v_cvt_pk_bf16_f32 v42, v26, v27
	v_cvt_pk_bf16_f32 v43, v28, v29
	global_store_dwordx2 v245, v[42:43], s[10:11] offset:1024
	v_pk_mul_f32 v[30:31], v[30:31], v[248:249] op_sel_hi:[1,0]
	v_pk_add_f32 v[62:63], v[62:63], 1.0 op_sel_hi:[1,0]
	v_pk_mul_f32 v[30:31], v[14:15], v[30:31]
	v_pk_fma_f32 v[30:31], v[62:63], v[30:31], v[46:47]
	v_pk_mul_f32 v[32:33], v[32:33], v[248:249] op_sel_hi:[1,0]
	v_pk_add_f32 v[64:65], v[64:65], 1.0 op_sel_hi:[1,0]
	v_pk_mul_f32 v[32:33], v[16:17], v[32:33]
	v_pk_fma_f32 v[32:33], v[64:65], v[32:33], v[48:49]
	v_cvt_pk_bf16_f32 v46, v30, v31
	v_cvt_pk_bf16_f32 v47, v32, v33
	global_store_dwordx2 v245, v[46:47], s[10:11] offset:1536
	s_add_i32 s21, s20, 12288
	s_mul_hi_u32 s7, s21, 0x38e38e39
	s_lshr_b32 s7, s7, 9
	s_mul_i32 s8, s7, 0x900
	s_sub_i32 s8, s21, s8
	s_lshl_b32 s9, s7, 11
	s_add_i32 s9, s9, s8
	s_add_i32 s9, s9, 0xffffff00
	s_lshl_b32 s10, s7, 8
	s_add_i32 s10, s10, s8
	s_cmpk_gt_i32 s8, 0xff
	s_cselect_b32 s9, s9, s10
	s_cselect_b32 s26, s12, s14
	s_cselect_b32 s27, s13, s15
	s_cselect_b32 s10, s7, 8
	s_lshl_b32 s9, s9, 12
	s_add_u32 s26, s26, s9
	s_addc_u32 s27, s27, 0
	s_add_i32 s10, s10, s82
	s_mul_i32 s10, s10, s24
	s_add_u32 s28, s58, s10
	s_addc_u32 s29, s59, 0
	s_add_u32 s28, s28, 0x3000
	s_addc_u32 s29, s29, 0
	s_add_u32 s0, s28, 0x1000
	s_addc_u32 s1, s29, 0
	global_load_dwordx4 v[18:21], v244, s[26:27]
	global_load_dwordx4 v[22:25], v244, s[26:27] offset:1024
	global_load_dwordx4 v[26:29], v244, s[26:27] offset:2048
	global_load_dwordx4 v[30:33], v244, s[26:27] offset:3072
	global_load_dwordx4 v[34:37], v244, s[28:29]
	global_load_dwordx4 v[38:41], v244, s[28:29] offset:1024
	global_load_dwordx4 v[42:45], v244, s[28:29] offset:2048
	global_load_dwordx4 v[46:49], v244, s[28:29] offset:3072
	global_load_dwordx4 v[50:53], v244, s[0:1]
	global_load_dwordx4 v[54:57], v244, s[0:1] offset:1024
	global_load_dwordx4 v[58:61], v244, s[0:1] offset:2048
	global_load_dwordx4 v[62:65], v244, s[0:1] offset:3072
	s_waitcnt vmcnt(32)
; DI unsigned pk_bf16(float lo, float hi) { f32x2 v = {lo, hi}; bf16v2 b = __builtin_convertvector(v, bf16v2); return __builtin_bit_cast(unsigned, b); }
; DI float red64(float x) { for (int o = 32; o > 0; o >>= 1) x += __shfl_xor(x, o); return x; }
; DI void modnorm_rows(const Params& p, int l, int which  , bool from_inputs, bool skip_ctx, int w0, int wstride, int lane) {
;     ...
;   for (; i < nrows; i += wstride) {
;     const int row = rowof(i); const int b = row / TB, s = row % TB;
;     f32x4 v[4];
; #pragma unroll
;     for (int q = 0; q < 4; ++q) v[q] = vn[q];
;     if (i + wstride < nrows) {
;       const int rn = rowof(i + wstride); const float* src = xsrc_row(p, from_inputs, rn / TB, rn % TB);
; #pragma unroll
;       for (int q = 0; q < 4; ++q) vn[q] = *(const f32x4*)(src + q * 256 + lane * 4);
;     }
;     const float* mod = p.MOD + (size_t)(l * 9 + (s < NCTX ? 8 : b)) * 6144 + (which ? 3 * 1024 : 0);
;     f32x4 sh[4], sc[4];
; #pragma unroll
;     for (int q = 0; q < 4; ++q) { sh[q] = *(const f32x4*)(mod + q * 256 + lane * 4); sc[q] = *(const f32x4*)(mod + 1024 + q * 256 + lane * 4); }
;     float ss = 0.f;
; #pragma unroll
;     for (int q = 0; q < 4; ++q) ss += v[q][0] * v[q][0] + v[q][1] * v[q][1] + v[q][2] * v[q][2] + v[q][3] * v[q][3];
;     ss = red64(ss);
;     const float rs = rsqrtf(ss * (1.f / 1024.f) + EPSF);
;     bf16_t* dst = p.HY + (size_t)row * DM;
; #pragma unroll
;     for (int q = 0; q < 4; ++q) {
;       float o[4];
; #pragma unroll
;       for (int j = 0; j < 4; ++j) o[j] = (v[q][j] * rs * gg[q][j]) * (1.f + sc[q][j]) + sh[q][j];
;       u32x2 w = {pk_bf16(o[0], o[1]), pk_bf16(o[2], o[3])};
;       *(u32x2*)(dst + q * 256 + lane * 4) = w;
;     }
	v_pk_mul_f32 v[246:247], v[66:67], v[66:67]
	v_pk_fma_f32 v[246:247], v[68:69], v[68:69], v[246:247]
	v_pk_fma_f32 v[246:247], v[70:71], v[70:71], v[246:247]
	v_pk_fma_f32 v[246:247], v[72:73], v[72:73], v[246:247]
	v_pk_fma_f32 v[246:247], v[74:75], v[74:75], v[246:247]
	v_pk_fma_f32 v[246:247], v[76:77], v[76:77], v[246:247]
	v_pk_fma_f32 v[246:247], v[78:79], v[78:79], v[246:247]
	v_pk_fma_f32 v[246:247], v[80:81], v[80:81], v[246:247]
	s_nop 0
	v_add_f32_e32 v246, v246, v247
	s_nop 1
	v_add_f32_dpp v246, v246, v246 quad_perm:[1,0,3,2] row_mask:0xf bank_mask:0xf
	s_nop 1
	v_add_f32_dpp v246, v246, v246 quad_perm:[2,3,0,1] row_mask:0xf bank_mask:0xf
	s_nop 1
	v_add_f32_dpp v246, v246, v246 row_half_mirror row_mask:0xf bank_mask:0xf
	s_nop 1
	v_add_f32_dpp v246, v246, v246 row_mirror row_mask:0xf bank_mask:0xf
	s_nop 1
	v_add_f32_dpp v246, v246, v246 row_bcast:15 row_mask:0xa bank_mask:0xf
	s_nop 1
	v_add_f32_dpp v246, v246, v246 row_bcast:31 row_mask:0xc bank_mask:0xf
	s_nop 1
	v_readlane_b32 s0, v246, 63
	s_add_i32 s21, s20, 8192
	s_lshl_b32 s21, s21, 11
	s_add_u32 s10, s16, s21
	s_addc_u32 s11, s17, 0
	v_mov_b32_e32 v248, s0
	v_fmamk_f32 v248, v248, 0x3a800000, v143
	v_rsq_f32_e32 v248, v248
	s_nop 0
	v_pk_mul_f32 v[66:67], v[66:67], v[248:249] op_sel_hi:[1,0]
	v_pk_add_f32 v[98:99], v[98:99], 1.0 op_sel_hi:[1,0]
	v_pk_mul_f32 v[66:67], v[2:3], v[66:67]
	v_pk_fma_f32 v[66:67], v[98:99], v[66:67], v[82:83]
	v_pk_mul_f32 v[68:69], v[68:69], v[248:249] op_sel_hi:[1,0]
	v_pk_add_f32 v[100:101], v[100:101], 1.0 op_sel_hi:[1,0]
	v_pk_mul_f32 v[68:69], v[4:5], v[68:69]
	v_pk_fma_f32 v[68:69], v[100:101], v[68:69], v[84:85]
	v_cvt_pk_bf16_f32 v82, v66, v67
	v_cvt_pk_bf16_f32 v83, v68, v69
	global_store_dwordx2 v245, v[82:83], s[10:11]
	v_pk_mul_f32 v[70:71], v[70:71], v[248:249] op_sel_hi:[1,0]
	v_pk_add_f32 v[102:103], v[102:103], 1.0 op_sel_hi:[1,0]
	v_pk_mul_f32 v[70:71], v[6:7], v[70:71]
	v_pk_fma_f32 v[70:71], v[102:103], v[70:71], v[86:87]
	v_pk_mul_f32 v[72:73], v[72:73], v[248:249] op_sel_hi:[1,0]
	v_pk_add_f32 v[104:105], v[104:105], 1.0 op_sel_hi:[1,0]
	v_pk_mul_f32 v[72:73], v[8:9], v[72:73]
	v_pk_fma_f32 v[72:73], v[104:105], v[72:73], v[88:89]
	v_cvt_pk_bf16_f32 v86, v70, v71
	v_cvt_pk_bf16_f32 v87, v72, v73
	global_store_dwordx2 v245, v[86:87], s[10:11] offset:512
	v_pk_mul_f32 v[74:75], v[74:75], v[248:249] op_sel_hi:[1,0]
	v_pk_add_f32 v[106:107], v[106:107], 1.0 op_sel_hi:[1,0]
	v_pk_mul_f32 v[74:75], v[10:11], v[74:75]
	v_pk_fma_f32 v[74:75], v[106:107], v[74:75], v[90:91]
	v_pk_mul_f32 v[76:77], v[76:77], v[248:249] op_sel_hi:[1,0]
	v_pk_add_f32 v[108:109], v[108:109], 1.0 op_sel_hi:[1,0]
	v_pk_mul_f32 v[76:77], v[12:13], v[76:77]
	v_pk_fma_f32 v[76:77], v[108:109], v[76:77], v[92:93]
	v_cvt_pk_bf16_f32 v90, v74, v75
	v_cvt_pk_bf16_f32 v91, v76, v77
	global_store_dwordx2 v245, v[90:91], s[10:11] offset:1024
	v_pk_mul_f32 v[78:79], v[78:79], v[248:249] op_sel_hi:[1,0]
	v_pk_add_f32 v[118:119], v[118:119], 1.0 op_sel_hi:[1,0]
	v_pk_mul_f32 v[78:79], v[14:15], v[78:79]
	v_pk_fma_f32 v[78:79], v[118:119], v[78:79], v[94:95]
	v_pk_mul_f32 v[80:81], v[80:81], v[248:249] op_sel_hi:[1,0]
	v_pk_add_f32 v[120:121], v[120:121], 1.0 op_sel_hi:[1,0]
	v_pk_mul_f32 v[80:81], v[16:17], v[80:81]
	v_pk_fma_f32 v[80:81], v[120:121], v[80:81], v[96:97]
	v_cvt_pk_bf16_f32 v94, v78, v79
	v_cvt_pk_bf16_f32 v95, v80, v81
	global_store_dwordx2 v245, v[94:95], s[10:11] offset:1536
	s_add_i32 s21, s20, 14336
	s_mul_hi_u32 s7, s21, 0x38e38e39
	s_lshr_b32 s7, s7, 9
	s_mul_i32 s8, s7, 0x900
	s_sub_i32 s8, s21, s8
	s_lshl_b32 s9, s7, 11
	s_add_i32 s9, s9, s8
	s_add_i32 s9, s9, 0xffffff00
	s_lshl_b32 s10, s7, 8
	s_add_i32 s10, s10, s8
	s_cmpk_gt_i32 s8, 0xff
	s_cselect_b32 s9, s9, s10
	s_cselect_b32 s26, s12, s14
	s_cselect_b32 s27, s13, s15
	s_cselect_b32 s10, s7, 8
	s_lshl_b32 s9, s9, 12
	s_add_u32 s26, s26, s9
	s_addc_u32 s27, s27, 0
	s_add_i32 s10, s10, s82
	s_mul_i32 s10, s10, s24
	s_add_u32 s28, s58, s10
	s_addc_u32 s29, s59, 0
	s_add_u32 s28, s28, 0x3000
	s_addc_u32 s29, s29, 0
	s_add_u32 s0, s28, 0x1000
	s_addc_u32 s1, s29, 0
	global_load_dwordx4 v[66:69], v244, s[26:27]
	global_load_dwordx4 v[70:73], v244, s[26:27] offset:1024
	global_load_dwordx4 v[74:77], v244, s[26:27] offset:2048
	global_load_dwordx4 v[78:81], v244, s[26:27] offset:3072
	global_load_dwordx4 v[82:85], v244, s[28:29]
	global_load_dwordx4 v[86:89], v244, s[28:29] offset:1024
	global_load_dwordx4 v[90:93], v244, s[28:29] offset:2048
	global_load_dwordx4 v[94:97], v244, s[28:29] offset:3072
	global_load_dwordx4 v[98:101], v244, s[0:1]
	global_load_dwordx4 v[102:105], v244, s[0:1] offset:1024
	global_load_dwordx4 v[106:109], v244, s[0:1] offset:2048
	global_load_dwordx4 v[118:121], v244, s[0:1] offset:3072
	s_waitcnt vmcnt(32)
; DI unsigned pk_bf16(float lo, float hi) { f32x2 v = {lo, hi}; bf16v2 b = __builtin_convertvector(v, bf16v2); return __builtin_bit_cast(unsigned, b); }
; DI float red64(float x) { for (int o = 32; o > 0; o >>= 1) x += __shfl_xor(x, o); return x; }
; DI void modnorm_rows(const Params& p, int l, int which  , bool from_inputs, bool skip_ctx, int w0, int wstride, int lane) {
;     ...
;   for (; i < nrows; i += wstride) {
;     const int row = rowof(i); const int b = row / TB, s = row % TB;
;     f32x4 v[4];
; #pragma unroll
;     for (int q = 0; q < 4; ++q) v[q] = vn[q];
;     if (i + wstride < nrows) {
;       const int rn = rowof(i + wstride); const float* src = xsrc_row(p, from_inputs, rn / TB, rn % TB);
; #pragma unroll
;       for (int q = 0; q < 4; ++q) vn[q] = *(const f32x4*)(src + q * 256 + lane * 4);
;     }
;     const float* mod = p.MOD + (size_t)(l * 9 + (s < NCTX ? 8 : b)) * 6144 + (which ? 3 * 1024 : 0);
;     f32x4 sh[4], sc[4];
; #pragma unroll
;     for (int q = 0; q < 4; ++q) { sh[q] = *(const f32x4*)(mod + q * 256 + lane * 4); sc[q] = *(const f32x4*)(mod + 1024 + q * 256 + lane * 4); }
;     float ss = 0.f;
; #pragma unroll
;     for (int q = 0; q < 4; ++q) ss += v[q][0] * v[q][0] + v[q][1] * v[q][1] + v[q][2] * v[q][2] + v[q][3] * v[q][3];
;     ss = red64(ss);
;     const float rs = rsqrtf(ss * (1.f / 1024.f) + EPSF);
;     bf16_t* dst = p.HY + (size_t)row * DM;
; #pragma unroll
;     for (int q = 0; q < 4; ++q) {
;       float o[4];
; #pragma unroll
;       for (int j = 0; j < 4; ++j) o[j] = (v[q][j] * rs * gg[q][j]) * (1.f + sc[q][j]) + sh[q][j];
;       u32x2 w = {pk_bf16(o[0], o[1]), pk_bf16(o[2], o[3])};
;       *(u32x2*)(dst + q * 256 + lane * 4) = w;
;     }
	v_pk_mul_f32 v[246:247], v[122:123], v[122:123]
	v_pk_fma_f32 v[246:247], v[124:125], v[124:125], v[246:247]
	v_pk_fma_f32 v[246:247], v[126:127], v[126:127], v[246:247]
	v_pk_fma_f32 v[246:247], v[128:129], v[128:129], v[246:247]
	v_pk_fma_f32 v[246:247], v[130:131], v[130:131], v[246:247]
	v_pk_fma_f32 v[246:247], v[132:133], v[132:133], v[246:247]
	v_pk_fma_f32 v[246:247], v[134:135], v[134:135], v[246:247]
	v_pk_fma_f32 v[246:247], v[136:137], v[136:137], v[246:247]
	s_nop 0
	v_add_f32_e32 v246, v246, v247
	s_nop 1
	v_add_f32_dpp v246, v246, v246 quad_perm:[1,0,3,2] row_mask:0xf bank_mask:0xf
	s_nop 1
	v_add_f32_dpp v246, v246, v246 quad_perm:[2,3,0,1] row_mask:0xf bank_mask:0xf
	s_nop 1
	v_add_f32_dpp v246, v246, v246 row_half_mirror row_mask:0xf bank_mask:0xf
	s_nop 1
	v_add_f32_dpp v246, v246, v246 row_mirror row_mask:0xf bank_mask:0xf
	s_nop 1
	v_add_f32_dpp v246, v246, v246 row_bcast:15 row_mask:0xa bank_mask:0xf
	s_nop 1
	v_add_f32_dpp v246, v246, v246 row_bcast:31 row_mask:0xc bank_mask:0xf
	s_nop 1
	v_readlane_b32 s0, v246, 63
	s_add_i32 s21, s20, 10240
	s_lshl_b32 s21, s21, 11
	s_add_u32 s10, s16, s21
	s_addc_u32 s11, s17, 0
	v_mov_b32_e32 v248, s0
	v_fmamk_f32 v248, v248, 0x3a800000, v143
	v_rsq_f32_e32 v248, v248
	s_nop 0
	v_pk_mul_f32 v[122:123], v[122:123], v[248:249] op_sel_hi:[1,0]
	v_pk_add_f32 v[176:177], v[176:177], 1.0 op_sel_hi:[1,0]
	v_pk_mul_f32 v[122:123], v[2:3], v[122:123]
	v_pk_fma_f32 v[122:123], v[176:177], v[122:123], v[160:161]
	v_pk_mul_f32 v[124:125], v[124:125], v[248:249] op_sel_hi:[1,0]
	v_pk_add_f32 v[178:179], v[178:179], 1.0 op_sel_hi:[1,0]
	v_pk_mul_f32 v[124:125], v[4:5], v[124:125]
	v_pk_fma_f32 v[124:125], v[178:179], v[124:125], v[162:163]
	v_cvt_pk_bf16_f32 v160, v122, v123
	v_cvt_pk_bf16_f32 v161, v124, v125
	global_store_dwordx2 v245, v[160:161], s[10:11]
	v_pk_mul_f32 v[126:127], v[126:127], v[248:249] op_sel_hi:[1,0]
	v_pk_add_f32 v[180:181], v[180:181], 1.0 op_sel_hi:[1,0]
	v_pk_mul_f32 v[126:127], v[6:7], v[126:127]
	v_pk_fma_f32 v[126:127], v[180:181], v[126:127], v[164:165]
	v_pk_mul_f32 v[128:129], v[128:129], v[248:249] op_sel_hi:[1,0]
	v_pk_add_f32 v[182:183], v[182:183], 1.0 op_sel_hi:[1,0]
	v_pk_mul_f32 v[128:129], v[8:9], v[128:129]
	v_pk_fma_f32 v[128:129], v[182:183], v[128:129], v[166:167]
	v_cvt_pk_bf16_f32 v164, v126, v127
	v_cvt_pk_bf16_f32 v165, v128, v129
	global_store_dwordx2 v245, v[164:165], s[10:11] offset:512
	v_pk_mul_f32 v[130:131], v[130:131], v[248:249] op_sel_hi:[1,0]
	v_pk_add_f32 v[184:185], v[184:185], 1.0 op_sel_hi:[1,0]
	v_pk_mul_f32 v[130:131], v[10:11], v[130:131]
	v_pk_fma_f32 v[130:131], v[184:185], v[130:131], v[168:169]
	v_pk_mul_f32 v[132:133], v[132:133], v[248:249] op_sel_hi:[1,0]
	v_pk_add_f32 v[186:187], v[186:187], 1.0 op_sel_hi:[1,0]
	v_pk_mul_f32 v[132:133], v[12:13], v[132:133]
	v_pk_fma_f32 v[132:133], v[186:187], v[132:133], v[170:171]
	v_cvt_pk_bf16_f32 v168, v130, v131
	v_cvt_pk_bf16_f32 v169, v132, v133
	global_store_dwordx2 v245, v[168:169], s[10:11] offset:1024
	v_pk_mul_f32 v[134:135], v[134:135], v[248:249] op_sel_hi:[1,0]
	v_pk_add_f32 v[188:189], v[188:189], 1.0 op_sel_hi:[1,0]
	v_pk_mul_f32 v[134:135], v[14:15], v[134:135]
	v_pk_fma_f32 v[134:135], v[188:189], v[134:135], v[172:173]
	v_pk_mul_f32 v[136:137], v[136:137], v[248:249] op_sel_hi:[1,0]
	v_pk_add_f32 v[190:191], v[190:191], 1.0 op_sel_hi:[1,0]
	v_pk_mul_f32 v[136:137], v[16:17], v[136:137]
	v_pk_fma_f32 v[136:137], v[190:191], v[136:137], v[174:175]
	v_cvt_pk_bf16_f32 v172, v134, v135
	v_cvt_pk_bf16_f32 v173, v136, v137
	global_store_dwordx2 v245, v[172:173], s[10:11] offset:1536
	s_add_i32 s21, s20, 16384
	s_mul_hi_u32 s7, s21, 0x38e38e39
	s_lshr_b32 s7, s7, 9
	s_mul_i32 s8, s7, 0x900
	s_sub_i32 s8, s21, s8
	s_lshl_b32 s9, s7, 11
	s_add_i32 s9, s9, s8
	s_add_i32 s9, s9, 0xffffff00
	s_lshl_b32 s10, s7, 8
	s_add_i32 s10, s10, s8
	s_cmpk_gt_i32 s8, 0xff
	s_cselect_b32 s9, s9, s10
	s_cselect_b32 s26, s12, s14
	s_cselect_b32 s27, s13, s15
	s_cselect_b32 s10, s7, 8
	s_lshl_b32 s9, s9, 12
	s_add_u32 s26, s26, s9
	s_addc_u32 s27, s27, 0
	s_add_i32 s10, s10, s82
	s_mul_i32 s10, s10, s24
	s_add_u32 s28, s58, s10
	s_addc_u32 s29, s59, 0
	s_add_u32 s28, s28, 0x3000
	s_addc_u32 s29, s29, 0
	s_add_u32 s0, s28, 0x1000
	s_addc_u32 s1, s29, 0
	global_load_dwordx4 v[122:125], v244, s[26:27]
	global_load_dwordx4 v[126:129], v244, s[26:27] offset:1024
	global_load_dwordx4 v[130:133], v244, s[26:27] offset:2048
	global_load_dwordx4 v[134:137], v244, s[26:27] offset:3072
	global_load_dwordx4 v[160:163], v244, s[28:29]
	global_load_dwordx4 v[164:167], v244, s[28:29] offset:1024
	global_load_dwordx4 v[168:171], v244, s[28:29] offset:2048
	global_load_dwordx4 v[172:175], v244, s[28:29] offset:3072
	global_load_dwordx4 v[176:179], v244, s[0:1]
	global_load_dwordx4 v[180:183], v244, s[0:1] offset:1024
	global_load_dwordx4 v[184:187], v244, s[0:1] offset:2048
	global_load_dwordx4 v[188:191], v244, s[0:1] offset:3072
	s_waitcnt vmcnt(32)
; DI unsigned pk_bf16(float lo, float hi) { f32x2 v = {lo, hi}; bf16v2 b = __builtin_convertvector(v, bf16v2); return __builtin_bit_cast(unsigned, b); }
; DI float red64(float x) { for (int o = 32; o > 0; o >>= 1) x += __shfl_xor(x, o); return x; }
; DI void modnorm_rows(const Params& p, int l, int which  , bool from_inputs, bool skip_ctx, int w0, int wstride, int lane) {
;     ...
;     float ss = 0.f;
; #pragma unroll
;     for (int q = 0; q < 4; ++q) ss += v[q][0] * v[q][0] + v[q][1] * v[q][1] + v[q][2] * v[q][2] + v[q][3] * v[q][3];
;     ss = red64(ss);
;     const float rs = rsqrtf(ss * (1.f / 1024.f) + EPSF);
;     bf16_t* dst = p.HY + (size_t)row * DM;
; #pragma unroll
;     for (int q = 0; q < 4; ++q) {
;       float o[4];
; #pragma unroll
;       for (int j = 0; j < 4; ++j) o[j] = (v[q][j] * rs * gg[q][j]) * (1.f + sc[q][j]) + sh[q][j];
;       u32x2 w = {pk_bf16(o[0], o[1]), pk_bf16(o[2], o[3])};
;       *(u32x2*)(dst + q * 256 + lane * 4) = w;
;     }
	v_pk_mul_f32 v[246:247], v[18:19], v[18:19]
	v_pk_fma_f32 v[246:247], v[20:21], v[20:21], v[246:247]
	v_pk_fma_f32 v[246:247], v[22:23], v[22:23], v[246:247]
	v_pk_fma_f32 v[246:247], v[24:25], v[24:25], v[246:247]
	v_pk_fma_f32 v[246:247], v[26:27], v[26:27], v[246:247]
	v_pk_fma_f32 v[246:247], v[28:29], v[28:29], v[246:247]
	v_pk_fma_f32 v[246:247], v[30:31], v[30:31], v[246:247]
	v_pk_fma_f32 v[246:247], v[32:33], v[32:33], v[246:247]
	s_nop 0
	v_add_f32_e32 v246, v246, v247
	s_nop 1
	v_add_f32_dpp v246, v246, v246 quad_perm:[1,0,3,2] row_mask:0xf bank_mask:0xf
	s_nop 1
	v_add_f32_dpp v246, v246, v246 quad_perm:[2,3,0,1] row_mask:0xf bank_mask:0xf
	s_nop 1
	v_add_f32_dpp v246, v246, v246 row_half_mirror row_mask:0xf bank_mask:0xf
	s_nop 1
	v_add_f32_dpp v246, v246, v246 row_mirror row_mask:0xf bank_mask:0xf
	s_nop 1
	v_add_f32_dpp v246, v246, v246 row_bcast:15 row_mask:0xa bank_mask:0xf
	s_nop 1
	v_add_f32_dpp v246, v246, v246 row_bcast:31 row_mask:0xc bank_mask:0xf
	s_nop 1
	v_readlane_b32 s0, v246, 63
	s_add_i32 s21, s20, 12288
	s_lshl_b32 s21, s21, 11
	s_add_u32 s10, s16, s21
	s_addc_u32 s11, s17, 0
	v_mov_b32_e32 v248, s0
	v_fmamk_f32 v248, v248, 0x3a800000, v143
	v_rsq_f32_e32 v248, v248
	s_nop 0
	v_pk_mul_f32 v[18:19], v[18:19], v[248:249] op_sel_hi:[1,0]
	v_pk_add_f32 v[50:51], v[50:51], 1.0 op_sel_hi:[1,0]
	v_pk_mul_f32 v[18:19], v[2:3], v[18:19]
	v_pk_fma_f32 v[18:19], v[50:51], v[18:19], v[34:35]
	v_pk_mul_f32 v[20:21], v[20:21], v[248:249] op_sel_hi:[1,0]
	v_pk_add_f32 v[52:53], v[52:53], 1.0 op_sel_hi:[1,0]
	v_pk_mul_f32 v[20:21], v[4:5], v[20:21]
	v_pk_fma_f32 v[20:21], v[52:53], v[20:21], v[36:37]
	v_cvt_pk_bf16_f32 v34, v18, v19
	v_cvt_pk_bf16_f32 v35, v20, v21
	global_store_dwordx2 v245, v[34:35], s[10:11]
	v_pk_mul_f32 v[22:23], v[22:23], v[248:249] op_sel_hi:[1,0]
	v_pk_add_f32 v[54:55], v[54:55], 1.0 op_sel_hi:[1,0]
	v_pk_mul_f32 v[22:23], v[6:7], v[22:23]
	v_pk_fma_f32 v[22:23], v[54:55], v[22:23], v[38:39]
	v_pk_mul_f32 v[24:25], v[24:25], v[248:249] op_sel_hi:[1,0]
	v_pk_add_f32 v[56:57], v[56:57], 1.0 op_sel_hi:[1,0]
	v_pk_mul_f32 v[24:25], v[8:9], v[24:25]
	v_pk_fma_f32 v[24:25], v[56:57], v[24:25], v[40:41]
	v_cvt_pk_bf16_f32 v38, v22, v23
	v_cvt_pk_bf16_f32 v39, v24, v25
	global_store_dwordx2 v245, v[38:39], s[10:11] offset:512
	v_pk_mul_f32 v[26:27], v[26:27], v[248:249] op_sel_hi:[1,0]
	v_pk_add_f32 v[58:59], v[58:59], 1.0 op_sel_hi:[1,0]
	v_pk_mul_f32 v[26:27], v[10:11], v[26:27]
	v_pk_fma_f32 v[26:27], v[58:59], v[26:27], v[42:43]
	v_pk_mul_f32 v[28:29], v[28:29], v[248:249] op_sel_hi:[1,0]
	v_pk_add_f32 v[60:61], v[60:61], 1.0 op_sel_hi:[1,0]
	v_pk_mul_f32 v[28:29], v[12:13], v[28:29]
	v_pk_fma_f32 v[28:29], v[60:61], v[28:29], v[44:45]
	v_cvt_pk_bf16_f32 v42, v26, v27
	v_cvt_pk_bf16_f32 v43, v28, v29
	global_store_dwordx2 v245, v[42:43], s[10:11] offset:1024
	v_pk_mul_f32 v[30:31], v[30:31], v[248:249] op_sel_hi:[1,0]
	v_pk_add_f32 v[62:63], v[62:63], 1.0 op_sel_hi:[1,0]
	v_pk_mul_f32 v[30:31], v[14:15], v[30:31]
	v_pk_fma_f32 v[30:31], v[62:63], v[30:31], v[46:47]
	v_pk_mul_f32 v[32:33], v[32:33], v[248:249] op_sel_hi:[1,0]
	v_pk_add_f32 v[64:65], v[64:65], 1.0 op_sel_hi:[1,0]
	v_pk_mul_f32 v[32:33], v[16:17], v[32:33]
	v_pk_fma_f32 v[32:33], v[64:65], v[32:33], v[48:49]
	v_cvt_pk_bf16_f32 v46, v30, v31
	v_cvt_pk_bf16_f32 v47, v32, v33
	global_store_dwordx2 v245, v[46:47], s[10:11] offset:1536
	s_waitcnt vmcnt(20)
	v_pk_mul_f32 v[246:247], v[66:67], v[66:67]
	v_pk_fma_f32 v[246:247], v[68:69], v[68:69], v[246:247]
	v_pk_fma_f32 v[246:247], v[70:71], v[70:71], v[246:247]
	v_pk_fma_f32 v[246:247], v[72:73], v[72:73], v[246:247]
	v_pk_fma_f32 v[246:247], v[74:75], v[74:75], v[246:247]
	v_pk_fma_f32 v[246:247], v[76:77], v[76:77], v[246:247]
	v_pk_fma_f32 v[246:247], v[78:79], v[78:79], v[246:247]
	v_pk_fma_f32 v[246:247], v[80:81], v[80:81], v[246:247]
	s_nop 0
	v_add_f32_e32 v246, v246, v247
	s_nop 1
	v_add_f32_dpp v246, v246, v246 quad_perm:[1,0,3,2] row_mask:0xf bank_mask:0xf
	s_nop 1
	v_add_f32_dpp v246, v246, v246 quad_perm:[2,3,0,1] row_mask:0xf bank_mask:0xf
	s_nop 1
	v_add_f32_dpp v246, v246, v246 row_half_mirror row_mask:0xf bank_mask:0xf
	s_nop 1
	v_add_f32_dpp v246, v246, v246 row_mirror row_mask:0xf bank_mask:0xf
	s_nop 1
	v_add_f32_dpp v246, v246, v246 row_bcast:15 row_mask:0xa bank_mask:0xf
	s_nop 1
	v_add_f32_dpp v246, v246, v246 row_bcast:31 row_mask:0xc bank_mask:0xf
	s_nop 1
	v_readlane_b32 s0, v246, 63
	s_add_i32 s21, s20, 14336
	s_lshl_b32 s21, s21, 11
	s_add_u32 s10, s16, s21
	s_addc_u32 s11, s17, 0
	v_mov_b32_e32 v248, s0
	v_fmamk_f32 v248, v248, 0x3a800000, v143
	v_rsq_f32_e32 v248, v248
	s_nop 0
	v_pk_mul_f32 v[66:67], v[66:67], v[248:249] op_sel_hi:[1,0]
	v_pk_add_f32 v[98:99], v[98:99], 1.0 op_sel_hi:[1,0]
	v_pk_mul_f32 v[66:67], v[2:3], v[66:67]
	v_pk_fma_f32 v[66:67], v[98:99], v[66:67], v[82:83]
	v_pk_mul_f32 v[68:69], v[68:69], v[248:249] op_sel_hi:[1,0]
	v_pk_add_f32 v[100:101], v[100:101], 1.0 op_sel_hi:[1,0]
	v_pk_mul_f32 v[68:69], v[4:5], v[68:69]
	v_pk_fma_f32 v[68:69], v[100:101], v[68:69], v[84:85]
	v_cvt_pk_bf16_f32 v82, v66, v67
	v_cvt_pk_bf16_f32 v83, v68, v69
	global_store_dwordx2 v245, v[82:83], s[10:11]
	v_pk_mul_f32 v[70:71], v[70:71], v[248:249] op_sel_hi:[1,0]
	v_pk_add_f32 v[102:103], v[102:103], 1.0 op_sel_hi:[1,0]
	v_pk_mul_f32 v[70:71], v[6:7], v[70:71]
	v_pk_fma_f32 v[70:71], v[102:103], v[70:71], v[86:87]
	v_pk_mul_f32 v[72:73], v[72:73], v[248:249] op_sel_hi:[1,0]
	v_pk_add_f32 v[104:105], v[104:105], 1.0 op_sel_hi:[1,0]
	v_pk_mul_f32 v[72:73], v[8:9], v[72:73]
	v_pk_fma_f32 v[72:73], v[104:105], v[72:73], v[88:89]
	v_cvt_pk_bf16_f32 v86, v70, v71
	v_cvt_pk_bf16_f32 v87, v72, v73
	global_store_dwordx2 v245, v[86:87], s[10:11] offset:512
	v_pk_mul_f32 v[74:75], v[74:75], v[248:249] op_sel_hi:[1,0]
	v_pk_add_f32 v[106:107], v[106:107], 1.0 op_sel_hi:[1,0]
	v_pk_mul_f32 v[74:75], v[10:11], v[74:75]
	v_pk_fma_f32 v[74:75], v[106:107], v[74:75], v[90:91]
	v_pk_mul_f32 v[76:77], v[76:77], v[248:249] op_sel_hi:[1,0]
	v_pk_add_f32 v[108:109], v[108:109], 1.0 op_sel_hi:[1,0]
	v_pk_mul_f32 v[76:77], v[12:13], v[76:77]
	v_pk_fma_f32 v[76:77], v[108:109], v[76:77], v[92:93]
	v_cvt_pk_bf16_f32 v90, v74, v75
	v_cvt_pk_bf16_f32 v91, v76, v77
	global_store_dwordx2 v245, v[90:91], s[10:11] offset:1024
	v_pk_mul_f32 v[78:79], v[78:79], v[248:249] op_sel_hi:[1,0]
	v_pk_add_f32 v[118:119], v[118:119], 1.0 op_sel_hi:[1,0]
	v_pk_mul_f32 v[78:79], v[14:15], v[78:79]
	v_pk_fma_f32 v[78:79], v[118:119], v[78:79], v[94:95]
	v_pk_mul_f32 v[80:81], v[80:81], v[248:249] op_sel_hi:[1,0]
	v_pk_add_f32 v[120:121], v[120:121], 1.0 op_sel_hi:[1,0]
	v_pk_mul_f32 v[80:81], v[16:17], v[80:81]
	v_pk_fma_f32 v[80:81], v[120:121], v[80:81], v[96:97]
	v_cvt_pk_bf16_f32 v94, v78, v79
	v_cvt_pk_bf16_f32 v95, v80, v81
	global_store_dwordx2 v245, v[94:95], s[10:11] offset:1536
	s_waitcnt vmcnt(8)
; DI unsigned pk_bf16(float lo, float hi) { f32x2 v = {lo, hi}; bf16v2 b = __builtin_convertvector(v, bf16v2); return __builtin_bit_cast(unsigned, b); }
; DI float red64(float x) { for (int o = 32; o > 0; o >>= 1) x += __shfl_xor(x, o); return x; }
; DI void modnorm_rows(const Params& p, int l, int which  , bool from_inputs, bool skip_ctx, int w0, int wstride, int lane) {
;     ...
;   auto rowof = [&](int i) -> int { return skip_ctx ? (i / NLAT) * TB + NCTX + (i % NLAT) : i; };
;   int i = w0;
;   if (i >= nrows) return;
;   f32x4 vn[4];
;   {
;     const int row = rowof(i); const float* src = xsrc_row(p, from_inputs, row / TB, row % TB);
; #pragma unroll
;     for (int q = 0; q < 4; ++q) vn[q] = *(const f32x4*)(src + q * 256 + lane * 4);
;   }
;   for (; i < nrows; i += wstride) {
;     const int row = rowof(i); const int b = row / TB, s = row % TB;
;     f32x4 v[4];
; #pragma unroll
;     for (int q = 0; q < 4; ++q) v[q] = vn[q];
;     if (i + wstride < nrows) {
;       const int rn = rowof(i + wstride); const float* src = xsrc_row(p, from_inputs, rn / TB, rn % TB);
; #pragma unroll
;       for (int q = 0; q < 4; ++q) vn[q] = *(const f32x4*)(src + q * 256 + lane * 4);
;     ...
;     float ss = 0.f;
; #pragma unroll
;     for (int q = 0; q < 4; ++q) ss += v[q][0] * v[q][0] + v[q][1] * v[q][1] + v[q][2] * v[q][2] + v[q][3] * v[q][3];
;     ss = red64(ss);
;     const float rs = rsqrtf(ss * (1.f / 1024.f) + EPSF);
;     bf16_t* dst = p.HY + (size_t)row * DM;
; #pragma unroll
;     for (int q = 0; q < 4; ++q) {
;       float o[4];
; #pragma unroll
;       for (int j = 0; j < 4; ++j) o[j] = (v[q][j] * rs * gg[q][j]) * (1.f + sc[q][j]) + sh[q][j];
;       u32x2 w = {pk_bf16(o[0], o[1]), pk_bf16(o[2], o[3])};
;       *(u32x2*)(dst + q * 256 + lane * 4) = w;
;     }
	v_pk_mul_f32 v[246:247], v[122:123], v[122:123]
	v_pk_fma_f32 v[246:247], v[124:125], v[124:125], v[246:247]
	v_pk_fma_f32 v[246:247], v[126:127], v[126:127], v[246:247]
	v_pk_fma_f32 v[246:247], v[128:129], v[128:129], v[246:247]
	v_pk_fma_f32 v[246:247], v[130:131], v[130:131], v[246:247]
	v_pk_fma_f32 v[246:247], v[132:133], v[132:133], v[246:247]
	v_pk_fma_f32 v[246:247], v[134:135], v[134:135], v[246:247]
	v_pk_fma_f32 v[246:247], v[136:137], v[136:137], v[246:247]
	s_nop 0
	v_add_f32_e32 v246, v246, v247
	s_nop 1
	v_add_f32_dpp v246, v246, v246 quad_perm:[1,0,3,2] row_mask:0xf bank_mask:0xf
	s_nop 1
	v_add_f32_dpp v246, v246, v246 quad_perm:[2,3,0,1] row_mask:0xf bank_mask:0xf
	s_nop 1
	v_add_f32_dpp v246, v246, v246 row_half_mirror row_mask:0xf bank_mask:0xf
	s_nop 1
	v_add_f32_dpp v246, v246, v246 row_mirror row_mask:0xf bank_mask:0xf
	s_nop 1
	v_add_f32_dpp v246, v246, v246 row_bcast:15 row_mask:0xa bank_mask:0xf
	s_nop 1
	v_add_f32_dpp v246, v246, v246 row_bcast:31 row_mask:0xc bank_mask:0xf
	s_nop 1
	v_readlane_b32 s0, v246, 63
	s_add_i32 s21, s20, 16384
	s_lshl_b32 s21, s21, 11
	s_add_u32 s10, s16, s21
	s_addc_u32 s11, s17, 0
	v_mov_b32_e32 v248, s0
	v_fmamk_f32 v248, v248, 0x3a800000, v143
	v_rsq_f32_e32 v248, v248
	s_nop 0
	v_pk_mul_f32 v[122:123], v[122:123], v[248:249] op_sel_hi:[1,0]
	v_pk_add_f32 v[176:177], v[176:177], 1.0 op_sel_hi:[1,0]
	v_pk_mul_f32 v[122:123], v[2:3], v[122:123]
	v_pk_fma_f32 v[122:123], v[176:177], v[122:123], v[160:161]
	v_pk_mul_f32 v[124:125], v[124:125], v[248:249] op_sel_hi:[1,0]
	v_pk_add_f32 v[178:179], v[178:179], 1.0 op_sel_hi:[1,0]
	v_pk_mul_f32 v[124:125], v[4:5], v[124:125]
	v_pk_fma_f32 v[124:125], v[178:179], v[124:125], v[162:163]
	v_cvt_pk_bf16_f32 v160, v122, v123
	v_cvt_pk_bf16_f32 v161, v124, v125
	global_store_dwordx2 v245, v[160:161], s[10:11]
	v_pk_mul_f32 v[126:127], v[126:127], v[248:249] op_sel_hi:[1,0]
	v_pk_add_f32 v[180:181], v[180:181], 1.0 op_sel_hi:[1,0]
	v_pk_mul_f32 v[126:127], v[6:7], v[126:127]
	v_pk_fma_f32 v[126:127], v[180:181], v[126:127], v[164:165]
	v_pk_mul_f32 v[128:129], v[128:129], v[248:249] op_sel_hi:[1,0]
	v_pk_add_f32 v[182:183], v[182:183], 1.0 op_sel_hi:[1,0]
	v_pk_mul_f32 v[128:129], v[8:9], v[128:129]
	v_pk_fma_f32 v[128:129], v[182:183], v[128:129], v[166:167]
	v_cvt_pk_bf16_f32 v164, v126, v127
	v_cvt_pk_bf16_f32 v165, v128, v129
	global_store_dwordx2 v245, v[164:165], s[10:11] offset:512
	v_pk_mul_f32 v[130:131], v[130:131], v[248:249] op_sel_hi:[1,0]
	v_pk_add_f32 v[184:185], v[184:185], 1.0 op_sel_hi:[1,0]
	v_pk_mul_f32 v[130:131], v[10:11], v[130:131]
	v_pk_fma_f32 v[130:131], v[184:185], v[130:131], v[168:169]
	v_pk_mul_f32 v[132:133], v[132:133], v[248:249] op_sel_hi:[1,0]
	v_pk_add_f32 v[186:187], v[186:187], 1.0 op_sel_hi:[1,0]
	v_pk_mul_f32 v[132:133], v[12:13], v[132:133]
	v_pk_fma_f32 v[132:133], v[186:187], v[132:133], v[170:171]
	v_cvt_pk_bf16_f32 v168, v130, v131
	v_cvt_pk_bf16_f32 v169, v132, v133
	global_store_dwordx2 v245, v[168:169], s[10:11] offset:1024
	v_pk_mul_f32 v[134:135], v[134:135], v[248:249] op_sel_hi:[1,0]
	v_pk_add_f32 v[188:189], v[188:189], 1.0 op_sel_hi:[1,0]
	v_pk_mul_f32 v[134:135], v[14:15], v[134:135]
	v_pk_fma_f32 v[134:135], v[188:189], v[134:135], v[172:173]
	v_pk_mul_f32 v[136:137], v[136:137], v[248:249] op_sel_hi:[1,0]
	v_pk_add_f32 v[190:191], v[190:191], 1.0 op_sel_hi:[1,0]
	v_pk_mul_f32 v[136:137], v[16:17], v[136:137]
	v_pk_fma_f32 v[136:137], v[190:191], v[136:137], v[174:175]
	v_cvt_pk_bf16_f32 v172, v134, v135
	v_cvt_pk_bf16_f32 v173, v136, v137
	global_store_dwordx2 v245, v[172:173], s[10:11] offset:1536
	s_branch .Lnorm2_done
.Lnorm2_last:
	s_add_i32 s21, s20, 256
	s_mov_b32 s7, 0
	s_add_i32 s8, s20, 256
	s_lshl_b32 s9, s7, 11
	s_add_i32 s9, s9, s8
	s_add_i32 s9, s9, 0xffffff00
	s_lshl_b32 s10, s7, 8
	s_add_i32 s10, s10, s8
	s_cmpk_gt_i32 s8, 0xff
	s_cselect_b32 s9, s9, s10
	s_cselect_b32 s26, s12, s14
	s_cselect_b32 s27, s13, s15
	s_cselect_b32 s10, s7, 8
	s_lshl_b32 s9, s9, 12
	s_add_u32 s26, s26, s9
	s_addc_u32 s27, s27, 0
	s_add_i32 s10, s10, s82
	s_mul_i32 s10, s10, s24
	s_add_u32 s28, s58, s10
	s_addc_u32 s29, s59, 0
	s_add_u32 s28, s28, 0x3000
	s_addc_u32 s29, s29, 0
	s_add_u32 s0, s28, 0x1000
	s_addc_u32 s1, s29, 0
	global_load_dwordx4 v[18:21], v244, s[26:27]
	global_load_dwordx4 v[22:25], v244, s[26:27] offset:1024
	global_load_dwordx4 v[26:29], v244, s[26:27] offset:2048
	global_load_dwordx4 v[30:33], v244, s[26:27] offset:3072
	global_load_dwordx4 v[34:37], v244, s[28:29]
	global_load_dwordx4 v[38:41], v244, s[28:29] offset:1024
	global_load_dwordx4 v[42:45], v244, s[28:29] offset:2048
	global_load_dwordx4 v[46:49], v244, s[28:29] offset:3072
	global_load_dwordx4 v[50:53], v244, s[0:1]
	global_load_dwordx4 v[54:57], v244, s[0:1] offset:1024
	global_load_dwordx4 v[58:61], v244, s[0:1] offset:2048
	global_load_dwordx4 v[62:65], v244, s[0:1] offset:3072
	s_add_i32 s21, s20, 2560
	s_mov_b32 s7, 1
	s_add_i32 s8, s20, 256
	s_lshl_b32 s9, s7, 11
	s_add_i32 s9, s9, s8
	s_add_i32 s9, s9, 0xffffff00
	s_lshl_b32 s10, s7, 8
	s_add_i32 s10, s10, s8
	s_cmpk_gt_i32 s8, 0xff
	s_cselect_b32 s9, s9, s10
	s_cselect_b32 s26, s12, s14
	s_cselect_b32 s27, s13, s15
	s_cselect_b32 s10, s7, 8
	s_lshl_b32 s9, s9, 12
	s_add_u32 s26, s26, s9
	s_addc_u32 s27, s27, 0
	s_add_i32 s10, s10, s82
	s_mul_i32 s10, s10, s24
	s_add_u32 s28, s58, s10
	s_addc_u32 s29, s59, 0
	s_add_u32 s28, s28, 0x3000
	s_addc_u32 s29, s29, 0
	s_add_u32 s0, s28, 0x1000
	s_addc_u32 s1, s29, 0
	global_load_dwordx4 v[66:69], v244, s[26:27]
	global_load_dwordx4 v[70:73], v244, s[26:27] offset:1024
	global_load_dwordx4 v[74:77], v244, s[26:27] offset:2048
; DI unsigned pk_bf16(float lo, float hi) { f32x2 v = {lo, hi}; bf16v2 b = __builtin_convertvector(v, bf16v2); return __builtin_bit_cast(unsigned, b); }
; DI float red64(float x) { for (int o = 32; o > 0; o >>= 1) x += __shfl_xor(x, o); return x; }
; DI void modnorm_rows(const Params& p, int l, int which  , bool from_inputs, bool skip_ctx, int w0, int wstride, int lane) {
;     ...
;   auto rowof = [&](int i) -> int { return skip_ctx ? (i / NLAT) * TB + NCTX + (i % NLAT) : i; };
;   int i = w0;
;   if (i >= nrows) return;
;   f32x4 vn[4];
;   {
;     const int row = rowof(i); const float* src = xsrc_row(p, from_inputs, row / TB, row % TB);
; #pragma unroll
;     for (int q = 0; q < 4; ++q) vn[q] = *(const f32x4*)(src + q * 256 + lane * 4);
;   }
;   for (; i < nrows; i += wstride) {
;     const int row = rowof(i); const int b = row / TB, s = row % TB;
;     f32x4 v[4];
; #pragma unroll
;     for (int q = 0; q < 4; ++q) v[q] = vn[q];
;     if (i + wstride < nrows) {
;       const int rn = rowof(i + wstride); const float* src = xsrc_row(p, from_inputs, rn / TB, rn % TB);
; #pragma unroll
;       for (int q = 0; q < 4; ++q) vn[q] = *(const f32x4*)(src + q * 256 + lane * 4);
;     }
;     const float* mod = p.MOD + (size_t)(l * 9 + (s < NCTX ? 8 : b)) * 6144 + (which ? 3 * 1024 : 0);
;     f32x4 sh[4], sc[4];
; #pragma unroll
;     for (int q = 0; q < 4; ++q) { sh[q] = *(const f32x4*)(mod + q * 256 + lane * 4); sc[q] = *(const f32x4*)(mod + 1024 + q * 256 + lane * 4); }
;     float ss = 0.f;
; #pragma unroll
;     for (int q = 0; q < 4; ++q) ss += v[q][0] * v[q][0] + v[q][1] * v[q][1] + v[q][2] * v[q][2] + v[q][3] * v[q][3];
;     ss = red64(ss);
;     const float rs = rsqrtf(ss * (1.f / 1024.f) + EPSF);
;     bf16_t* dst = p.HY + (size_t)row * DM;
; #pragma unroll
;     for (int q = 0; q < 4; ++q) {
;       float o[4];
; #pragma unroll
;       for (int j = 0; j < 4; ++j) o[j] = (v[q][j] * rs * gg[q][j]) * (1.f + sc[q][j]) + sh[q][j];
;       u32x2 w = {pk_bf16(o[0], o[1]), pk_bf16(o[2], o[3])};
;       *(u32x2*)(dst + q * 256 + lane * 4) = w;
;     }
	global_load_dwordx4 v[78:81], v244, s[26:27] offset:3072
	global_load_dwordx4 v[82:85], v244, s[28:29]
	global_load_dwordx4 v[86:89], v244, s[28:29] offset:1024
	global_load_dwordx4 v[90:93], v244, s[28:29] offset:2048
	global_load_dwordx4 v[94:97], v244, s[28:29] offset:3072
	global_load_dwordx4 v[98:101], v244, s[0:1]
	global_load_dwordx4 v[102:105], v244, s[0:1] offset:1024
	global_load_dwordx4 v[106:109], v244, s[0:1] offset:2048
	global_load_dwordx4 v[118:121], v244, s[0:1] offset:3072
	s_add_i32 s21, s20, 4864
	s_mov_b32 s7, 2
	s_add_i32 s8, s20, 256
	s_lshl_b32 s9, s7, 11
	s_add_i32 s9, s9, s8
	s_add_i32 s9, s9, 0xffffff00
	s_lshl_b32 s10, s7, 8
	s_add_i32 s10, s10, s8
	s_cmpk_gt_i32 s8, 0xff
	s_cselect_b32 s9, s9, s10
	s_cselect_b32 s26, s12, s14
	s_cselect_b32 s27, s13, s15
	s_cselect_b32 s10, s7, 8
	s_lshl_b32 s9, s9, 12
	s_add_u32 s26, s26, s9
	s_addc_u32 s27, s27, 0
	s_add_i32 s10, s10, s82
	s_mul_i32 s10, s10, s24
	s_add_u32 s28, s58, s10
	s_addc_u32 s29, s59, 0
	s_add_u32 s28, s28, 0x3000
	s_addc_u32 s29, s29, 0
	s_add_u32 s0, s28, 0x1000
	s_addc_u32 s1, s29, 0
	global_load_dwordx4 v[122:125], v244, s[26:27]
	global_load_dwordx4 v[126:129], v244, s[26:27] offset:1024
	global_load_dwordx4 v[130:133], v244, s[26:27] offset:2048
	global_load_dwordx4 v[134:137], v244, s[26:27] offset:3072
	global_load_dwordx4 v[160:163], v244, s[28:29]
	global_load_dwordx4 v[164:167], v244, s[28:29] offset:1024
	global_load_dwordx4 v[168:171], v244, s[28:29] offset:2048
	global_load_dwordx4 v[172:175], v244, s[28:29] offset:3072
	global_load_dwordx4 v[176:179], v244, s[0:1]
	global_load_dwordx4 v[180:183], v244, s[0:1] offset:1024
	global_load_dwordx4 v[184:187], v244, s[0:1] offset:2048
	global_load_dwordx4 v[188:191], v244, s[0:1] offset:3072
	s_waitcnt vmcnt(24)
	v_pk_mul_f32 v[246:247], v[18:19], v[18:19]
	v_pk_fma_f32 v[246:247], v[20:21], v[20:21], v[246:247]
	v_pk_fma_f32 v[246:247], v[22:23], v[22:23], v[246:247]
	v_pk_fma_f32 v[246:247], v[24:25], v[24:25], v[246:247]
	v_pk_fma_f32 v[246:247], v[26:27], v[26:27], v[246:247]
	v_pk_fma_f32 v[246:247], v[28:29], v[28:29], v[246:247]
	v_pk_fma_f32 v[246:247], v[30:31], v[30:31], v[246:247]
	v_pk_fma_f32 v[246:247], v[32:33], v[32:33], v[246:247]
	s_nop 0
	v_add_f32_e32 v246, v246, v247
	s_nop 1
	v_add_f32_dpp v246, v246, v246 quad_perm:[1,0,3,2] row_mask:0xf bank_mask:0xf
	s_nop 1
	v_add_f32_dpp v246, v246, v246 quad_perm:[2,3,0,1] row_mask:0xf bank_mask:0xf
	s_nop 1
	v_add_f32_dpp v246, v246, v246 row_half_mirror row_mask:0xf bank_mask:0xf
	s_nop 1
	v_add_f32_dpp v246, v246, v246 row_mirror row_mask:0xf bank_mask:0xf
	s_nop 1
	v_add_f32_dpp v246, v246, v246 row_bcast:15 row_mask:0xa bank_mask:0xf
	s_nop 1
	v_add_f32_dpp v246, v246, v246 row_bcast:31 row_mask:0xc bank_mask:0xf
	s_nop 1
	v_readlane_b32 s0, v246, 63
	s_add_i32 s21, s20, 256
	s_lshl_b32 s21, s21, 11
	s_add_u32 s10, s16, s21
	s_addc_u32 s11, s17, 0
	v_mov_b32_e32 v248, s0
	v_fmamk_f32 v248, v248, 0x3a800000, v143
	v_rsq_f32_e32 v248, v248
	s_nop 0
	v_pk_mul_f32 v[18:19], v[18:19], v[248:249] op_sel_hi:[1,0]
	v_pk_add_f32 v[50:51], v[50:51], 1.0 op_sel_hi:[1,0]
	v_pk_mul_f32 v[18:19], v[2:3], v[18:19]
	v_pk_fma_f32 v[18:19], v[50:51], v[18:19], v[34:35]
	v_pk_mul_f32 v[20:21], v[20:21], v[248:249] op_sel_hi:[1,0]
	v_pk_add_f32 v[52:53], v[52:53], 1.0 op_sel_hi:[1,0]
	v_pk_mul_f32 v[20:21], v[4:5], v[20:21]
	v_pk_fma_f32 v[20:21], v[52:53], v[20:21], v[36:37]
	v_cvt_pk_bf16_f32 v34, v18, v19
	v_cvt_pk_bf16_f32 v35, v20, v21
	global_store_dwordx2 v245, v[34:35], s[10:11]
	v_pk_mul_f32 v[22:23], v[22:23], v[248:249] op_sel_hi:[1,0]
	v_pk_add_f32 v[54:55], v[54:55], 1.0 op_sel_hi:[1,0]
	v_pk_mul_f32 v[22:23], v[6:7], v[22:23]
	v_pk_fma_f32 v[22:23], v[54:55], v[22:23], v[38:39]
	v_pk_mul_f32 v[24:25], v[24:25], v[248:249] op_sel_hi:[1,0]
	v_pk_add_f32 v[56:57], v[56:57], 1.0 op_sel_hi:[1,0]
	v_pk_mul_f32 v[24:25], v[8:9], v[24:25]
	v_pk_fma_f32 v[24:25], v[56:57], v[24:25], v[40:41]
	v_cvt_pk_bf16_f32 v38, v22, v23
	v_cvt_pk_bf16_f32 v39, v24, v25
	global_store_dwordx2 v245, v[38:39], s[10:11] offset:512
	v_pk_mul_f32 v[26:27], v[26:27], v[248:249] op_sel_hi:[1,0]
	v_pk_add_f32 v[58:59], v[58:59], 1.0 op_sel_hi:[1,0]
	v_pk_mul_f32 v[26:27], v[10:11], v[26:27]
	v_pk_fma_f32 v[26:27], v[58:59], v[26:27], v[42:43]
	v_pk_mul_f32 v[28:29], v[28:29], v[248:249] op_sel_hi:[1,0]
	v_pk_add_f32 v[60:61], v[60:61], 1.0 op_sel_hi:[1,0]
	v_pk_mul_f32 v[28:29], v[12:13], v[28:29]
	v_pk_fma_f32 v[28:29], v[60:61], v[28:29], v[44:45]
	v_cvt_pk_bf16_f32 v42, v26, v27
	v_cvt_pk_bf16_f32 v43, v28, v29
	global_store_dwordx2 v245, v[42:43], s[10:11] offset:1024
	v_pk_mul_f32 v[30:31], v[30:31], v[248:249] op_sel_hi:[1,0]
	v_pk_add_f32 v[62:63], v[62:63], 1.0 op_sel_hi:[1,0]
	v_pk_mul_f32 v[30:31], v[14:15], v[30:31]
	v_pk_fma_f32 v[30:31], v[62:63], v[30:31], v[46:47]
	v_pk_mul_f32 v[32:33], v[32:33], v[248:249] op_sel_hi:[1,0]
	v_pk_add_f32 v[64:65], v[64:65], 1.0 op_sel_hi:[1,0]
	v_pk_mul_f32 v[32:33], v[16:17], v[32:33]
	v_pk_fma_f32 v[32:33], v[64:65], v[32:33], v[48:49]
	v_cvt_pk_bf16_f32 v46, v30, v31
	v_cvt_pk_bf16_f32 v47, v32, v33
	global_store_dwordx2 v245, v[46:47], s[10:11] offset:1536
	s_add_i32 s21, s20, 7168
	s_mov_b32 s7, 3
	s_add_i32 s8, s20, 256
	s_lshl_b32 s9, s7, 11
	s_add_i32 s9, s9, s8
	s_add_i32 s9, s9, 0xffffff00
	s_lshl_b32 s10, s7, 8
	s_add_i32 s10, s10, s8
	s_cmpk_gt_i32 s8, 0xff
	s_cselect_b32 s9, s9, s10
	s_cselect_b32 s26, s12, s14
	s_cselect_b32 s27, s13, s15
	s_cselect_b32 s10, s7, 8
	s_lshl_b32 s9, s9, 12
	s_add_u32 s26, s26, s9
	s_addc_u32 s27, s27, 0
	s_add_i32 s10, s10, s82
	s_mul_i32 s10, s10, s24
	s_add_u32 s28, s58, s10
	s_addc_u32 s29, s59, 0
	s_add_u32 s28, s28, 0x3000
	s_addc_u32 s29, s29, 0
	s_add_u32 s0, s28, 0x1000
	s_addc_u32 s1, s29, 0
	global_load_dwordx4 v[18:21], v244, s[26:27]
	global_load_dwordx4 v[22:25], v244, s[26:27] offset:1024
	global_load_dwordx4 v[26:29], v244, s[26:27] offset:2048
	global_load_dwordx4 v[30:33], v244, s[26:27] offset:3072
	global_load_dwordx4 v[34:37], v244, s[28:29]
	global_load_dwordx4 v[38:41], v244, s[28:29] offset:1024
	global_load_dwordx4 v[42:45], v244, s[28:29] offset:2048
	global_load_dwordx4 v[46:49], v244, s[28:29] offset:3072
	global_load_dwordx4 v[50:53], v244, s[0:1]
	global_load_dwordx4 v[54:57], v244, s[0:1] offset:1024
	global_load_dwordx4 v[58:61], v244, s[0:1] offset:2048
	global_load_dwordx4 v[62:65], v244, s[0:1] offset:3072
	s_waitcnt vmcnt(28)
; DI unsigned pk_bf16(float lo, float hi) { f32x2 v = {lo, hi}; bf16v2 b = __builtin_convertvector(v, bf16v2); return __builtin_bit_cast(unsigned, b); }
; DI float red64(float x) { for (int o = 32; o > 0; o >>= 1) x += __shfl_xor(x, o); return x; }
; DI void modnorm_rows(const Params& p, int l, int which  , bool from_inputs, bool skip_ctx, int w0, int wstride, int lane) {
;     ...
;   for (; i < nrows; i += wstride) {
;     const int row = rowof(i); const int b = row / TB, s = row % TB;
;     f32x4 v[4];
; #pragma unroll
;     for (int q = 0; q < 4; ++q) v[q] = vn[q];
;     if (i + wstride < nrows) {
;       const int rn = rowof(i + wstride); const float* src = xsrc_row(p, from_inputs, rn / TB, rn % TB);
; #pragma unroll
;       for (int q = 0; q < 4; ++q) vn[q] = *(const f32x4*)(src + q * 256 + lane * 4);
;     }
;     const float* mod = p.MOD + (size_t)(l * 9 + (s < NCTX ? 8 : b)) * 6144 + (which ? 3 * 1024 : 0);
;     f32x4 sh[4], sc[4];
; #pragma unroll
;     for (int q = 0; q < 4; ++q) { sh[q] = *(const f32x4*)(mod + q * 256 + lane * 4); sc[q] = *(const f32x4*)(mod + 1024 + q * 256 + lane * 4); }
;     float ss = 0.f;
; #pragma unroll
;     for (int q = 0; q < 4; ++q) ss += v[q][0] * v[q][0] + v[q][1] * v[q][1] + v[q][2] * v[q][2] + v[q][3] * v[q][3];
;     ss = red64(ss);
;     const float rs = rsqrtf(ss * (1.f / 1024.f) + EPSF);
;     bf16_t* dst = p.HY + (size_t)row * DM;
; #pragma unroll
;     for (int q = 0; q < 4; ++q) {
;       float o[4];
; #pragma unroll
;       for (int j = 0; j < 4; ++j) o[j] = (v[q][j] * rs * gg[q][j]) * (1.f + sc[q][j]) + sh[q][j];
;       u32x2 w = {pk_bf16(o[0], o[1]), pk_bf16(o[2], o[3])};
;       *(u32x2*)(dst + q * 256 + lane * 4) = w;
;     }
	v_pk_mul_f32 v[246:247], v[66:67], v[66:67]
	v_pk_fma_f32 v[246:247], v[68:69], v[68:69], v[246:247]
	v_pk_fma_f32 v[246:247], v[70:71], v[70:71], v[246:247]
	v_pk_fma_f32 v[246:247], v[72:73], v[72:73], v[246:247]
	v_pk_fma_f32 v[246:247], v[74:75], v[74:75], v[246:247]
	v_pk_fma_f32 v[246:247], v[76:77], v[76:77], v[246:247]
	v_pk_fma_f32 v[246:247], v[78:79], v[78:79], v[246:247]
	v_pk_fma_f32 v[246:247], v[80:81], v[80:81], v[246:247]
	s_nop 0
	v_add_f32_e32 v246, v246, v247
	s_nop 1
	v_add_f32_dpp v246, v246, v246 quad_perm:[1,0,3,2] row_mask:0xf bank_mask:0xf
	s_nop 1
	v_add_f32_dpp v246, v246, v246 quad_perm:[2,3,0,1] row_mask:0xf bank_mask:0xf
	s_nop 1
	v_add_f32_dpp v246, v246, v246 row_half_mirror row_mask:0xf bank_mask:0xf
	s_nop 1
	v_add_f32_dpp v246, v246, v246 row_mirror row_mask:0xf bank_mask:0xf
	s_nop 1
	v_add_f32_dpp v246, v246, v246 row_bcast:15 row_mask:0xa bank_mask:0xf
	s_nop 1
	v_add_f32_dpp v246, v246, v246 row_bcast:31 row_mask:0xc bank_mask:0xf
	s_nop 1
	v_readlane_b32 s0, v246, 63
	s_add_i32 s21, s20, 2560
	s_lshl_b32 s21, s21, 11
	s_add_u32 s10, s16, s21
	s_addc_u32 s11, s17, 0
	v_mov_b32_e32 v248, s0
	v_fmamk_f32 v248, v248, 0x3a800000, v143
	v_rsq_f32_e32 v248, v248
	s_nop 0
	v_pk_mul_f32 v[66:67], v[66:67], v[248:249] op_sel_hi:[1,0]
	v_pk_add_f32 v[98:99], v[98:99], 1.0 op_sel_hi:[1,0]
	v_pk_mul_f32 v[66:67], v[2:3], v[66:67]
	v_pk_fma_f32 v[66:67], v[98:99], v[66:67], v[82:83]
	v_pk_mul_f32 v[68:69], v[68:69], v[248:249] op_sel_hi:[1,0]
	v_pk_add_f32 v[100:101], v[100:101], 1.0 op_sel_hi:[1,0]
	v_pk_mul_f32 v[68:69], v[4:5], v[68:69]
	v_pk_fma_f32 v[68:69], v[100:101], v[68:69], v[84:85]
	v_cvt_pk_bf16_f32 v82, v66, v67
	v_cvt_pk_bf16_f32 v83, v68, v69
	global_store_dwordx2 v245, v[82:83], s[10:11]
	v_pk_mul_f32 v[70:71], v[70:71], v[248:249] op_sel_hi:[1,0]
	v_pk_add_f32 v[102:103], v[102:103], 1.0 op_sel_hi:[1,0]
	v_pk_mul_f32 v[70:71], v[6:7], v[70:71]
	v_pk_fma_f32 v[70:71], v[102:103], v[70:71], v[86:87]
	v_pk_mul_f32 v[72:73], v[72:73], v[248:249] op_sel_hi:[1,0]
	v_pk_add_f32 v[104:105], v[104:105], 1.0 op_sel_hi:[1,0]
	v_pk_mul_f32 v[72:73], v[8:9], v[72:73]
	v_pk_fma_f32 v[72:73], v[104:105], v[72:73], v[88:89]
	v_cvt_pk_bf16_f32 v86, v70, v71
	v_cvt_pk_bf16_f32 v87, v72, v73
	global_store_dwordx2 v245, v[86:87], s[10:11] offset:512
	v_pk_mul_f32 v[74:75], v[74:75], v[248:249] op_sel_hi:[1,0]
	v_pk_add_f32 v[106:107], v[106:107], 1.0 op_sel_hi:[1,0]
	v_pk_mul_f32 v[74:75], v[10:11], v[74:75]
	v_pk_fma_f32 v[74:75], v[106:107], v[74:75], v[90:91]
	v_pk_mul_f32 v[76:77], v[76:77], v[248:249] op_sel_hi:[1,0]
	v_pk_add_f32 v[108:109], v[108:109], 1.0 op_sel_hi:[1,0]
	v_pk_mul_f32 v[76:77], v[12:13], v[76:77]
	v_pk_fma_f32 v[76:77], v[108:109], v[76:77], v[92:93]
	v_cvt_pk_bf16_f32 v90, v74, v75
	v_cvt_pk_bf16_f32 v91, v76, v77
	global_store_dwordx2 v245, v[90:91], s[10:11] offset:1024
	v_pk_mul_f32 v[78:79], v[78:79], v[248:249] op_sel_hi:[1,0]
	v_pk_add_f32 v[118:119], v[118:119], 1.0 op_sel_hi:[1,0]
	v_pk_mul_f32 v[78:79], v[14:15], v[78:79]
	v_pk_fma_f32 v[78:79], v[118:119], v[78:79], v[94:95]
	v_pk_mul_f32 v[80:81], v[80:81], v[248:249] op_sel_hi:[1,0]
	v_pk_add_f32 v[120:121], v[120:121], 1.0 op_sel_hi:[1,0]
	v_pk_mul_f32 v[80:81], v[16:17], v[80:81]
	v_pk_fma_f32 v[80:81], v[120:121], v[80:81], v[96:97]
	v_cvt_pk_bf16_f32 v94, v78, v79
	v_cvt_pk_bf16_f32 v95, v80, v81
	global_store_dwordx2 v245, v[94:95], s[10:11] offset:1536
	s_add_i32 s21, s20, 9472
	s_mov_b32 s7, 4
	s_add_i32 s8, s20, 256
	s_lshl_b32 s9, s7, 11
	s_add_i32 s9, s9, s8
	s_add_i32 s9, s9, 0xffffff00
	s_lshl_b32 s10, s7, 8
	s_add_i32 s10, s10, s8
	s_cmpk_gt_i32 s8, 0xff
	s_cselect_b32 s9, s9, s10
	s_cselect_b32 s26, s12, s14
	s_cselect_b32 s27, s13, s15
	s_cselect_b32 s10, s7, 8
	s_lshl_b32 s9, s9, 12
	s_add_u32 s26, s26, s9
	s_addc_u32 s27, s27, 0
	s_add_i32 s10, s10, s82
	s_mul_i32 s10, s10, s24
	s_add_u32 s28, s58, s10
	s_addc_u32 s29, s59, 0
	s_add_u32 s28, s28, 0x3000
	s_addc_u32 s29, s29, 0
	s_add_u32 s0, s28, 0x1000
	s_addc_u32 s1, s29, 0
	global_load_dwordx4 v[66:69], v244, s[26:27]
	global_load_dwordx4 v[70:73], v244, s[26:27] offset:1024
	global_load_dwordx4 v[74:77], v244, s[26:27] offset:2048
	global_load_dwordx4 v[78:81], v244, s[26:27] offset:3072
	global_load_dwordx4 v[82:85], v244, s[28:29]
	global_load_dwordx4 v[86:89], v244, s[28:29] offset:1024
	global_load_dwordx4 v[90:93], v244, s[28:29] offset:2048
	global_load_dwordx4 v[94:97], v244, s[28:29] offset:3072
	global_load_dwordx4 v[98:101], v244, s[0:1]
	global_load_dwordx4 v[102:105], v244, s[0:1] offset:1024
	global_load_dwordx4 v[106:109], v244, s[0:1] offset:2048
	global_load_dwordx4 v[118:121], v244, s[0:1] offset:3072
	s_waitcnt vmcnt(32)
; DI unsigned pk_bf16(float lo, float hi) { f32x2 v = {lo, hi}; bf16v2 b = __builtin_convertvector(v, bf16v2); return __builtin_bit_cast(unsigned, b); }
; DI float red64(float x) { for (int o = 32; o > 0; o >>= 1) x += __shfl_xor(x, o); return x; }
; DI void modnorm_rows(const Params& p, int l, int which  , bool from_inputs, bool skip_ctx, int w0, int wstride, int lane) {
;     ...
;   for (; i < nrows; i += wstride) {
;     const int row = rowof(i); const int b = row / TB, s = row % TB;
;     f32x4 v[4];
; #pragma unroll
;     for (int q = 0; q < 4; ++q) v[q] = vn[q];
;     if (i + wstride < nrows) {
;       const int rn = rowof(i + wstride); const float* src = xsrc_row(p, from_inputs, rn / TB, rn % TB);
; #pragma unroll
;       for (int q = 0; q < 4; ++q) vn[q] = *(const f32x4*)(src + q * 256 + lane * 4);
;     }
;     const float* mod = p.MOD + (size_t)(l * 9 + (s < NCTX ? 8 : b)) * 6144 + (which ? 3 * 1024 : 0);
;     f32x4 sh[4], sc[4];
; #pragma unroll
;     for (int q = 0; q < 4; ++q) { sh[q] = *(const f32x4*)(mod + q * 256 + lane * 4); sc[q] = *(const f32x4*)(mod + 1024 + q * 256 + lane * 4); }
;     float ss = 0.f;
; #pragma unroll
;     for (int q = 0; q < 4; ++q) ss += v[q][0] * v[q][0] + v[q][1] * v[q][1] + v[q][2] * v[q][2] + v[q][3] * v[q][3];
;     ss = red64(ss);
;     const float rs = rsqrtf(ss * (1.f / 1024.f) + EPSF);
;     bf16_t* dst = p.HY + (size_t)row * DM;
; #pragma unroll
;     for (int q = 0; q < 4; ++q) {
;       float o[4];
; #pragma unroll
;       for (int j = 0; j < 4; ++j) o[j] = (v[q][j] * rs * gg[q][j]) * (1.f + sc[q][j]) + sh[q][j];
;       u32x2 w = {pk_bf16(o[0], o[1]), pk_bf16(o[2], o[3])};
;       *(u32x2*)(dst + q * 256 + lane * 4) = w;
;     }
;   }
	v_pk_mul_f32 v[246:247], v[122:123], v[122:123]
	v_pk_fma_f32 v[246:247], v[124:125], v[124:125], v[246:247]
	v_pk_fma_f32 v[246:247], v[126:127], v[126:127], v[246:247]
	v_pk_fma_f32 v[246:247], v[128:129], v[128:129], v[246:247]
	v_pk_fma_f32 v[246:247], v[130:131], v[130:131], v[246:247]
	v_pk_fma_f32 v[246:247], v[132:133], v[132:133], v[246:247]
	v_pk_fma_f32 v[246:247], v[134:135], v[134:135], v[246:247]
	v_pk_fma_f32 v[246:247], v[136:137], v[136:137], v[246:247]
	s_nop 0
	v_add_f32_e32 v246, v246, v247
	s_nop 1
	v_add_f32_dpp v246, v246, v246 quad_perm:[1,0,3,2] row_mask:0xf bank_mask:0xf
	s_nop 1
	v_add_f32_dpp v246, v246, v246 quad_perm:[2,3,0,1] row_mask:0xf bank_mask:0xf
	s_nop 1
	v_add_f32_dpp v246, v246, v246 row_half_mirror row_mask:0xf bank_mask:0xf
	s_nop 1
	v_add_f32_dpp v246, v246, v246 row_mirror row_mask:0xf bank_mask:0xf
	s_nop 1
	v_add_f32_dpp v246, v246, v246 row_bcast:15 row_mask:0xa bank_mask:0xf
	s_nop 1
	v_add_f32_dpp v246, v246, v246 row_bcast:31 row_mask:0xc bank_mask:0xf
	s_nop 1
	v_readlane_b32 s0, v246, 63
	s_add_i32 s21, s20, 4864
	s_lshl_b32 s21, s21, 11
	s_add_u32 s10, s16, s21
	s_addc_u32 s11, s17, 0
	v_mov_b32_e32 v248, s0
	v_fmamk_f32 v248, v248, 0x3a800000, v143
	v_rsq_f32_e32 v248, v248
	s_nop 0
	v_pk_mul_f32 v[122:123], v[122:123], v[248:249] op_sel_hi:[1,0]
	v_pk_add_f32 v[176:177], v[176:177], 1.0 op_sel_hi:[1,0]
	v_pk_mul_f32 v[122:123], v[2:3], v[122:123]
	v_pk_fma_f32 v[122:123], v[176:177], v[122:123], v[160:161]
	v_pk_mul_f32 v[124:125], v[124:125], v[248:249] op_sel_hi:[1,0]
	v_pk_add_f32 v[178:179], v[178:179], 1.0 op_sel_hi:[1,0]
	v_pk_mul_f32 v[124:125], v[4:5], v[124:125]
	v_pk_fma_f32 v[124:125], v[178:179], v[124:125], v[162:163]
	v_cvt_pk_bf16_f32 v160, v122, v123
	v_cvt_pk_bf16_f32 v161, v124, v125
	global_store_dwordx2 v245, v[160:161], s[10:11]
	v_pk_mul_f32 v[126:127], v[126:127], v[248:249] op_sel_hi:[1,0]
	v_pk_add_f32 v[180:181], v[180:181], 1.0 op_sel_hi:[1,0]
	v_pk_mul_f32 v[126:127], v[6:7], v[126:127]
	v_pk_fma_f32 v[126:127], v[180:181], v[126:127], v[164:165]
	v_pk_mul_f32 v[128:129], v[128:129], v[248:249] op_sel_hi:[1,0]
	v_pk_add_f32 v[182:183], v[182:183], 1.0 op_sel_hi:[1,0]
	v_pk_mul_f32 v[128:129], v[8:9], v[128:129]
	v_pk_fma_f32 v[128:129], v[182:183], v[128:129], v[166:167]
	v_cvt_pk_bf16_f32 v164, v126, v127
	v_cvt_pk_bf16_f32 v165, v128, v129
	global_store_dwordx2 v245, v[164:165], s[10:11] offset:512
	v_pk_mul_f32 v[130:131], v[130:131], v[248:249] op_sel_hi:[1,0]
	v_pk_add_f32 v[184:185], v[184:185], 1.0 op_sel_hi:[1,0]
	v_pk_mul_f32 v[130:131], v[10:11], v[130:131]
	v_pk_fma_f32 v[130:131], v[184:185], v[130:131], v[168:169]
	v_pk_mul_f32 v[132:133], v[132:133], v[248:249] op_sel_hi:[1,0]
	v_pk_add_f32 v[186:187], v[186:187], 1.0 op_sel_hi:[1,0]
	v_pk_mul_f32 v[132:133], v[12:13], v[132:133]
	v_pk_fma_f32 v[132:133], v[186:187], v[132:133], v[170:171]
	v_cvt_pk_bf16_f32 v168, v130, v131
	v_cvt_pk_bf16_f32 v169, v132, v133
	global_store_dwordx2 v245, v[168:169], s[10:11] offset:1024
	v_pk_mul_f32 v[134:135], v[134:135], v[248:249] op_sel_hi:[1,0]
	v_pk_add_f32 v[188:189], v[188:189], 1.0 op_sel_hi:[1,0]
	v_pk_mul_f32 v[134:135], v[14:15], v[134:135]
	v_pk_fma_f32 v[134:135], v[188:189], v[134:135], v[172:173]
	v_pk_mul_f32 v[136:137], v[136:137], v[248:249] op_sel_hi:[1,0]
	v_pk_add_f32 v[190:191], v[190:191], 1.0 op_sel_hi:[1,0]
	v_pk_mul_f32 v[136:137], v[16:17], v[136:137]
	v_pk_fma_f32 v[136:137], v[190:191], v[136:137], v[174:175]
	v_cvt_pk_bf16_f32 v172, v134, v135
	v_cvt_pk_bf16_f32 v173, v136, v137
	global_store_dwordx2 v245, v[172:173], s[10:11] offset:1536
	s_add_i32 s21, s20, 11776
	s_mov_b32 s7, 5
	s_add_i32 s8, s20, 256
	s_lshl_b32 s9, s7, 11
	s_add_i32 s9, s9, s8
	s_add_i32 s9, s9, 0xffffff00
	s_lshl_b32 s10, s7, 8
	s_add_i32 s10, s10, s8
	s_cmpk_gt_i32 s8, 0xff
	s_cselect_b32 s9, s9, s10
	s_cselect_b32 s26, s12, s14
	s_cselect_b32 s27, s13, s15
	s_cselect_b32 s10, s7, 8
	s_lshl_b32 s9, s9, 12
	s_add_u32 s26, s26, s9
	s_addc_u32 s27, s27, 0
	s_add_i32 s10, s10, s82
	s_mul_i32 s10, s10, s24
	s_add_u32 s28, s58, s10
	s_addc_u32 s29, s59, 0
	s_add_u32 s28, s28, 0x3000
	s_addc_u32 s29, s29, 0
	s_add_u32 s0, s28, 0x1000
	s_addc_u32 s1, s29, 0
	global_load_dwordx4 v[122:125], v244, s[26:27]
	global_load_dwordx4 v[126:129], v244, s[26:27] offset:1024
	global_load_dwordx4 v[130:133], v244, s[26:27] offset:2048
	global_load_dwordx4 v[134:137], v244, s[26:27] offset:3072
	global_load_dwordx4 v[160:163], v244, s[28:29]
	global_load_dwordx4 v[164:167], v244, s[28:29] offset:1024
	global_load_dwordx4 v[168:171], v244, s[28:29] offset:2048
	global_load_dwordx4 v[172:175], v244, s[28:29] offset:3072
	global_load_dwordx4 v[176:179], v244, s[0:1]
	global_load_dwordx4 v[180:183], v244, s[0:1] offset:1024
	global_load_dwordx4 v[184:187], v244, s[0:1] offset:2048
	global_load_dwordx4 v[188:191], v244, s[0:1] offset:3072
	s_waitcnt vmcnt(32)
; DI unsigned pk_bf16(float lo, float hi) { f32x2 v = {lo, hi}; bf16v2 b = __builtin_convertvector(v, bf16v2); return __builtin_bit_cast(unsigned, b); }
; DI float red64(float x) { for (int o = 32; o > 0; o >>= 1) x += __shfl_xor(x, o); return x; }
; DI void modnorm_rows(const Params& p, int l, int which  , bool from_inputs, bool skip_ctx, int w0, int wstride, int lane) {
;     ...
;   for (; i < nrows; i += wstride) {
;     const int row = rowof(i); const int b = row / TB, s = row % TB;
;     f32x4 v[4];
; #pragma unroll
;     for (int q = 0; q < 4; ++q) v[q] = vn[q];
;     if (i + wstride < nrows) {
;       const int rn = rowof(i + wstride); const float* src = xsrc_row(p, from_inputs, rn / TB, rn % TB);
; #pragma unroll
;       for (int q = 0; q < 4; ++q) vn[q] = *(const f32x4*)(src + q * 256 + lane * 4);
;     }
;     const float* mod = p.MOD + (size_t)(l * 9 + (s < NCTX ? 8 : b)) * 6144 + (which ? 3 * 1024 : 0);
;     f32x4 sh[4], sc[4];
; #pragma unroll
;     for (int q = 0; q < 4; ++q) { sh[q] = *(const f32x4*)(mod + q * 256 + lane * 4); sc[q] = *(const f32x4*)(mod + 1024 + q * 256 + lane * 4); }
;     float ss = 0.f;
; #pragma unroll
;     for (int q = 0; q < 4; ++q) ss += v[q][0] * v[q][0] + v[q][1] * v[q][1] + v[q][2] * v[q][2] + v[q][3] * v[q][3];
;     ss = red64(ss);
;     const float rs = rsqrtf(ss * (1.f / 1024.f) + EPSF);
;     bf16_t* dst = p.HY + (size_t)row * DM;
; #pragma unroll
;     for (int q = 0; q < 4; ++q) {
;       float o[4];
; #pragma unroll
;       for (int j = 0; j < 4; ++j) o[j] = (v[q][j] * rs * gg[q][j]) * (1.f + sc[q][j]) + sh[q][j];
;       u32x2 w = {pk_bf16(o[0], o[1]), pk_bf16(o[2], o[3])};
;       *(u32x2*)(dst + q * 256 + lane * 4) = w;
;     }
;   }
	v_pk_mul_f32 v[246:247], v[18:19], v[18:19]
	v_pk_fma_f32 v[246:247], v[20:21], v[20:21], v[246:247]
	v_pk_fma_f32 v[246:247], v[22:23], v[22:23], v[246:247]
	v_pk_fma_f32 v[246:247], v[24:25], v[24:25], v[246:247]
	v_pk_fma_f32 v[246:247], v[26:27], v[26:27], v[246:247]
	v_pk_fma_f32 v[246:247], v[28:29], v[28:29], v[246:247]
	v_pk_fma_f32 v[246:247], v[30:31], v[30:31], v[246:247]
	v_pk_fma_f32 v[246:247], v[32:33], v[32:33], v[246:247]
	s_nop 0
	v_add_f32_e32 v246, v246, v247
	s_nop 1
	v_add_f32_dpp v246, v246, v246 quad_perm:[1,0,3,2] row_mask:0xf bank_mask:0xf
	s_nop 1
	v_add_f32_dpp v246, v246, v246 quad_perm:[2,3,0,1] row_mask:0xf bank_mask:0xf
	s_nop 1
	v_add_f32_dpp v246, v246, v246 row_half_mirror row_mask:0xf bank_mask:0xf
	s_nop 1
	v_add_f32_dpp v246, v246, v246 row_mirror row_mask:0xf bank_mask:0xf
	s_nop 1
	v_add_f32_dpp v246, v246, v246 row_bcast:15 row_mask:0xa bank_mask:0xf
	s_nop 1
	v_add_f32_dpp v246, v246, v246 row_bcast:31 row_mask:0xc bank_mask:0xf
	s_nop 1
	v_readlane_b32 s0, v246, 63
	s_add_i32 s21, s20, 7168
	s_lshl_b32 s21, s21, 11
	s_add_u32 s10, s16, s21
	s_addc_u32 s11, s17, 0
	v_mov_b32_e32 v248, s0
	v_fmamk_f32 v248, v248, 0x3a800000, v143
	v_rsq_f32_e32 v248, v248
	s_nop 0
	v_pk_mul_f32 v[18:19], v[18:19], v[248:249] op_sel_hi:[1,0]
	v_pk_add_f32 v[50:51], v[50:51], 1.0 op_sel_hi:[1,0]
	v_pk_mul_f32 v[18:19], v[2:3], v[18:19]
	v_pk_fma_f32 v[18:19], v[50:51], v[18:19], v[34:35]
	v_pk_mul_f32 v[20:21], v[20:21], v[248:249] op_sel_hi:[1,0]
	v_pk_add_f32 v[52:53], v[52:53], 1.0 op_sel_hi:[1,0]
	v_pk_mul_f32 v[20:21], v[4:5], v[20:21]
	v_pk_fma_f32 v[20:21], v[52:53], v[20:21], v[36:37]
	v_cvt_pk_bf16_f32 v34, v18, v19
	v_cvt_pk_bf16_f32 v35, v20, v21
	global_store_dwordx2 v245, v[34:35], s[10:11]
	v_pk_mul_f32 v[22:23], v[22:23], v[248:249] op_sel_hi:[1,0]
	v_pk_add_f32 v[54:55], v[54:55], 1.0 op_sel_hi:[1,0]
	v_pk_mul_f32 v[22:23], v[6:7], v[22:23]
	v_pk_fma_f32 v[22:23], v[54:55], v[22:23], v[38:39]
	v_pk_mul_f32 v[24:25], v[24:25], v[248:249] op_sel_hi:[1,0]
	v_pk_add_f32 v[56:57], v[56:57], 1.0 op_sel_hi:[1,0]
	v_pk_mul_f32 v[24:25], v[8:9], v[24:25]
	v_pk_fma_f32 v[24:25], v[56:57], v[24:25], v[40:41]
	v_cvt_pk_bf16_f32 v38, v22, v23
	v_cvt_pk_bf16_f32 v39, v24, v25
	global_store_dwordx2 v245, v[38:39], s[10:11] offset:512
	v_pk_mul_f32 v[26:27], v[26:27], v[248:249] op_sel_hi:[1,0]
	v_pk_add_f32 v[58:59], v[58:59], 1.0 op_sel_hi:[1,0]
	v_pk_mul_f32 v[26:27], v[10:11], v[26:27]
	v_pk_fma_f32 v[26:27], v[58:59], v[26:27], v[42:43]
	v_pk_mul_f32 v[28:29], v[28:29], v[248:249] op_sel_hi:[1,0]
	v_pk_add_f32 v[60:61], v[60:61], 1.0 op_sel_hi:[1,0]
	v_pk_mul_f32 v[28:29], v[12:13], v[28:29]
	v_pk_fma_f32 v[28:29], v[60:61], v[28:29], v[44:45]
	v_cvt_pk_bf16_f32 v42, v26, v27
	v_cvt_pk_bf16_f32 v43, v28, v29
	global_store_dwordx2 v245, v[42:43], s[10:11] offset:1024
	v_pk_mul_f32 v[30:31], v[30:31], v[248:249] op_sel_hi:[1,0]
	v_pk_add_f32 v[62:63], v[62:63], 1.0 op_sel_hi:[1,0]
	v_pk_mul_f32 v[30:31], v[14:15], v[30:31]
	v_pk_fma_f32 v[30:31], v[62:63], v[30:31], v[46:47]
	v_pk_mul_f32 v[32:33], v[32:33], v[248:249] op_sel_hi:[1,0]
	v_pk_add_f32 v[64:65], v[64:65], 1.0 op_sel_hi:[1,0]
	v_pk_mul_f32 v[32:33], v[16:17], v[32:33]
	v_pk_fma_f32 v[32:33], v[64:65], v[32:33], v[48:49]
	v_cvt_pk_bf16_f32 v46, v30, v31
	v_cvt_pk_bf16_f32 v47, v32, v33
	global_store_dwordx2 v245, v[46:47], s[10:11] offset:1536
	s_add_i32 s21, s20, 14080
	s_mov_b32 s7, 6
	s_add_i32 s8, s20, 256
	s_lshl_b32 s9, s7, 11
	s_add_i32 s9, s9, s8
	s_add_i32 s9, s9, 0xffffff00
	s_lshl_b32 s10, s7, 8
	s_add_i32 s10, s10, s8
	s_cmpk_gt_i32 s8, 0xff
	s_cselect_b32 s9, s9, s10
	s_cselect_b32 s26, s12, s14
	s_cselect_b32 s27, s13, s15
	s_cselect_b32 s10, s7, 8
	s_lshl_b32 s9, s9, 12
	s_add_u32 s26, s26, s9
	s_addc_u32 s27, s27, 0
	s_add_i32 s10, s10, s82
	s_mul_i32 s10, s10, s24
	s_add_u32 s28, s58, s10
	s_addc_u32 s29, s59, 0
	s_add_u32 s28, s28, 0x3000
	s_addc_u32 s29, s29, 0
	s_add_u32 s0, s28, 0x1000
	s_addc_u32 s1, s29, 0
	global_load_dwordx4 v[18:21], v244, s[26:27]
	global_load_dwordx4 v[22:25], v244, s[26:27] offset:1024
	global_load_dwordx4 v[26:29], v244, s[26:27] offset:2048
	global_load_dwordx4 v[30:33], v244, s[26:27] offset:3072
	global_load_dwordx4 v[34:37], v244, s[28:29]
	global_load_dwordx4 v[38:41], v244, s[28:29] offset:1024
	global_load_dwordx4 v[42:45], v244, s[28:29] offset:2048
	global_load_dwordx4 v[46:49], v244, s[28:29] offset:3072
	global_load_dwordx4 v[50:53], v244, s[0:1]
	global_load_dwordx4 v[54:57], v244, s[0:1] offset:1024
	global_load_dwordx4 v[58:61], v244, s[0:1] offset:2048
	global_load_dwordx4 v[62:65], v244, s[0:1] offset:3072
	s_waitcnt vmcnt(32)
; DI unsigned pk_bf16(float lo, float hi) { f32x2 v = {lo, hi}; bf16v2 b = __builtin_convertvector(v, bf16v2); return __builtin_bit_cast(unsigned, b); }
; DI float red64(float x) { for (int o = 32; o > 0; o >>= 1) x += __shfl_xor(x, o); return x; }
; DI void modnorm_rows(const Params& p, int l, int which  , bool from_inputs, bool skip_ctx, int w0, int wstride, int lane) {
;     ...
;   for (; i < nrows; i += wstride) {
;     const int row = rowof(i); const int b = row / TB, s = row % TB;
;     f32x4 v[4];
; #pragma unroll
;     for (int q = 0; q < 4; ++q) v[q] = vn[q];
;     if (i + wstride < nrows) {
;       const int rn = rowof(i + wstride); const float* src = xsrc_row(p, from_inputs, rn / TB, rn % TB);
; #pragma unroll
;       for (int q = 0; q < 4; ++q) vn[q] = *(const f32x4*)(src + q * 256 + lane * 4);
;     }
;     const float* mod = p.MOD + (size_t)(l * 9 + (s < NCTX ? 8 : b)) * 6144 + (which ? 3 * 1024 : 0);
;     f32x4 sh[4], sc[4];
; #pragma unroll
;     for (int q = 0; q < 4; ++q) { sh[q] = *(const f32x4*)(mod + q * 256 + lane * 4); sc[q] = *(const f32x4*)(mod + 1024 + q * 256 + lane * 4); }
;     float ss = 0.f;
; #pragma unroll
;     for (int q = 0; q < 4; ++q) ss += v[q][0] * v[q][0] + v[q][1] * v[q][1] + v[q][2] * v[q][2] + v[q][3] * v[q][3];
;     ss = red64(ss);
;     const float rs = rsqrtf(ss * (1.f / 1024.f) + EPSF);
;     bf16_t* dst = p.HY + (size_t)row * DM;
; #pragma unroll
;     for (int q = 0; q < 4; ++q) {
;       float o[4];
; #pragma unroll
;       for (int j = 0; j < 4; ++j) o[j] = (v[q][j] * rs * gg[q][j]) * (1.f + sc[q][j]) + sh[q][j];
;       u32x2 w = {pk_bf16(o[0], o[1]), pk_bf16(o[2], o[3])};
;       *(u32x2*)(dst + q * 256 + lane * 4) = w;
;     }
;   }
	v_pk_mul_f32 v[246:247], v[66:67], v[66:67]
	v_pk_fma_f32 v[246:247], v[68:69], v[68:69], v[246:247]
	v_pk_fma_f32 v[246:247], v[70:71], v[70:71], v[246:247]
	v_pk_fma_f32 v[246:247], v[72:73], v[72:73], v[246:247]
	v_pk_fma_f32 v[246:247], v[74:75], v[74:75], v[246:247]
	v_pk_fma_f32 v[246:247], v[76:77], v[76:77], v[246:247]
	v_pk_fma_f32 v[246:247], v[78:79], v[78:79], v[246:247]
	v_pk_fma_f32 v[246:247], v[80:81], v[80:81], v[246:247]
	s_nop 0
	v_add_f32_e32 v246, v246, v247
	s_nop 1
	v_add_f32_dpp v246, v246, v246 quad_perm:[1,0,3,2] row_mask:0xf bank_mask:0xf
	s_nop 1
	v_add_f32_dpp v246, v246, v246 quad_perm:[2,3,0,1] row_mask:0xf bank_mask:0xf
	s_nop 1
	v_add_f32_dpp v246, v246, v246 row_half_mirror row_mask:0xf bank_mask:0xf
	s_nop 1
	v_add_f32_dpp v246, v246, v246 row_mirror row_mask:0xf bank_mask:0xf
	s_nop 1
	v_add_f32_dpp v246, v246, v246 row_bcast:15 row_mask:0xa bank_mask:0xf
	s_nop 1
	v_add_f32_dpp v246, v246, v246 row_bcast:31 row_mask:0xc bank_mask:0xf
	s_nop 1
	v_readlane_b32 s0, v246, 63
	s_add_i32 s21, s20, 9472
	s_lshl_b32 s21, s21, 11
	s_add_u32 s10, s16, s21
	s_addc_u32 s11, s17, 0
	v_mov_b32_e32 v248, s0
	v_fmamk_f32 v248, v248, 0x3a800000, v143
	v_rsq_f32_e32 v248, v248
	s_nop 0
	v_pk_mul_f32 v[66:67], v[66:67], v[248:249] op_sel_hi:[1,0]
	v_pk_add_f32 v[98:99], v[98:99], 1.0 op_sel_hi:[1,0]
	v_pk_mul_f32 v[66:67], v[2:3], v[66:67]
	v_pk_fma_f32 v[66:67], v[98:99], v[66:67], v[82:83]
	v_pk_mul_f32 v[68:69], v[68:69], v[248:249] op_sel_hi:[1,0]
	v_pk_add_f32 v[100:101], v[100:101], 1.0 op_sel_hi:[1,0]
	v_pk_mul_f32 v[68:69], v[4:5], v[68:69]
	v_pk_fma_f32 v[68:69], v[100:101], v[68:69], v[84:85]
	v_cvt_pk_bf16_f32 v82, v66, v67
	v_cvt_pk_bf16_f32 v83, v68, v69
	global_store_dwordx2 v245, v[82:83], s[10:11]
	v_pk_mul_f32 v[70:71], v[70:71], v[248:249] op_sel_hi:[1,0]
	v_pk_add_f32 v[102:103], v[102:103], 1.0 op_sel_hi:[1,0]
	v_pk_mul_f32 v[70:71], v[6:7], v[70:71]
	v_pk_fma_f32 v[70:71], v[102:103], v[70:71], v[86:87]
	v_pk_mul_f32 v[72:73], v[72:73], v[248:249] op_sel_hi:[1,0]
	v_pk_add_f32 v[104:105], v[104:105], 1.0 op_sel_hi:[1,0]
	v_pk_mul_f32 v[72:73], v[8:9], v[72:73]
	v_pk_fma_f32 v[72:73], v[104:105], v[72:73], v[88:89]
	v_cvt_pk_bf16_f32 v86, v70, v71
	v_cvt_pk_bf16_f32 v87, v72, v73
	global_store_dwordx2 v245, v[86:87], s[10:11] offset:512
	v_pk_mul_f32 v[74:75], v[74:75], v[248:249] op_sel_hi:[1,0]
	v_pk_add_f32 v[106:107], v[106:107], 1.0 op_sel_hi:[1,0]
	v_pk_mul_f32 v[74:75], v[10:11], v[74:75]
	v_pk_fma_f32 v[74:75], v[106:107], v[74:75], v[90:91]
	v_pk_mul_f32 v[76:77], v[76:77], v[248:249] op_sel_hi:[1,0]
	v_pk_add_f32 v[108:109], v[108:109], 1.0 op_sel_hi:[1,0]
	v_pk_mul_f32 v[76:77], v[12:13], v[76:77]
	v_pk_fma_f32 v[76:77], v[108:109], v[76:77], v[92:93]
	v_cvt_pk_bf16_f32 v90, v74, v75
	v_cvt_pk_bf16_f32 v91, v76, v77
	global_store_dwordx2 v245, v[90:91], s[10:11] offset:1024
	v_pk_mul_f32 v[78:79], v[78:79], v[248:249] op_sel_hi:[1,0]
	v_pk_add_f32 v[118:119], v[118:119], 1.0 op_sel_hi:[1,0]
	v_pk_mul_f32 v[78:79], v[14:15], v[78:79]
	v_pk_fma_f32 v[78:79], v[118:119], v[78:79], v[94:95]
	v_pk_mul_f32 v[80:81], v[80:81], v[248:249] op_sel_hi:[1,0]
	v_pk_add_f32 v[120:121], v[120:121], 1.0 op_sel_hi:[1,0]
	v_pk_mul_f32 v[80:81], v[16:17], v[80:81]
	v_pk_fma_f32 v[80:81], v[120:121], v[80:81], v[96:97]
	v_cvt_pk_bf16_f32 v94, v78, v79
	v_cvt_pk_bf16_f32 v95, v80, v81
	global_store_dwordx2 v245, v[94:95], s[10:11] offset:1536
	s_add_i32 s21, s20, 16384
	s_mov_b32 s7, 7
	s_add_i32 s8, s20, 256
	s_lshl_b32 s9, s7, 11
	s_add_i32 s9, s9, s8
	s_add_i32 s9, s9, 0xffffff00
	s_lshl_b32 s10, s7, 8
	s_add_i32 s10, s10, s8
	s_cmpk_gt_i32 s8, 0xff
	s_cselect_b32 s9, s9, s10
	s_cselect_b32 s26, s12, s14
	s_cselect_b32 s27, s13, s15
	s_cselect_b32 s10, s7, 8
	s_lshl_b32 s9, s9, 12
	s_add_u32 s26, s26, s9
	s_addc_u32 s27, s27, 0
	s_add_i32 s10, s10, s82
	s_mul_i32 s10, s10, s24
	s_add_u32 s28, s58, s10
	s_addc_u32 s29, s59, 0
	s_add_u32 s28, s28, 0x3000
	s_addc_u32 s29, s29, 0
	s_add_u32 s0, s28, 0x1000
	s_addc_u32 s1, s29, 0
	global_load_dwordx4 v[66:69], v244, s[26:27]
	global_load_dwordx4 v[70:73], v244, s[26:27] offset:1024
	global_load_dwordx4 v[74:77], v244, s[26:27] offset:2048
	global_load_dwordx4 v[78:81], v244, s[26:27] offset:3072
	global_load_dwordx4 v[82:85], v244, s[28:29]
	global_load_dwordx4 v[86:89], v244, s[28:29] offset:1024
	global_load_dwordx4 v[90:93], v244, s[28:29] offset:2048
	global_load_dwordx4 v[94:97], v244, s[28:29] offset:3072
	global_load_dwordx4 v[98:101], v244, s[0:1]
	global_load_dwordx4 v[102:105], v244, s[0:1] offset:1024
	global_load_dwordx4 v[106:109], v244, s[0:1] offset:2048
	global_load_dwordx4 v[118:121], v244, s[0:1] offset:3072
	s_waitcnt vmcnt(32)
; DI unsigned pk_bf16(float lo, float hi) { f32x2 v = {lo, hi}; bf16v2 b = __builtin_convertvector(v, bf16v2); return __builtin_bit_cast(unsigned, b); }
; DI float red64(float x) { for (int o = 32; o > 0; o >>= 1) x += __shfl_xor(x, o); return x; }
; DI void modnorm_rows(const Params& p, int l, int which  , bool from_inputs, bool skip_ctx, int w0, int wstride, int lane) {
;     ...
;   for (; i < nrows; i += wstride) {
;     const int row = rowof(i); const int b = row / TB, s = row % TB;
;     f32x4 v[4];
; #pragma unroll
;     for (int q = 0; q < 4; ++q) v[q] = vn[q];
;     if (i + wstride < nrows) {
;       const int rn = rowof(i + wstride); const float* src = xsrc_row(p, from_inputs, rn / TB, rn % TB);
; #pragma unroll
;       for (int q = 0; q < 4; ++q) vn[q] = *(const f32x4*)(src + q * 256 + lane * 4);
;     }
;     const float* mod = p.MOD + (size_t)(l * 9 + (s < NCTX ? 8 : b)) * 6144 + (which ? 3 * 1024 : 0);
;     f32x4 sh[4], sc[4];
; #pragma unroll
;     for (int q = 0; q < 4; ++q) { sh[q] = *(const f32x4*)(mod + q * 256 + lane * 4); sc[q] = *(const f32x4*)(mod + 1024 + q * 256 + lane * 4); }
;     float ss = 0.f;
; #pragma unroll
;     for (int q = 0; q < 4; ++q) ss += v[q][0] * v[q][0] + v[q][1] * v[q][1] + v[q][2] * v[q][2] + v[q][3] * v[q][3];
;     ss = red64(ss);
;     const float rs = rsqrtf(ss * (1.f / 1024.f) + EPSF);
;     bf16_t* dst = p.HY + (size_t)row * DM;
; #pragma unroll
;     for (int q = 0; q < 4; ++q) {
;       float o[4];
; #pragma unroll
;       for (int j = 0; j < 4; ++j) o[j] = (v[q][j] * rs * gg[q][j]) * (1.f + sc[q][j]) + sh[q][j];
;       u32x2 w = {pk_bf16(o[0], o[1]), pk_bf16(o[2], o[3])};
;       *(u32x2*)(dst + q * 256 + lane * 4) = w;
;     }
;   }
	v_pk_mul_f32 v[246:247], v[122:123], v[122:123]
	v_pk_fma_f32 v[246:247], v[124:125], v[124:125], v[246:247]
	v_pk_fma_f32 v[246:247], v[126:127], v[126:127], v[246:247]
	v_pk_fma_f32 v[246:247], v[128:129], v[128:129], v[246:247]
	v_pk_fma_f32 v[246:247], v[130:131], v[130:131], v[246:247]
	v_pk_fma_f32 v[246:247], v[132:133], v[132:133], v[246:247]
	v_pk_fma_f32 v[246:247], v[134:135], v[134:135], v[246:247]
	v_pk_fma_f32 v[246:247], v[136:137], v[136:137], v[246:247]
	s_nop 0
	v_add_f32_e32 v246, v246, v247
	s_nop 1
	v_add_f32_dpp v246, v246, v246 quad_perm:[1,0,3,2] row_mask:0xf bank_mask:0xf
	s_nop 1
	v_add_f32_dpp v246, v246, v246 quad_perm:[2,3,0,1] row_mask:0xf bank_mask:0xf
	s_nop 1
	v_add_f32_dpp v246, v246, v246 row_half_mirror row_mask:0xf bank_mask:0xf
	s_nop 1
	v_add_f32_dpp v246, v246, v246 row_mirror row_mask:0xf bank_mask:0xf
	s_nop 1
	v_add_f32_dpp v246, v246, v246 row_bcast:15 row_mask:0xa bank_mask:0xf
	s_nop 1
	v_add_f32_dpp v246, v246, v246 row_bcast:31 row_mask:0xc bank_mask:0xf
	s_nop 1
	v_readlane_b32 s0, v246, 63
	s_add_i32 s21, s20, 11776
	s_lshl_b32 s21, s21, 11
	s_add_u32 s10, s16, s21
	s_addc_u32 s11, s17, 0
	v_mov_b32_e32 v248, s0
	v_fmamk_f32 v248, v248, 0x3a800000, v143
	v_rsq_f32_e32 v248, v248
	s_nop 0
	v_pk_mul_f32 v[122:123], v[122:123], v[248:249] op_sel_hi:[1,0]
	v_pk_add_f32 v[176:177], v[176:177], 1.0 op_sel_hi:[1,0]
	v_pk_mul_f32 v[122:123], v[2:3], v[122:123]
	v_pk_fma_f32 v[122:123], v[176:177], v[122:123], v[160:161]
	v_pk_mul_f32 v[124:125], v[124:125], v[248:249] op_sel_hi:[1,0]
	v_pk_add_f32 v[178:179], v[178:179], 1.0 op_sel_hi:[1,0]
	v_pk_mul_f32 v[124:125], v[4:5], v[124:125]
	v_pk_fma_f32 v[124:125], v[178:179], v[124:125], v[162:163]
	v_cvt_pk_bf16_f32 v160, v122, v123
	v_cvt_pk_bf16_f32 v161, v124, v125
	global_store_dwordx2 v245, v[160:161], s[10:11]
	v_pk_mul_f32 v[126:127], v[126:127], v[248:249] op_sel_hi:[1,0]
	v_pk_add_f32 v[180:181], v[180:181], 1.0 op_sel_hi:[1,0]
	v_pk_mul_f32 v[126:127], v[6:7], v[126:127]
	v_pk_fma_f32 v[126:127], v[180:181], v[126:127], v[164:165]
	v_pk_mul_f32 v[128:129], v[128:129], v[248:249] op_sel_hi:[1,0]
	v_pk_add_f32 v[182:183], v[182:183], 1.0 op_sel_hi:[1,0]
	v_pk_mul_f32 v[128:129], v[8:9], v[128:129]
	v_pk_fma_f32 v[128:129], v[182:183], v[128:129], v[166:167]
	v_cvt_pk_bf16_f32 v164, v126, v127
	v_cvt_pk_bf16_f32 v165, v128, v129
	global_store_dwordx2 v245, v[164:165], s[10:11] offset:512
	v_pk_mul_f32 v[130:131], v[130:131], v[248:249] op_sel_hi:[1,0]
	v_pk_add_f32 v[184:185], v[184:185], 1.0 op_sel_hi:[1,0]
	v_pk_mul_f32 v[130:131], v[10:11], v[130:131]
	v_pk_fma_f32 v[130:131], v[184:185], v[130:131], v[168:169]
	v_pk_mul_f32 v[132:133], v[132:133], v[248:249] op_sel_hi:[1,0]
	v_pk_add_f32 v[186:187], v[186:187], 1.0 op_sel_hi:[1,0]
	v_pk_mul_f32 v[132:133], v[12:13], v[132:133]
	v_pk_fma_f32 v[132:133], v[186:187], v[132:133], v[170:171]
	v_cvt_pk_bf16_f32 v168, v130, v131
	v_cvt_pk_bf16_f32 v169, v132, v133
	global_store_dwordx2 v245, v[168:169], s[10:11] offset:1024
	v_pk_mul_f32 v[134:135], v[134:135], v[248:249] op_sel_hi:[1,0]
	v_pk_add_f32 v[188:189], v[188:189], 1.0 op_sel_hi:[1,0]
	v_pk_mul_f32 v[134:135], v[14:15], v[134:135]
	v_pk_fma_f32 v[134:135], v[188:189], v[134:135], v[172:173]
	v_pk_mul_f32 v[136:137], v[136:137], v[248:249] op_sel_hi:[1,0]
	v_pk_add_f32 v[190:191], v[190:191], 1.0 op_sel_hi:[1,0]
	v_pk_mul_f32 v[136:137], v[16:17], v[136:137]
	v_pk_fma_f32 v[136:137], v[190:191], v[136:137], v[174:175]
	v_cvt_pk_bf16_f32 v172, v134, v135
	v_cvt_pk_bf16_f32 v173, v136, v137
	global_store_dwordx2 v245, v[172:173], s[10:11] offset:1536
	s_waitcnt vmcnt(20)
; DI unsigned pk_bf16(float lo, float hi) { f32x2 v = {lo, hi}; bf16v2 b = __builtin_convertvector(v, bf16v2); return __builtin_bit_cast(unsigned, b); }
; DI float red64(float x) { for (int o = 32; o > 0; o >>= 1) x += __shfl_xor(x, o); return x; }
; DI void modnorm_rows(const Params& p, int l, int which  , bool from_inputs, bool skip_ctx, int w0, int wstride, int lane) {
;     ...
;   for (; i < nrows; i += wstride) {
;     const int row = rowof(i); const int b = row / TB, s = row % TB;
;     f32x4 v[4];
; #pragma unroll
;     for (int q = 0; q < 4; ++q) v[q] = vn[q];
;     if (i + wstride < nrows) {
;       const int rn = rowof(i + wstride); const float* src = xsrc_row(p, from_inputs, rn / TB, rn % TB);
; #pragma unroll
;       for (int q = 0; q < 4; ++q) vn[q] = *(const f32x4*)(src + q * 256 + lane * 4);
;     }
;     const float* mod = p.MOD + (size_t)(l * 9 + (s < NCTX ? 8 : b)) * 6144 + (which ? 3 * 1024 : 0);
;     f32x4 sh[4], sc[4];
; #pragma unroll
;     for (int q = 0; q < 4; ++q) { sh[q] = *(const f32x4*)(mod + q * 256 + lane * 4); sc[q] = *(const f32x4*)(mod + 1024 + q * 256 + lane * 4); }
;     float ss = 0.f;
; #pragma unroll
;     for (int q = 0; q < 4; ++q) ss += v[q][0] * v[q][0] + v[q][1] * v[q][1] + v[q][2] * v[q][2] + v[q][3] * v[q][3];
;     ss = red64(ss);
;     const float rs = rsqrtf(ss * (1.f / 1024.f) + EPSF);
;     bf16_t* dst = p.HY + (size_t)row * DM;
; #pragma unroll
;     for (int q = 0; q < 4; ++q) {
;       float o[4];
; #pragma unroll
;       for (int j = 0; j < 4; ++j) o[j] = (v[q][j] * rs * gg[q][j]) * (1.f + sc[q][j]) + sh[q][j];
;       u32x2 w = {pk_bf16(o[0], o[1]), pk_bf16(o[2], o[3])};
;       *(u32x2*)(dst + q * 256 + lane * 4) = w;
;     }
;   }
	v_pk_mul_f32 v[246:247], v[18:19], v[18:19]
	v_pk_fma_f32 v[246:247], v[20:21], v[20:21], v[246:247]
	v_pk_fma_f32 v[246:247], v[22:23], v[22:23], v[246:247]
	v_pk_fma_f32 v[246:247], v[24:25], v[24:25], v[246:247]
	v_pk_fma_f32 v[246:247], v[26:27], v[26:27], v[246:247]
	v_pk_fma_f32 v[246:247], v[28:29], v[28:29], v[246:247]
	v_pk_fma_f32 v[246:247], v[30:31], v[30:31], v[246:247]
	v_pk_fma_f32 v[246:247], v[32:33], v[32:33], v[246:247]
	s_nop 0
	v_add_f32_e32 v246, v246, v247
	s_nop 1
	v_add_f32_dpp v246, v246, v246 quad_perm:[1,0,3,2] row_mask:0xf bank_mask:0xf
	s_nop 1
	v_add_f32_dpp v246, v246, v246 quad_perm:[2,3,0,1] row_mask:0xf bank_mask:0xf
	s_nop 1
	v_add_f32_dpp v246, v246, v246 row_half_mirror row_mask:0xf bank_mask:0xf
	s_nop 1
	v_add_f32_dpp v246, v246, v246 row_mirror row_mask:0xf bank_mask:0xf
	s_nop 1
	v_add_f32_dpp v246, v246, v246 row_bcast:15 row_mask:0xa bank_mask:0xf
	s_nop 1
	v_add_f32_dpp v246, v246, v246 row_bcast:31 row_mask:0xc bank_mask:0xf
	s_nop 1
	v_readlane_b32 s0, v246, 63
	s_add_i32 s21, s20, 14080
	s_lshl_b32 s21, s21, 11
	s_add_u32 s10, s16, s21
	s_addc_u32 s11, s17, 0
	v_mov_b32_e32 v248, s0
	v_fmamk_f32 v248, v248, 0x3a800000, v143
	v_rsq_f32_e32 v248, v248
	s_nop 0
	v_pk_mul_f32 v[18:19], v[18:19], v[248:249] op_sel_hi:[1,0]
	v_pk_add_f32 v[50:51], v[50:51], 1.0 op_sel_hi:[1,0]
	v_pk_mul_f32 v[18:19], v[2:3], v[18:19]
	v_pk_fma_f32 v[18:19], v[50:51], v[18:19], v[34:35]
	v_pk_mul_f32 v[20:21], v[20:21], v[248:249] op_sel_hi:[1,0]
	v_pk_add_f32 v[52:53], v[52:53], 1.0 op_sel_hi:[1,0]
	v_pk_mul_f32 v[20:21], v[4:5], v[20:21]
	v_pk_fma_f32 v[20:21], v[52:53], v[20:21], v[36:37]
	v_cvt_pk_bf16_f32 v34, v18, v19
	v_cvt_pk_bf16_f32 v35, v20, v21
	global_store_dwordx2 v245, v[34:35], s[10:11]
	v_pk_mul_f32 v[22:23], v[22:23], v[248:249] op_sel_hi:[1,0]
	v_pk_add_f32 v[54:55], v[54:55], 1.0 op_sel_hi:[1,0]
	v_pk_mul_f32 v[22:23], v[6:7], v[22:23]
	v_pk_fma_f32 v[22:23], v[54:55], v[22:23], v[38:39]
	v_pk_mul_f32 v[24:25], v[24:25], v[248:249] op_sel_hi:[1,0]
	v_pk_add_f32 v[56:57], v[56:57], 1.0 op_sel_hi:[1,0]
	v_pk_mul_f32 v[24:25], v[8:9], v[24:25]
	v_pk_fma_f32 v[24:25], v[56:57], v[24:25], v[40:41]
	v_cvt_pk_bf16_f32 v38, v22, v23
	v_cvt_pk_bf16_f32 v39, v24, v25
	global_store_dwordx2 v245, v[38:39], s[10:11] offset:512
	v_pk_mul_f32 v[26:27], v[26:27], v[248:249] op_sel_hi:[1,0]
	v_pk_add_f32 v[58:59], v[58:59], 1.0 op_sel_hi:[1,0]
	v_pk_mul_f32 v[26:27], v[10:11], v[26:27]
	v_pk_fma_f32 v[26:27], v[58:59], v[26:27], v[42:43]
	v_pk_mul_f32 v[28:29], v[28:29], v[248:249] op_sel_hi:[1,0]
	v_pk_add_f32 v[60:61], v[60:61], 1.0 op_sel_hi:[1,0]
	v_pk_mul_f32 v[28:29], v[12:13], v[28:29]
	v_pk_fma_f32 v[28:29], v[60:61], v[28:29], v[44:45]
	v_cvt_pk_bf16_f32 v42, v26, v27
	v_cvt_pk_bf16_f32 v43, v28, v29
	global_store_dwordx2 v245, v[42:43], s[10:11] offset:1024
	v_pk_mul_f32 v[30:31], v[30:31], v[248:249] op_sel_hi:[1,0]
	v_pk_add_f32 v[62:63], v[62:63], 1.0 op_sel_hi:[1,0]
	v_pk_mul_f32 v[30:31], v[14:15], v[30:31]
	v_pk_fma_f32 v[30:31], v[62:63], v[30:31], v[46:47]
	v_pk_mul_f32 v[32:33], v[32:33], v[248:249] op_sel_hi:[1,0]
	v_pk_add_f32 v[64:65], v[64:65], 1.0 op_sel_hi:[1,0]
	v_pk_mul_f32 v[32:33], v[16:17], v[32:33]
	v_pk_fma_f32 v[32:33], v[64:65], v[32:33], v[48:49]
	v_cvt_pk_bf16_f32 v46, v30, v31
	v_cvt_pk_bf16_f32 v47, v32, v33
	global_store_dwordx2 v245, v[46:47], s[10:11] offset:1536
	s_waitcnt vmcnt(8)
	v_pk_mul_f32 v[246:247], v[66:67], v[66:67]
	v_pk_fma_f32 v[246:247], v[68:69], v[68:69], v[246:247]
	v_pk_fma_f32 v[246:247], v[70:71], v[70:71], v[246:247]
	v_pk_fma_f32 v[246:247], v[72:73], v[72:73], v[246:247]
	v_pk_fma_f32 v[246:247], v[74:75], v[74:75], v[246:247]
	v_pk_fma_f32 v[246:247], v[76:77], v[76:77], v[246:247]
	v_pk_fma_f32 v[246:247], v[78:79], v[78:79], v[246:247]
	v_pk_fma_f32 v[246:247], v[80:81], v[80:81], v[246:247]
	s_nop 0
	v_add_f32_e32 v246, v246, v247
	s_nop 1
	v_add_f32_dpp v246, v246, v246 quad_perm:[1,0,3,2] row_mask:0xf bank_mask:0xf
	s_nop 1
	v_add_f32_dpp v246, v246, v246 quad_perm:[2,3,0,1] row_mask:0xf bank_mask:0xf
	s_nop 1
	v_add_f32_dpp v246, v246, v246 row_half_mirror row_mask:0xf bank_mask:0xf
	s_nop 1
	v_add_f32_dpp v246, v246, v246 row_mirror row_mask:0xf bank_mask:0xf
	s_nop 1
	v_add_f32_dpp v246, v246, v246 row_bcast:15 row_mask:0xa bank_mask:0xf
	s_nop 1
	v_add_f32_dpp v246, v246, v246 row_bcast:31 row_mask:0xc bank_mask:0xf
	s_nop 1
	v_readlane_b32 s0, v246, 63
	s_add_i32 s21, s20, 16384
	s_lshl_b32 s21, s21, 11
	s_add_u32 s10, s16, s21
	s_addc_u32 s11, s17, 0
	v_mov_b32_e32 v248, s0
	v_fmamk_f32 v248, v248, 0x3a800000, v143
	v_rsq_f32_e32 v248, v248
	s_nop 0
	v_pk_mul_f32 v[66:67], v[66:67], v[248:249] op_sel_hi:[1,0]
	v_pk_add_f32 v[98:99], v[98:99], 1.0 op_sel_hi:[1,0]
	v_pk_mul_f32 v[66:67], v[2:3], v[66:67]
	v_pk_fma_f32 v[66:67], v[98:99], v[66:67], v[82:83]
	v_pk_mul_f32 v[68:69], v[68:69], v[248:249] op_sel_hi:[1,0]
	v_pk_add_f32 v[100:101], v[100:101], 1.0 op_sel_hi:[1,0]
	v_pk_mul_f32 v[68:69], v[4:5], v[68:69]
	v_pk_fma_f32 v[68:69], v[100:101], v[68:69], v[84:85]
	v_cvt_pk_bf16_f32 v82, v66, v67
	v_cvt_pk_bf16_f32 v83, v68, v69
	global_store_dwordx2 v245, v[82:83], s[10:11]
	v_pk_mul_f32 v[70:71], v[70:71], v[248:249] op_sel_hi:[1,0]
	v_pk_add_f32 v[102:103], v[102:103], 1.0 op_sel_hi:[1,0]
	v_pk_mul_f32 v[70:71], v[6:7], v[70:71]
	v_pk_fma_f32 v[70:71], v[102:103], v[70:71], v[86:87]
	v_pk_mul_f32 v[72:73], v[72:73], v[248:249] op_sel_hi:[1,0]
	v_pk_add_f32 v[104:105], v[104:105], 1.0 op_sel_hi:[1,0]
	v_pk_mul_f32 v[72:73], v[8:9], v[72:73]
	v_pk_fma_f32 v[72:73], v[104:105], v[72:73], v[88:89]
	v_cvt_pk_bf16_f32 v86, v70, v71
	v_cvt_pk_bf16_f32 v87, v72, v73
	global_store_dwordx2 v245, v[86:87], s[10:11] offset:512
	v_pk_mul_f32 v[74:75], v[74:75], v[248:249] op_sel_hi:[1,0]
	v_pk_add_f32 v[106:107], v[106:107], 1.0 op_sel_hi:[1,0]
	v_pk_mul_f32 v[74:75], v[10:11], v[74:75]
	v_pk_fma_f32 v[74:75], v[106:107], v[74:75], v[90:91]
	v_pk_mul_f32 v[76:77], v[76:77], v[248:249] op_sel_hi:[1,0]
	v_pk_add_f32 v[108:109], v[108:109], 1.0 op_sel_hi:[1,0]
	v_pk_mul_f32 v[76:77], v[12:13], v[76:77]
	v_pk_fma_f32 v[76:77], v[108:109], v[76:77], v[92:93]
	v_cvt_pk_bf16_f32 v90, v74, v75
	v_cvt_pk_bf16_f32 v91, v76, v77
	global_store_dwordx2 v245, v[90:91], s[10:11] offset:1024
	v_pk_mul_f32 v[78:79], v[78:79], v[248:249] op_sel_hi:[1,0]
	v_pk_add_f32 v[118:119], v[118:119], 1.0 op_sel_hi:[1,0]
	v_pk_mul_f32 v[78:79], v[14:15], v[78:79]
	v_pk_fma_f32 v[78:79], v[118:119], v[78:79], v[94:95]
	v_pk_mul_f32 v[80:81], v[80:81], v[248:249] op_sel_hi:[1,0]
	v_pk_add_f32 v[120:121], v[120:121], 1.0 op_sel_hi:[1,0]
	v_pk_mul_f32 v[80:81], v[16:17], v[80:81]
	v_pk_fma_f32 v[80:81], v[120:121], v[80:81], v[96:97]
	v_cvt_pk_bf16_f32 v94, v78, v79
	v_cvt_pk_bf16_f32 v95, v80, v81
	global_store_dwordx2 v245, v[94:95], s[10:11] offset:1536
	s_branch .Lnorm2_done
.Lnorm2_done:
.LBB0_248:
	s_or_b64 exec, exec, s[2:3]

; DI float red16(float x) { x = red8(x); x += dppf<0x140>(x); return x; }
; DI void unpack4(u32x2 v, float* f) { f[0] = bflo(v[0]); f[1] = bfhi(v[0]); f[2] = bflo(v[1]); f[3] = bfhi(v[1]); }
; DI void scan_task(const Params& p, int l, int b, int h, int dir, int half, char* lds) {
;     ...
;       float pc[4], pp[4], pn[4];
;       unpack4(ld[sec][1], pc); unpack4(ld[sec][0], pp); unpack4(ld[sec][2], pn);
; #pragma unroll
;       for (int j = 0; j < 4; ++j) ts[sec][j] = pc[j] + mu0[sec][j] * (pp[j] * mprev - pc[j]) + mu1[sec][j] * (pn[j] * mnext - pc[j]);
;     ...
;       for (int ii = 0; ii < 16; ++ii) {
;         f32x4 nw = cw, nkk = ckk, nbb = cbb, nkd = ckd, nrr = crr; f32x2 nvv = cvv;
;         if (ii < 15) {
;           ps += inc; pv += inc;
;           nw = *(const f32x4*)(ps + VW * CP); nkk = *(const f32x4*)(ps + VKK * CP); nbb = *(const f32x4*)(ps + VB * CP);
;           nkd = *(const f32x4*)(ps + VKD * CP); nrr = *(const f32x4*)(ps + VR * CP); nvv = *(const f32x2*)pv;
;         }
;         __builtin_amdgcn_sched_barrier(0x7);
;         const f32x2 kk0 = {ckk[0], ckk[1]}, kk1 = {ckk[2], ckk[3]}, w0 = {cw[0], cw[1]}, w1 = {cw[2], cw[3]};
;         const f32x2 b0 = {cbb[0], cbb[1]}, b1 = {cbb[2], cbb[3]}, kd0 = {ckd[0], ckd[1]}, kd1 = {ckd[2], ckd[3]};
;         const f32x2 r0 = {crr[0], crr[1]}, r1 = {crr[2], crr[3]};
;         const f32x2 p0 = S0[0] * kk0 + S0[1] * kk1, p1 = S1[0] * kk0 + S1[1] * kk1;
;         const f32x2 u00 = S0[0] * w0 + kd0 * cvv[0], u01 = S0[1] * w1 + kd1 * cvv[0];
;         const f32x2 u10 = S1[0] * w0 + kd0 * cvv[1], u11 = S1[1] * w1 + kd1 * cvv[1];
;         const float q0 = red16(p0[0] + p0[1]), q1 = red16(p1[0] + p1[1]);
;         S0[0] = u00 - b0 * q0; S0[1] = u01 - b1 * q0;
;         S1[0] = u10 - b0 * q1; S1[1] = u11 - b1 * q1;
;         const f32x2 y0 = S0[0] * r0 + S0[1] * r1, y1 = S1[0] * r0 + S1[1] * r1;
;         *(f32x2*)py = (f32x2){y0[0] + y0[1], y1[0] + y1[1]};
;         py += dir ? -512 : 512;
;         cw = nw; ckk = nkk; cbb = nbb; ckd = nkd; crr = nrr; cvv = nvv;
;       }
.Lscan_loop:
	s_add_i32 s20, s38, 2
	s_min_u32 s20, s20, 0x8f
	s_lshl_b32 s21, s20, 4
	s_cmp_lt_u32 s20, 16
	s_movk_i32 s28, 0x9f0
	s_cselect_b32 s28, 0xf0, s28
	s_sub_u32 s28, s28, s21
	s_cmp_eq_u32 s26, 0
	s_cselect_b32 s28, s21, s28
	ds_read_b128 v[226:229], v244 offset:4624
	s_waitcnt vmcnt(8)
	ds_read_b128 v[222:225], v244 offset:272
	ds_read_b128 v[234:237], v244 offset:13328
	v_lshlrev_b32_e32 v202, 16, v78
	ds_read_b128 v[230:233], v244 offset:8976
	ds_read_b128 v[238:241], v244 offset:17680
	ds_read_b64 v[242:243], v245 offset:22032
	v_and_b32_e32 v203, 0xffff0000, v78
	v_pk_mul_f32 v[128:129], v[116:117], v[164:165]
	v_pk_mul_f32 v[130:131], v[120:121], v[164:165]
	v_lshlrev_b32_e32 v204, 16, v80
	v_pk_fma_f32 v[128:129], v[118:119], v[166:167], v[128:129]
	v_pk_fma_f32 v[130:131], v[122:123], v[166:167], v[130:131]
	v_and_b32_e32 v205, 0xffff0000, v80
	v_pk_mul_f32 v[136:137], v[172:173], v[180:181] op_sel_hi:[1,0]
	v_pk_mul_f32 v[182:183], v[174:175], v[180:181] op_sel_hi:[1,0]
	v_add_f32_e32 v132, v128, v129
	v_lshlrev_b32_e32 v206, 16, v84
	v_add_f32_e32 v134, v130, v131
	v_pk_mul_f32 v[184:185], v[172:173], v[180:181] op_sel:[0,1]
	v_pk_mul_f32 v[186:187], v[174:175], v[180:181] op_sel:[0,1]
	v_and_b32_e32 v207, 0xffff0000, v84
	v_add_f32_dpp v132, v132, v132 quad_perm:[1,0,3,2] row_mask:0xf bank_mask:0xf bound_ctrl:1
	v_add_f32_dpp v134, v134, v134 quad_perm:[1,0,3,2] row_mask:0xf bank_mask:0xf bound_ctrl:1
	v_pk_fma_f32 v[136:137], v[116:117], v[160:161], v[136:137]
	v_pk_fma_f32 v[204:205], v[96:97], v[204:205], v[202:203] op_sel_hi:[0,1,1] neg_lo:[0,0,1] neg_hi:[0,0,1]
	v_add_f32_dpp v132, v132, v132 quad_perm:[2,3,0,1] row_mask:0xf bank_mask:0xf bound_ctrl:1
	v_add_f32_dpp v134, v134, v134 quad_perm:[2,3,0,1] row_mask:0xf bank_mask:0xf bound_ctrl:1
	v_pk_fma_f32 v[204:205], v[22:23], v[204:205], v[202:203]
	v_pk_fma_f32 v[182:183], v[118:119], v[162:163], v[182:183]
	v_add_f32_dpp v132, v132, v132 row_half_mirror row_mask:0xf bank_mask:0xf bound_ctrl:1
	v_add_f32_dpp v134, v134, v134 row_half_mirror row_mask:0xf bank_mask:0xf bound_ctrl:1
	v_pk_fma_f32 v[202:203], v[98:99], v[206:207], v[202:203] op_sel_hi:[0,1,1] neg_lo:[0,0,1] neg_hi:[0,0,1]
	v_pk_fma_f32 v[184:185], v[120:121], v[160:161], v[184:185]
	v_add_f32_dpp v132, v132, v132 row_mirror row_mask:0xf bank_mask:0xf bound_ctrl:1
	v_add_f32_dpp v134, v134, v134 row_mirror row_mask:0xf bank_mask:0xf bound_ctrl:1
	v_pk_fma_f32 v[202:203], v[18:19], v[202:203], v[204:205]
	v_pk_fma_f32 v[186:187], v[122:123], v[162:163], v[186:187]
	v_pk_fma_f32 v[116:117], v[168:169], v[132:133], v[136:137] op_sel_hi:[1,0,1] neg_lo:[1,0,0] neg_hi:[1,0,0]
	v_lshlrev_b32_e32 v204, 16, v79
	v_pk_fma_f32 v[118:119], v[170:171], v[132:133], v[182:183] op_sel_hi:[1,0,1] neg_lo:[1,0,0] neg_hi:[1,0,0]
	v_pk_fma_f32 v[120:121], v[168:169], v[134:135], v[184:185] op_sel_hi:[1,0,1] neg_lo:[1,0,0] neg_hi:[1,0,0]
	v_pk_fma_f32 v[122:123], v[170:171], v[134:135], v[186:187] op_sel_hi:[1,0,1] neg_lo:[1,0,0] neg_hi:[1,0,0]
	v_and_b32_e32 v205, 0xffff0000, v79
	v_pk_mul_f32 v[188:189], v[116:117], v[176:177]
	v_pk_mul_f32 v[190:191], v[120:121], v[176:177]
	v_pk_fma_f32 v[188:189], v[118:119], v[178:179], v[188:189]
	v_lshlrev_b32_e32 v206, 16, v81
	v_pk_fma_f32 v[190:191], v[122:123], v[178:179], v[190:191]
	v_add_f32_e32 v246, v188, v189
	v_add_f32_e32 v247, v190, v191
	v_and_b32_e32 v207, 0xffff0000, v81
	ds_write_b64 v159, v[246:247] offset:52224
	ds_read_b128 v[164:167], v244 offset:4896
	v_lshlrev_b32_e32 v208, 16, v85
	ds_read_b128 v[160:163], v244 offset:544
	ds_read_b128 v[172:175], v244 offset:13600
	ds_read_b128 v[168:171], v244 offset:9248
	v_and_b32_e32 v209, 0xffff0000, v85
	ds_read_b128 v[176:179], v244 offset:17952
	ds_read_b64 v[180:181], v245 offset:22304
	s_waitcnt lgkmcnt(7)
	v_pk_fma_f32 v[206:207], v[96:97], v[206:207], v[204:205] op_sel_hi:[0,1,1] neg_lo:[0,0,1] neg_hi:[0,0,1]
	v_pk_mul_f32 v[128:129], v[116:117], v[226:227]
	v_pk_mul_f32 v[130:131], v[120:121], v[226:227]
	v_pk_fma_f32 v[206:207], v[24:25], v[206:207], v[204:205]
	v_pk_fma_f32 v[128:129], v[118:119], v[228:229], v[128:129]
	v_pk_fma_f32 v[130:131], v[122:123], v[228:229], v[130:131]
	v_pk_mul_f32 v[136:137], v[234:235], v[242:243] op_sel_hi:[1,0]
	v_pk_fma_f32 v[204:205], v[98:99], v[208:209], v[204:205] op_sel_hi:[0,1,1] neg_lo:[0,0,1] neg_hi:[0,0,1]
	v_pk_mul_f32 v[182:183], v[236:237], v[242:243] op_sel_hi:[1,0]
	v_add_f32_e32 v132, v128, v129
	v_add_f32_e32 v134, v130, v131
	v_pk_fma_f32 v[204:205], v[20:21], v[204:205], v[206:207]
	v_pk_mul_f32 v[184:185], v[234:235], v[242:243] op_sel:[0,1]
	v_pk_mul_f32 v[186:187], v[236:237], v[242:243] op_sel:[0,1]
	v_add_f32_dpp v132, v132, v132 quad_perm:[1,0,3,2] row_mask:0xf bank_mask:0xf bound_ctrl:1
	v_lshlrev_b32_e32 v206, 16, v82
	v_add_f32_dpp v134, v134, v134 quad_perm:[1,0,3,2] row_mask:0xf bank_mask:0xf bound_ctrl:1
	v_pk_fma_f32 v[136:137], v[116:117], v[222:223], v[136:137]
	v_and_b32_e32 v207, 0xffff0000, v82
	v_add_f32_dpp v132, v132, v132 quad_perm:[2,3,0,1] row_mask:0xf bank_mask:0xf bound_ctrl:1
	v_add_f32_dpp v134, v134, v134 quad_perm:[2,3,0,1] row_mask:0xf bank_mask:0xf bound_ctrl:1
	v_pk_fma_f32 v[182:183], v[118:119], v[224:225], v[182:183]
	v_lshlrev_b32_e32 v208, 16, v88
	v_add_f32_dpp v132, v132, v132 row_half_mirror row_mask:0xf bank_mask:0xf bound_ctrl:1
	v_add_f32_dpp v134, v134, v134 row_half_mirror row_mask:0xf bank_mask:0xf bound_ctrl:1
	v_pk_fma_f32 v[184:185], v[120:121], v[222:223], v[184:185]
	v_and_b32_e32 v209, 0xffff0000, v88
	v_add_f32_dpp v132, v132, v132 row_mirror row_mask:0xf bank_mask:0xf bound_ctrl:1
; DI float red16(float x) { x = red8(x); x += dppf<0x140>(x); return x; }
; DI void unpack4(u32x2 v, float* f) { f[0] = bflo(v[0]); f[1] = bfhi(v[0]); f[2] = bflo(v[1]); f[3] = bfhi(v[1]); }
; DI void scan_task(const Params& p, int l, int b, int h, int dir, int half, char* lds) {
;     ...
;       float pc[4], pp[4], pn[4];
;       unpack4(ld[sec][1], pc); unpack4(ld[sec][0], pp); unpack4(ld[sec][2], pn);
; #pragma unroll
;       for (int j = 0; j < 4; ++j) ts[sec][j] = pc[j] + mu0[sec][j] * (pp[j] * mprev - pc[j]) + mu1[sec][j] * (pn[j] * mnext - pc[j]);
;     ...
;       for (int ii = 0; ii < 16; ++ii) {
;         f32x4 nw = cw, nkk = ckk, nbb = cbb, nkd = ckd, nrr = crr; f32x2 nvv = cvv;
;         if (ii < 15) {
;           ps += inc; pv += inc;
;           nw = *(const f32x4*)(ps + VW * CP); nkk = *(const f32x4*)(ps + VKK * CP); nbb = *(const f32x4*)(ps + VB * CP);
;           nkd = *(const f32x4*)(ps + VKD * CP); nrr = *(const f32x4*)(ps + VR * CP); nvv = *(const f32x2*)pv;
;         }
;         __builtin_amdgcn_sched_barrier(0x7);
;         const f32x2 kk0 = {ckk[0], ckk[1]}, kk1 = {ckk[2], ckk[3]}, w0 = {cw[0], cw[1]}, w1 = {cw[2], cw[3]};
;         const f32x2 b0 = {cbb[0], cbb[1]}, b1 = {cbb[2], cbb[3]}, kd0 = {ckd[0], ckd[1]}, kd1 = {ckd[2], ckd[3]};
;         const f32x2 r0 = {crr[0], crr[1]}, r1 = {crr[2], crr[3]};
;         const f32x2 p0 = S0[0] * kk0 + S0[1] * kk1, p1 = S1[0] * kk0 + S1[1] * kk1;
;         const f32x2 u00 = S0[0] * w0 + kd0 * cvv[0], u01 = S0[1] * w1 + kd1 * cvv[0];
;         const f32x2 u10 = S1[0] * w0 + kd0 * cvv[1], u11 = S1[1] * w1 + kd1 * cvv[1];
;         const float q0 = red16(p0[0] + p0[1]), q1 = red16(p1[0] + p1[1]);
;         S0[0] = u00 - b0 * q0; S0[1] = u01 - b1 * q0;
;         S1[0] = u10 - b0 * q1; S1[1] = u11 - b1 * q1;
;         const f32x2 y0 = S0[0] * r0 + S0[1] * r1, y1 = S1[0] * r0 + S1[1] * r1;
;         *(f32x2*)py = (f32x2){y0[0] + y0[1], y1[0] + y1[1]};
;         py += dir ? -512 : 512;
;         cw = nw; ckk = nkk; cbb = nbb; ckd = nkd; crr = nrr; cvv = nvv;
;       }
	v_add_f32_dpp v134, v134, v134 row_mirror row_mask:0xf bank_mask:0xf bound_ctrl:1
	v_lshlrev_b32_e32 v210, 16, v90
	v_pk_fma_f32 v[186:187], v[122:123], v[224:225], v[186:187]
	v_pk_fma_f32 v[116:117], v[230:231], v[132:133], v[136:137] op_sel_hi:[1,0,1] neg_lo:[1,0,0] neg_hi:[1,0,0]
	v_pk_fma_f32 v[118:119], v[232:233], v[132:133], v[182:183] op_sel_hi:[1,0,1] neg_lo:[1,0,0] neg_hi:[1,0,0]
	v_and_b32_e32 v211, 0xffff0000, v90
	v_pk_fma_f32 v[120:121], v[230:231], v[134:135], v[184:185] op_sel_hi:[1,0,1] neg_lo:[1,0,0] neg_hi:[1,0,0]
	v_pk_fma_f32 v[122:123], v[232:233], v[134:135], v[186:187] op_sel_hi:[1,0,1] neg_lo:[1,0,0] neg_hi:[1,0,0]
	v_pk_mul_f32 v[188:189], v[116:117], v[238:239]
	v_pk_fma_f32 v[208:209], v[96:97], v[208:209], v[206:207] op_sel_hi:[0,1,1] neg_lo:[0,0,1] neg_hi:[0,0,1]
	v_pk_mul_f32 v[190:191], v[120:121], v[238:239]
	v_pk_fma_f32 v[188:189], v[118:119], v[240:241], v[188:189]
	v_pk_fma_f32 v[190:191], v[122:123], v[240:241], v[190:191]
	v_pk_fma_f32 v[208:209], v[26:27], v[208:209], v[206:207]
	v_add_f32_e32 v246, v188, v189
	v_add_f32_e32 v247, v190, v191
	v_pk_fma_f32 v[206:207], v[98:99], v[210:211], v[206:207] op_sel_hi:[0,1,1] neg_lo:[0,0,1] neg_hi:[0,0,1]
	ds_write_b64 v159, v[246:247] offset:54272
	ds_read_b128 v[226:229], v244 offset:5168
	ds_read_b128 v[222:225], v244 offset:816
	v_pk_fma_f32 v[206:207], v[30:31], v[206:207], v[208:209]
	ds_read_b128 v[234:237], v244 offset:13872
	ds_read_b128 v[230:233], v244 offset:9520
	ds_read_b128 v[238:241], v244 offset:18224
	v_lshlrev_b32_e32 v208, 16, v83
	ds_read_b64 v[242:243], v245 offset:22576
	s_waitcnt lgkmcnt(7)
	v_and_b32_e32 v209, 0xffff0000, v83
	v_pk_mul_f32 v[128:129], v[116:117], v[164:165]
	v_pk_mul_f32 v[130:131], v[120:121], v[164:165]
	v_pk_fma_f32 v[128:129], v[118:119], v[166:167], v[128:129]
	v_lshlrev_b32_e32 v210, 16, v89
	v_pk_fma_f32 v[130:131], v[122:123], v[166:167], v[130:131]
	v_pk_mul_f32 v[136:137], v[172:173], v[180:181] op_sel_hi:[1,0]
	v_pk_mul_f32 v[182:183], v[174:175], v[180:181] op_sel_hi:[1,0]
	v_and_b32_e32 v211, 0xffff0000, v89
	v_add_f32_e32 v132, v128, v129
	v_add_f32_e32 v134, v130, v131
	v_pk_mul_f32 v[184:185], v[172:173], v[180:181] op_sel:[0,1]
	v_lshlrev_b32_e32 v212, 16, v91
	v_pk_mul_f32 v[186:187], v[174:175], v[180:181] op_sel:[0,1]
	v_add_f32_dpp v132, v132, v132 quad_perm:[1,0,3,2] row_mask:0xf bank_mask:0xf bound_ctrl:1
	v_and_b32_e32 v213, 0xffff0000, v91
	v_add_f32_dpp v134, v134, v134 quad_perm:[1,0,3,2] row_mask:0xf bank_mask:0xf bound_ctrl:1
	v_pk_fma_f32 v[136:137], v[116:117], v[160:161], v[136:137]
	v_add_f32_dpp v132, v132, v132 quad_perm:[2,3,0,1] row_mask:0xf bank_mask:0xf bound_ctrl:1
	v_pk_fma_f32 v[210:211], v[96:97], v[210:211], v[208:209] op_sel_hi:[0,1,1] neg_lo:[0,0,1] neg_hi:[0,0,1]
	v_add_f32_dpp v134, v134, v134 quad_perm:[2,3,0,1] row_mask:0xf bank_mask:0xf bound_ctrl:1
	v_pk_fma_f32 v[182:183], v[118:119], v[162:163], v[182:183]
	v_add_f32_dpp v132, v132, v132 row_half_mirror row_mask:0xf bank_mask:0xf bound_ctrl:1
	v_pk_fma_f32 v[210:211], v[28:29], v[210:211], v[208:209]
	v_add_f32_dpp v134, v134, v134 row_half_mirror row_mask:0xf bank_mask:0xf bound_ctrl:1
	v_pk_fma_f32 v[184:185], v[120:121], v[160:161], v[184:185]
	v_add_f32_dpp v132, v132, v132 row_mirror row_mask:0xf bank_mask:0xf bound_ctrl:1
	v_pk_fma_f32 v[208:209], v[98:99], v[212:213], v[208:209] op_sel_hi:[0,1,1] neg_lo:[0,0,1] neg_hi:[0,0,1]
	v_add_f32_dpp v134, v134, v134 row_mirror row_mask:0xf bank_mask:0xf bound_ctrl:1
	v_pk_fma_f32 v[186:187], v[122:123], v[162:163], v[186:187]
	v_pk_fma_f32 v[208:209], v[32:33], v[208:209], v[210:211]
	v_pk_fma_f32 v[116:117], v[168:169], v[132:133], v[136:137] op_sel_hi:[1,0,1] neg_lo:[1,0,0] neg_hi:[1,0,0]
	v_pk_fma_f32 v[118:119], v[170:171], v[132:133], v[182:183] op_sel_hi:[1,0,1] neg_lo:[1,0,0] neg_hi:[1,0,0]
	v_pk_fma_f32 v[120:121], v[168:169], v[134:135], v[184:185] op_sel_hi:[1,0,1] neg_lo:[1,0,0] neg_hi:[1,0,0]
	v_lshlrev_b32_e32 v210, 16, v86
	v_pk_fma_f32 v[122:123], v[170:171], v[134:135], v[186:187] op_sel_hi:[1,0,1] neg_lo:[1,0,0] neg_hi:[1,0,0]
	v_pk_mul_f32 v[188:189], v[116:117], v[176:177]
	v_pk_mul_f32 v[190:191], v[120:121], v[176:177]
	v_and_b32_e32 v211, 0xffff0000, v86
	v_pk_fma_f32 v[188:189], v[118:119], v[178:179], v[188:189]
	v_pk_fma_f32 v[190:191], v[122:123], v[178:179], v[190:191]
	v_lshlrev_b32_e32 v212, 16, v92
	v_add_f32_e32 v246, v188, v189
	v_add_f32_e32 v247, v190, v191
	ds_write_b64 v159, v[246:247] offset:56320
	v_and_b32_e32 v213, 0xffff0000, v92
	ds_read_b128 v[164:167], v244 offset:5440
	ds_read_b128 v[160:163], v244 offset:1088
	ds_read_b128 v[172:175], v244 offset:14144
	v_lshlrev_b32_e32 v214, 16, v94
	ds_read_b128 v[168:171], v244 offset:9792
	ds_read_b128 v[176:179], v244 offset:18496
	ds_read_b64 v[180:181], v245 offset:22848
	v_and_b32_e32 v215, 0xffff0000, v94
	s_waitcnt lgkmcnt(7)
; DI void scan_task(const Params& p, int l, int b, int h, int dir, int half, char* lds) {
;     ...
;       float pc[4], pp[4], pn[4];
;       unpack4(ld[sec][1], pc); unpack4(ld[sec][0], pp); unpack4(ld[sec][2], pn);
; #pragma unroll
;       for (int j = 0; j < 4; ++j) ts[sec][j] = pc[j] + mu0[sec][j] * (pp[j] * mprev - pc[j]) + mu1[sec][j] * (pn[j] * mnext - pc[j]);
;     }
;     *(f32x4*)(cb + VR * CP + st_p * CS + c4 * 4) = (f32x4){ts[0][0], ts[0][1], ts[0][2], ts[0][3]};
;     *(f32x4*)(cb + VV * CP + st_p * CS + c4 * 4) = (f32x4){ts[2][0], ts[2][1], ts[2][2], ts[2][3]};
;     *(f32x4*)(tk + st_p * CS + c4 * 4) = (f32x4){ts[1][0], ts[1][1], ts[1][2], ts[1][3]};
;     float kx[4], ss = 0.f;
; #pragma unroll
;     for (int j = 0; j < 4; ++j) { kx[j] = ts[1][j] * kkg[j]; ss += kx[j] * kx[j]; }
;     ss = red16(ss);
;     const float inv = rsqrtf(ss + 1e-12f);
;     ...
;       for (int ii = 0; ii < 16; ++ii) {
;         f32x4 nw = cw, nkk = ckk, nbb = cbb, nkd = ckd, nrr = crr; f32x2 nvv = cvv;
;         if (ii < 15) {
;           ps += inc; pv += inc;
;           nw = *(const f32x4*)(ps + VW * CP); nkk = *(const f32x4*)(ps + VKK * CP); nbb = *(const f32x4*)(ps + VB * CP);
;           nkd = *(const f32x4*)(ps + VKD * CP); nrr = *(const f32x4*)(ps + VR * CP); nvv = *(const f32x2*)pv;
;         }
;         __builtin_amdgcn_sched_barrier(0x7);
;         const f32x2 kk0 = {ckk[0], ckk[1]}, kk1 = {ckk[2], ckk[3]}, w0 = {cw[0], cw[1]}, w1 = {cw[2], cw[3]};
;         const f32x2 b0 = {cbb[0], cbb[1]}, b1 = {cbb[2], cbb[3]}, kd0 = {ckd[0], ckd[1]}, kd1 = {ckd[2], ckd[3]};
;         const f32x2 r0 = {crr[0], crr[1]}, r1 = {crr[2], crr[3]};
;         const f32x2 p0 = S0[0] * kk0 + S0[1] * kk1, p1 = S1[0] * kk0 + S1[1] * kk1;
;         const f32x2 u00 = S0[0] * w0 + kd0 * cvv[0], u01 = S0[1] * w1 + kd1 * cvv[0];
;         const f32x2 u10 = S1[0] * w0 + kd0 * cvv[1], u11 = S1[1] * w1 + kd1 * cvv[1];
;         const float q0 = red16(p0[0] + p0[1]), q1 = red16(p1[0] + p1[1]);
;         S0[0] = u00 - b0 * q0; S0[1] = u01 - b1 * q0;
;         S1[0] = u10 - b0 * q1; S1[1] = u11 - b1 * q1;
;         const f32x2 y0 = S0[0] * r0 + S0[1] * r1, y1 = S1[0] * r0 + S1[1] * r1;
;         *(f32x2*)py = (f32x2){y0[0] + y0[1], y1[0] + y1[1]};
;         py += dir ? -512 : 512;
;         cw = nw; ckk = nkk; cbb = nbb; ckd = nkd; crr = nrr; cvv = nvv;
;       }
	v_pk_mul_f32 v[128:129], v[116:117], v[226:227]
	v_pk_fma_f32 v[212:213], v[96:97], v[212:213], v[210:211] op_sel_hi:[0,1,1] neg_lo:[0,0,1] neg_hi:[0,0,1]
	v_pk_mul_f32 v[130:131], v[120:121], v[226:227]
	v_pk_fma_f32 v[128:129], v[118:119], v[228:229], v[128:129]
	v_pk_fma_f32 v[130:131], v[122:123], v[228:229], v[130:131]
	v_pk_fma_f32 v[212:213], v[38:39], v[212:213], v[210:211]
	v_pk_mul_f32 v[136:137], v[234:235], v[242:243] op_sel_hi:[1,0]
	v_pk_mul_f32 v[182:183], v[236:237], v[242:243] op_sel_hi:[1,0]
	v_add_f32_e32 v132, v128, v129
	v_pk_fma_f32 v[210:211], v[98:99], v[214:215], v[210:211] op_sel_hi:[0,1,1] neg_lo:[0,0,1] neg_hi:[0,0,1]
	v_add_f32_e32 v134, v130, v131
	v_pk_mul_f32 v[184:185], v[234:235], v[242:243] op_sel:[0,1]
	v_pk_fma_f32 v[210:211], v[34:35], v[210:211], v[212:213]
	v_pk_mul_f32 v[186:187], v[236:237], v[242:243] op_sel:[0,1]
	v_add_f32_dpp v132, v132, v132 quad_perm:[1,0,3,2] row_mask:0xf bank_mask:0xf bound_ctrl:1
	v_add_f32_dpp v134, v134, v134 quad_perm:[1,0,3,2] row_mask:0xf bank_mask:0xf bound_ctrl:1
	v_lshlrev_b32_e32 v212, 16, v87
	v_pk_fma_f32 v[136:137], v[116:117], v[222:223], v[136:137]
	v_add_f32_dpp v132, v132, v132 quad_perm:[2,3,0,1] row_mask:0xf bank_mask:0xf bound_ctrl:1
	v_add_f32_dpp v134, v134, v134 quad_perm:[2,3,0,1] row_mask:0xf bank_mask:0xf bound_ctrl:1
	v_and_b32_e32 v213, 0xffff0000, v87
	v_pk_fma_f32 v[182:183], v[118:119], v[224:225], v[182:183]
	v_add_f32_dpp v132, v132, v132 row_half_mirror row_mask:0xf bank_mask:0xf bound_ctrl:1
	v_add_f32_dpp v134, v134, v134 row_half_mirror row_mask:0xf bank_mask:0xf bound_ctrl:1
	v_lshlrev_b32_e32 v214, 16, v93
	v_pk_fma_f32 v[184:185], v[120:121], v[222:223], v[184:185]
	v_add_f32_dpp v132, v132, v132 row_mirror row_mask:0xf bank_mask:0xf bound_ctrl:1
	v_and_b32_e32 v215, 0xffff0000, v93
	v_add_f32_dpp v134, v134, v134 row_mirror row_mask:0xf bank_mask:0xf bound_ctrl:1
	v_pk_fma_f32 v[186:187], v[122:123], v[224:225], v[186:187]
	v_pk_fma_f32 v[116:117], v[230:231], v[132:133], v[136:137] op_sel_hi:[1,0,1] neg_lo:[1,0,0] neg_hi:[1,0,0]
	v_lshlrev_b32_e32 v216, 16, v95
	v_pk_fma_f32 v[118:119], v[232:233], v[132:133], v[182:183] op_sel_hi:[1,0,1] neg_lo:[1,0,0] neg_hi:[1,0,0]
	v_pk_fma_f32 v[120:121], v[230:231], v[134:135], v[184:185] op_sel_hi:[1,0,1] neg_lo:[1,0,0] neg_hi:[1,0,0]
	v_pk_fma_f32 v[122:123], v[232:233], v[134:135], v[186:187] op_sel_hi:[1,0,1] neg_lo:[1,0,0] neg_hi:[1,0,0]
	v_and_b32_e32 v217, 0xffff0000, v95
	v_pk_mul_f32 v[188:189], v[116:117], v[238:239]
	v_pk_mul_f32 v[190:191], v[120:121], v[238:239]
	v_pk_fma_f32 v[214:215], v[96:97], v[214:215], v[212:213] op_sel_hi:[0,1,1] neg_lo:[0,0,1] neg_hi:[0,0,1]
	v_pk_fma_f32 v[188:189], v[118:119], v[240:241], v[188:189]
	v_pk_fma_f32 v[190:191], v[122:123], v[240:241], v[190:191]
	v_add_f32_e32 v246, v188, v189
	v_pk_fma_f32 v[214:215], v[40:41], v[214:215], v[212:213]
	v_add_f32_e32 v247, v190, v191
	ds_write_b64 v159, v[246:247] offset:58368
	ds_read_b128 v[192:195], v124 offset:52224
	v_pk_fma_f32 v[212:213], v[98:99], v[216:217], v[212:213] op_sel_hi:[0,1,1] neg_lo:[0,0,1] neg_hi:[0,0,1]
	ds_read_b128 v[196:199], v124 offset:52240
	s_mul_i32 s20, s26, 15
	s_add_i32 s20, s20, 0
	v_pk_fma_f32 v[212:213], v[36:37], v[212:213], v[214:215]
	s_add_i32 s20, s20, s27
	s_add_i32 s20, s20, s100
	v_pk_mul_f32 v[214:215], v[42:43], v[206:207]
	s_mulk_i32 s20, 0x600
	s_waitcnt lgkmcnt(0)
	v_pk_add_f32 v[192:193], v[192:193], v[194:195]
	v_pk_mul_f32 v[218:219], v[44:45], v[208:209]
	v_pk_add_f32 v[196:197], v[196:197], v[198:199]
	v_add_u32_e32 v125, s20, v200
	v_pk_add_f32 v[192:193], v[192:193], v[196:197]
	v_pk_mul_f32 v[216:217], v[214:215], v[214:215]
	s_nop 1
	v_add_f32_dpp v192, v192, v192 quad_perm:[1,0,3,2] row_mask:0xf bank_mask:0xf bound_ctrl:1
	v_pk_mul_f32 v[220:221], v[218:219], v[218:219]
	v_add_f32_dpp v193, v193, v193 quad_perm:[1,0,3,2] row_mask:0xf bank_mask:0xf bound_ctrl:1
	s_nop 0
	v_add_f32_dpp v192, v192, v192 quad_perm:[2,3,0,1] row_mask:0xf bank_mask:0xf bound_ctrl:1
	v_add_f32_e32 v110, v216, v217
	v_add_f32_dpp v193, v193, v193 quad_perm:[2,3,0,1] row_mask:0xf bank_mask:0xf bound_ctrl:1
	global_store_dwordx2 v125, v[192:193], s[98:99]
	ds_read_b128 v[226:229], v244 offset:5712
	v_add_f32_e32 v110, v220, v110
	ds_read_b128 v[222:225], v244 offset:1360
	ds_read_b128 v[234:237], v244 offset:14416
	ds_read_b128 v[230:233], v244 offset:10064
	v_add_f32_e32 v110, v221, v110
	ds_read_b128 v[238:241], v244 offset:18768
	ds_read_b64 v[242:243], v245 offset:23120
	ds_write_b128 v100, v[202:205] offset:17408
	v_pk_mul_f32 v[128:129], v[116:117], v[164:165]
	v_pk_mul_f32 v[130:131], v[120:121], v[164:165]
	ds_write_b128 v100, v[210:213] offset:21760
	v_pk_fma_f32 v[128:129], v[118:119], v[166:167], v[128:129]
	v_pk_fma_f32 v[130:131], v[122:123], v[166:167], v[130:131]
	v_pk_mul_f32 v[136:137], v[172:173], v[180:181] op_sel_hi:[1,0]
	ds_write_b128 v100, v[206:209] offset:13056
	v_pk_mul_f32 v[182:183], v[174:175], v[180:181] op_sel_hi:[1,0]
	v_add_f32_e32 v132, v128, v129
	v_add_f32_e32 v134, v130, v131
	v_add_f32_dpp v110, v110, v110 quad_perm:[1,0,3,2] row_mask:0xf bank_mask:0xf bound_ctrl:1
	v_pk_mul_f32 v[184:185], v[172:173], v[180:181] op_sel:[0,1]
	v_pk_mul_f32 v[186:187], v[174:175], v[180:181] op_sel:[0,1]
	s_waitcnt vmcnt(4)
; DI float red16(float x) { x = red8(x); x += dppf<0x140>(x); return x; }
; DI void scan_task(const Params& p, int l, int b, int h, int dir, int half, char* lds) {
;     ...
;     float kx[4], ss = 0.f;
; #pragma unroll
;     for (int j = 0; j < 4; ++j) { kx[j] = ts[1][j] * kkg[j]; ss += kx[j] * kx[j]; }
;     ss = red16(ss);
;     const float inv = rsqrtf(ss + 1e-12f);
;     *(f32x4*)(cb + VKK * CP + st_p * CS + c4 * 4) = (f32x4){kx[0] * inv, kx[1] * inv, kx[2] * inv, kx[3] * inv};
;     __syncthreads();
;     f32x4 dw = {0.f, 0.f, 0.f, 0.f}, da = {0.f, 0.f, 0.f, 0.f};
; #pragma unroll
;     for (int ks = 0; ks < 2; ++ks) {
;       dw = __builtin_amdgcn_mfma_f32_16x16x32_bf16(bw[ks], aw[ks], dw, 0, 0, 0);
;       da = __builtin_amdgcn_mfma_f32_16x16x32_bf16(ba[ks], aa[ks], da, 0, 0, 0);
;     ...
;       for (int ii = 0; ii < 16; ++ii) {
;         f32x4 nw = cw, nkk = ckk, nbb = cbb, nkd = ckd, nrr = crr; f32x2 nvv = cvv;
;         if (ii < 15) {
;           ps += inc; pv += inc;
;           nw = *(const f32x4*)(ps + VW * CP); nkk = *(const f32x4*)(ps + VKK * CP); nbb = *(const f32x4*)(ps + VB * CP);
;           nkd = *(const f32x4*)(ps + VKD * CP); nrr = *(const f32x4*)(ps + VR * CP); nvv = *(const f32x2*)pv;
;         }
;         __builtin_amdgcn_sched_barrier(0x7);
;         const f32x2 kk0 = {ckk[0], ckk[1]}, kk1 = {ckk[2], ckk[3]}, w0 = {cw[0], cw[1]}, w1 = {cw[2], cw[3]};
;         const f32x2 b0 = {cbb[0], cbb[1]}, b1 = {cbb[2], cbb[3]}, kd0 = {ckd[0], ckd[1]}, kd1 = {ckd[2], ckd[3]};
;         const f32x2 r0 = {crr[0], crr[1]}, r1 = {crr[2], crr[3]};
;         const f32x2 p0 = S0[0] * kk0 + S0[1] * kk1, p1 = S1[0] * kk0 + S1[1] * kk1;
;         const f32x2 u00 = S0[0] * w0 + kd0 * cvv[0], u01 = S0[1] * w1 + kd1 * cvv[0];
;         const f32x2 u10 = S1[0] * w0 + kd0 * cvv[1], u11 = S1[1] * w1 + kd1 * cvv[1];
;         const float q0 = red16(p0[0] + p0[1]), q1 = red16(p1[0] + p1[1]);
;         S0[0] = u00 - b0 * q0; S0[1] = u01 - b1 * q0;
;         S1[0] = u10 - b0 * q1; S1[1] = u11 - b1 * q1;
;         const f32x2 y0 = S0[0] * r0 + S0[1] * r1, y1 = S1[0] * r0 + S1[1] * r1;
;         *(f32x2*)py = (f32x2){y0[0] + y0[1], y1[0] + y1[1]};
;         py += dir ? -512 : 512;
;         cw = nw; ckk = nkk; cbb = nbb; ckd = nkd; crr = nrr; cvv = nvv;
;       }
	v_add_f32_dpp v132, v132, v132 quad_perm:[1,0,3,2] row_mask:0xf bank_mask:0xf bound_ctrl:1
	v_add_f32_dpp v134, v134, v134 quad_perm:[1,0,3,2] row_mask:0xf bank_mask:0xf bound_ctrl:1
	v_pk_fma_f32 v[136:137], v[116:117], v[160:161], v[136:137]
	v_mfma_f32_16x16x32_bf16 v[206:209], v[2:5], v[62:65], 0
	v_add_f32_dpp v132, v132, v132 quad_perm:[2,3,0,1] row_mask:0xf bank_mask:0xf bound_ctrl:1
	v_add_f32_dpp v134, v134, v134 quad_perm:[2,3,0,1] row_mask:0xf bank_mask:0xf bound_ctrl:1
	v_pk_fma_f32 v[182:183], v[118:119], v[162:163], v[182:183]
	v_add_f32_dpp v110, v110, v110 quad_perm:[2,3,0,1] row_mask:0xf bank_mask:0xf bound_ctrl:1
	v_add_f32_dpp v132, v132, v132 row_half_mirror row_mask:0xf bank_mask:0xf bound_ctrl:1
	v_add_f32_dpp v134, v134, v134 row_half_mirror row_mask:0xf bank_mask:0xf bound_ctrl:1
	s_nop 1
	v_pk_fma_f32 v[184:185], v[120:121], v[160:161], v[184:185]
	v_add_f32_dpp v132, v132, v132 row_mirror row_mask:0xf bank_mask:0xf bound_ctrl:1
	v_add_f32_dpp v134, v134, v134 row_mirror row_mask:0xf bank_mask:0xf bound_ctrl:1
	v_add_f32_dpp v110, v110, v110 row_half_mirror row_mask:0xf bank_mask:0xf bound_ctrl:1
	v_pk_fma_f32 v[186:187], v[122:123], v[162:163], v[186:187]
	v_pk_fma_f32 v[116:117], v[168:169], v[132:133], v[136:137] op_sel_hi:[1,0,1] neg_lo:[1,0,0] neg_hi:[1,0,0]
	v_pk_fma_f32 v[118:119], v[170:171], v[132:133], v[182:183] op_sel_hi:[1,0,1] neg_lo:[1,0,0] neg_hi:[1,0,0]
	s_nop 1
	v_pk_fma_f32 v[120:121], v[168:169], v[134:135], v[184:185] op_sel_hi:[1,0,1] neg_lo:[1,0,0] neg_hi:[1,0,0]
	v_pk_fma_f32 v[122:123], v[170:171], v[134:135], v[186:187] op_sel_hi:[1,0,1] neg_lo:[1,0,0] neg_hi:[1,0,0]
	v_pk_mul_f32 v[188:189], v[116:117], v[176:177]
	v_add_f32_dpp v110, v110, v110 row_mirror row_mask:0xf bank_mask:0xf bound_ctrl:1
	v_pk_mul_f32 v[190:191], v[120:121], v[176:177]
	v_pk_fma_f32 v[188:189], v[118:119], v[178:179], v[188:189]
	v_add_f32_e32 v110, 0x2b8cbccc, v110
	v_pk_fma_f32 v[190:191], v[122:123], v[178:179], v[190:191]
	v_add_f32_e32 v246, v188, v189
	v_add_f32_e32 v247, v190, v191
	v_mul_f32_e32 v201, 0x4b800000, v110
	ds_write_b64 v159, v[246:247] offset:52224
	ds_read_b128 v[164:167], v244 offset:5984
	ds_read_b128 v[160:163], v244 offset:1632
	v_cmp_gt_f32_e32 vcc, s53, v110
	ds_read_b128 v[172:175], v244 offset:14688
	ds_read_b128 v[168:171], v244 offset:10336
	s_nop 1
	ds_read_b128 v[176:179], v244 offset:19040
	ds_read_b64 v[180:181], v245 offset:23392
	s_waitcnt lgkmcnt(10)
	v_cndmask_b32_e32 v110, v110, v201, vcc
	v_pk_mul_f32 v[128:129], v[116:117], v[226:227]
	v_pk_mul_f32 v[130:131], v[120:121], v[226:227]
	v_pk_fma_f32 v[128:129], v[118:119], v[228:229], v[128:129]
	v_rsq_f32_e32 v110, v110
	v_pk_fma_f32 v[130:131], v[122:123], v[228:229], v[130:131]
	v_pk_mul_f32 v[136:137], v[234:235], v[242:243] op_sel_hi:[1,0]
	v_pk_mul_f32 v[182:183], v[236:237], v[242:243] op_sel_hi:[1,0]
	s_nop 0
	v_add_f32_e32 v132, v128, v129
	v_add_f32_e32 v134, v130, v131
	v_mul_f32_e32 v201, 0x45800000, v110
	v_pk_mul_f32 v[184:185], v[234:235], v[242:243] op_sel:[0,1]
	v_pk_mul_f32 v[186:187], v[236:237], v[242:243] op_sel:[0,1]
	v_add_f32_dpp v132, v132, v132 quad_perm:[1,0,3,2] row_mask:0xf bank_mask:0xf bound_ctrl:1
	v_cndmask_b32_e32 v110, v110, v201, vcc
	v_add_f32_dpp v134, v134, v134 quad_perm:[1,0,3,2] row_mask:0xf bank_mask:0xf bound_ctrl:1
	v_pk_fma_f32 v[136:137], v[116:117], v[222:223], v[136:137]
	v_add_f32_dpp v132, v132, v132 quad_perm:[2,3,0,1] row_mask:0xf bank_mask:0xf bound_ctrl:1
	v_pk_mul_f32 v[204:205], v[218:219], v[110:111] op_sel_hi:[1,0]
	v_add_f32_dpp v134, v134, v134 quad_perm:[2,3,0,1] row_mask:0xf bank_mask:0xf bound_ctrl:1
	v_pk_fma_f32 v[182:183], v[118:119], v[224:225], v[182:183]
	v_pk_mul_f32 v[202:203], v[214:215], v[110:111] op_sel_hi:[1,0]
	v_add_f32_dpp v132, v132, v132 row_half_mirror row_mask:0xf bank_mask:0xf bound_ctrl:1
	v_add_f32_dpp v134, v134, v134 row_half_mirror row_mask:0xf bank_mask:0xf bound_ctrl:1
	v_pk_fma_f32 v[184:185], v[120:121], v[222:223], v[184:185]
	ds_write_b128 v100, v[202:205] offset:4352
	v_add_f32_dpp v132, v132, v132 row_mirror row_mask:0xf bank_mask:0xf bound_ctrl:1
	v_add_f32_dpp v134, v134, v134 row_mirror row_mask:0xf bank_mask:0xf bound_ctrl:1
	v_pk_fma_f32 v[186:187], v[122:123], v[224:225], v[186:187]
	s_nop 0
	v_pk_fma_f32 v[116:117], v[230:231], v[132:133], v[136:137] op_sel_hi:[1,0,1] neg_lo:[1,0,0] neg_hi:[1,0,0]
	v_pk_fma_f32 v[118:119], v[232:233], v[132:133], v[182:183] op_sel_hi:[1,0,1] neg_lo:[1,0,0] neg_hi:[1,0,0]
	v_pk_fma_f32 v[120:121], v[230:231], v[134:135], v[184:185] op_sel_hi:[1,0,1] neg_lo:[1,0,0] neg_hi:[1,0,0]
	v_mfma_f32_16x16x32_bf16 v[202:205], v[6:9], v[66:69], v[206:209]
	v_pk_fma_f32 v[122:123], v[232:233], v[134:135], v[186:187] op_sel_hi:[1,0,1] neg_lo:[1,0,0] neg_hi:[1,0,0]
	v_pk_mul_f32 v[188:189], v[116:117], v[238:239]
	s_waitcnt lgkmcnt(0)
	s_barrier
; DI float red16(float x) { x = red8(x); x += dppf<0x140>(x); return x; }
; DI void scan_task(const Params& p, int l, int b, int h, int dir, int half, char* lds) {
;     ...
;   auto issue_loads = [&](int c) {
;     const int slo = chunk_lo(c);
;     const int s = slo + st_p;
;     const bool hasprev = (s != 0 && s != NCTX), hasnext = (s != NCTX - 1 && s != TB - 1);
;     const bf16_t* pa = p.PA + (size_t)(b * TB + s) * LDPA + hc + c4 * 4;
;     const int op = hasprev ? -LDPA : 0, on = hasnext ? LDPA : 0;
;     mprev = hasprev ? 1.f : 0.f; mnext = hasnext ? 1.f : 0.f;
; #pragma unroll
;     for (int sec = 0; sec < 3; ++sec) {
;       ld[sec][1] = *(const u32x2*)(pa + sec * 384);
;       ld[sec][0] = *(const u32x2*)(pa + sec * 384 + op);
;       ld[sec][2] = *(const u32x2*)(pa + sec * 384 + on);
;     }
;     const size_t trow = (size_t)(b * TB + slo + fr) * 64;
; #pragma unroll
;     ...
;       for (int ii = 0; ii < 16; ++ii) {
;         f32x4 nw = cw, nkk = ckk, nbb = cbb, nkd = ckd, nrr = crr; f32x2 nvv = cvv;
;         if (ii < 15) {
;           ps += inc; pv += inc;
;           nw = *(const f32x4*)(ps + VW * CP); nkk = *(const f32x4*)(ps + VKK * CP); nbb = *(const f32x4*)(ps + VB * CP);
;           nkd = *(const f32x4*)(ps + VKD * CP); nrr = *(const f32x4*)(ps + VR * CP); nvv = *(const f32x2*)pv;
;         }
;         __builtin_amdgcn_sched_barrier(0x7);
;         const f32x2 kk0 = {ckk[0], ckk[1]}, kk1 = {ckk[2], ckk[3]}, w0 = {cw[0], cw[1]}, w1 = {cw[2], cw[3]};
;         const f32x2 b0 = {cbb[0], cbb[1]}, b1 = {cbb[2], cbb[3]}, kd0 = {ckd[0], ckd[1]}, kd1 = {ckd[2], ckd[3]};
;         const f32x2 r0 = {crr[0], crr[1]}, r1 = {crr[2], crr[3]};
;         const f32x2 p0 = S0[0] * kk0 + S0[1] * kk1, p1 = S1[0] * kk0 + S1[1] * kk1;
;         const f32x2 u00 = S0[0] * w0 + kd0 * cvv[0], u01 = S0[1] * w1 + kd1 * cvv[0];
;         const f32x2 u10 = S1[0] * w0 + kd0 * cvv[1], u11 = S1[1] * w1 + kd1 * cvv[1];
;         const float q0 = red16(p0[0] + p0[1]), q1 = red16(p1[0] + p1[1]);
;         S0[0] = u00 - b0 * q0; S0[1] = u01 - b1 * q0;
;         S1[0] = u10 - b0 * q1; S1[1] = u11 - b1 * q1;
;         const f32x2 y0 = S0[0] * r0 + S0[1] * r1, y1 = S1[0] * r0 + S1[1] * r1;
;         *(f32x2*)py = (f32x2){y0[0] + y0[1], y1[0] + y1[1]};
;         py += dir ? -512 : 512;
;         cw = nw; ckk = nkk; cbb = nbb; ckd = nkd; crr = nrr; cvv = nvv;
;       }
	v_pk_mul_f32 v[190:191], v[120:121], v[238:239]
	v_pk_fma_f32 v[188:189], v[118:119], v[240:241], v[188:189]
	v_pk_fma_f32 v[190:191], v[122:123], v[240:241], v[190:191]
	s_nop 0
	v_add_f32_e32 v246, v188, v189
	v_add_f32_e32 v247, v190, v191
	ds_write_b64 v159, v[246:247] offset:54272
	v_mfma_f32_16x16x32_bf16 v[206:209], v[10:13], v[70:73], 0
	ds_read_b128 v[226:229], v244 offset:6256
	ds_read_b128 v[222:225], v244 offset:1904
	ds_read_b128 v[210:213], v97 offset:13056
	ds_read_b128 v[234:237], v244 offset:14960
	ds_read_b128 v[230:233], v244 offset:10608
	ds_read_b128 v[238:241], v244 offset:19312
	ds_read_b128 v[214:217], v97 offset:4352
	ds_read_b64 v[242:243], v245 offset:23664
	v_pk_mul_f32 v[128:129], v[116:117], v[164:165]
	s_nop 1
	v_pk_mul_f32 v[130:131], v[120:121], v[164:165]
	v_pk_fma_f32 v[128:129], v[118:119], v[166:167], v[128:129]
	v_pk_fma_f32 v[130:131], v[122:123], v[166:167], v[130:131]
	v_add_f32_e32 v110, v50, v202
	v_pk_mul_f32 v[136:137], v[172:173], v[180:181] op_sel_hi:[1,0]
	v_pk_mul_f32 v[182:183], v[174:175], v[180:181] op_sel_hi:[1,0]
	v_mul_f32_e32 v110, 0xbfb8aa3b, v110
	v_add_f32_e32 v132, v128, v129
	v_add_f32_e32 v134, v130, v131
	v_pk_mul_f32 v[184:185], v[172:173], v[180:181] op_sel:[0,1]
	v_exp_f32_e32 v110, v110
	v_pk_mul_f32 v[186:187], v[174:175], v[180:181] op_sel:[0,1]
	v_add_f32_dpp v132, v132, v132 quad_perm:[1,0,3,2] row_mask:0xf bank_mask:0xf bound_ctrl:1
	v_add_f32_dpp v134, v134, v134 quad_perm:[1,0,3,2] row_mask:0xf bank_mask:0xf bound_ctrl:1
	s_nop 0
	v_pk_fma_f32 v[136:137], v[116:117], v[160:161], v[136:137]
	v_add_f32_dpp v132, v132, v132 quad_perm:[2,3,0,1] row_mask:0xf bank_mask:0xf bound_ctrl:1
	v_mfma_f32_16x16x32_bf16 v[206:209], v[14:17], v[74:77], v[206:209]
	v_add_f32_dpp v134, v134, v134 quad_perm:[2,3,0,1] row_mask:0xf bank_mask:0xf bound_ctrl:1
	v_pk_fma_f32 v[182:183], v[118:119], v[162:163], v[182:183]
	v_add_f32_dpp v132, v132, v132 row_half_mirror row_mask:0xf bank_mask:0xf bound_ctrl:1
	v_mov_b32_e32 v249, 0
	v_add_f32_dpp v134, v134, v134 row_half_mirror row_mask:0xf bank_mask:0xf bound_ctrl:1
	v_pk_fma_f32 v[184:185], v[120:121], v[160:161], v[184:185]
	v_add_f32_dpp v132, v132, v132 row_mirror row_mask:0xf bank_mask:0xf bound_ctrl:1
	s_nop 0
	v_add_f32_dpp v134, v134, v134 row_mirror row_mask:0xf bank_mask:0xf bound_ctrl:1
	v_pk_fma_f32 v[186:187], v[122:123], v[162:163], v[186:187]
	v_pk_fma_f32 v[116:117], v[168:169], v[132:133], v[136:137] op_sel_hi:[1,0,1] neg_lo:[1,0,0] neg_hi:[1,0,0]
	v_add_u32_e32 v62, s28, v1
	v_pk_fma_f32 v[118:119], v[170:171], v[132:133], v[182:183] op_sel_hi:[1,0,1] neg_lo:[1,0,0] neg_hi:[1,0,0]
	v_pk_fma_f32 v[120:121], v[168:169], v[134:135], v[184:185] op_sel_hi:[1,0,1] neg_lo:[1,0,0] neg_hi:[1,0,0]
	v_readlane_b32 s0, v252, 48
	v_pk_fma_f32 v[122:123], v[170:171], v[134:135], v[186:187] op_sel_hi:[1,0,1] neg_lo:[1,0,0] neg_hi:[1,0,0]
	v_pk_mul_f32 v[188:189], v[116:117], v[176:177]
	v_pk_mul_f32 v[190:191], v[120:121], v[176:177]
	v_and_b32_e32 v64, 0xfffffeff, v62
	v_pk_fma_f32 v[188:189], v[118:119], v[178:179], v[188:189]
	v_pk_fma_f32 v[190:191], v[122:123], v[178:179], v[190:191]
	v_add_f32_e32 v246, v188, v189
	s_nop 0
	v_add_f32_e32 v247, v190, v191
	ds_write_b64 v159, v[246:247] offset:56320
	ds_read_b128 v[164:167], v244 offset:6528
	v_and_b32_e32 v66, 0xfffff7ff, v62
	ds_read_b128 v[160:163], v244 offset:2176
	ds_read_b128 v[172:175], v244 offset:15232
	v_add_u32_e32 v62, s0, v62
	ds_read_b128 v[168:171], v244 offset:10880
	ds_read_b128 v[176:179], v244 offset:19584
	ds_read_b64 v[180:181], v245 offset:23936
	s_movk_i32 s0, 0xb00
	s_waitcnt lgkmcnt(7)
	v_pk_mul_f32 v[128:129], v[116:117], v[226:227]
	v_pk_mul_f32 v[130:131], v[120:121], v[226:227]
	v_mad_i64_i32 v[62:63], s[0:1], v62, s0, v[102:103]
	v_pk_fma_f32 v[128:129], v[118:119], v[228:229], v[128:129]
	v_pk_fma_f32 v[130:131], v[122:123], v[228:229], v[130:131]
	v_cmp_eq_u32_e32 vcc, 0, v64
	v_pk_mul_f32 v[136:137], v[234:235], v[242:243] op_sel_hi:[1,0]
	v_pk_mul_f32 v[182:183], v[236:237], v[242:243] op_sel_hi:[1,0]
	v_add_f32_e32 v132, v128, v129
	v_cmp_eq_u32_e64 s[0:1], s33, v66
	v_add_f32_e32 v134, v130, v131
	v_pk_mul_f32 v[184:185], v[234:235], v[242:243] op_sel:[0,1]
	v_pk_mul_f32 v[186:187], v[236:237], v[242:243] op_sel:[0,1]
	s_nop 0
	v_add_f32_dpp v132, v132, v132 quad_perm:[1,0,3,2] row_mask:0xf bank_mask:0xf bound_ctrl:1
	v_add_f32_dpp v134, v134, v134 quad_perm:[1,0,3,2] row_mask:0xf bank_mask:0xf bound_ctrl:1
	v_pk_fma_f32 v[136:137], v[116:117], v[222:223], v[136:137]
	v_cndmask_b32_e64 v65, -1, 0, vcc
	v_add_f32_dpp v132, v132, v132 quad_perm:[2,3,0,1] row_mask:0xf bank_mask:0xf bound_ctrl:1
	v_add_f32_dpp v134, v134, v134 quad_perm:[2,3,0,1] row_mask:0xf bank_mask:0xf bound_ctrl:1
	v_cndmask_b32_e64 v64, v150, 0, vcc
	v_pk_fma_f32 v[182:183], v[118:119], v[224:225], v[182:183]
	v_add_f32_dpp v132, v132, v132 row_half_mirror row_mask:0xf bank_mask:0xf bound_ctrl:1
	v_add_f32_dpp v134, v134, v134 row_half_mirror row_mask:0xf bank_mask:0xf bound_ctrl:1
	v_cndmask_b32_e64 v248, v151, 0, s[0:1]
	v_pk_fma_f32 v[184:185], v[120:121], v[222:223], v[184:185]
	v_add_f32_dpp v132, v132, v132 row_mirror row_mask:0xf bank_mask:0xf bound_ctrl:1
	v_add_f32_dpp v134, v134, v134 row_mirror row_mask:0xf bank_mask:0xf bound_ctrl:1
	v_lshl_add_u64 v[64:65], v[62:63], 0, v[64:65]
	v_pk_fma_f32 v[186:187], v[122:123], v[224:225], v[186:187]
	v_pk_fma_f32 v[116:117], v[230:231], v[132:133], v[136:137] op_sel_hi:[1,0,1] neg_lo:[1,0,0] neg_hi:[1,0,0]
	v_lshl_add_u64 v[66:67], v[62:63], 0, v[248:249]
	v_pk_fma_f32 v[118:119], v[232:233], v[132:133], v[182:183] op_sel_hi:[1,0,1] neg_lo:[1,0,0] neg_hi:[1,0,0]
	v_pk_fma_f32 v[120:121], v[230:231], v[134:135], v[184:185] op_sel_hi:[1,0,1] neg_lo:[1,0,0] neg_hi:[1,0,0]
	v_pk_fma_f32 v[122:123], v[232:233], v[134:135], v[186:187] op_sel_hi:[1,0,1] neg_lo:[1,0,0] neg_hi:[1,0,0]
	global_load_dwordx2 v[78:79], v[62:63], off
	v_pk_mul_f32 v[188:189], v[116:117], v[238:239]
	v_pk_mul_f32 v[190:191], v[120:121], v[238:239]
	v_pk_fma_f32 v[188:189], v[118:119], v[240:241], v[188:189]
	global_load_dwordx2 v[80:81], v[64:65], off
	v_pk_fma_f32 v[190:191], v[122:123], v[240:241], v[190:191]
	v_add_f32_e32 v246, v188, v189
	v_add_f32_e32 v247, v190, v191
	global_load_dwordx2 v[82:83], v[62:63], off offset:768
	ds_write_b64 v159, v[246:247] offset:58368
	ds_read_b128 v[192:195], v124 offset:52224
	global_load_dwordx2 v[86:87], v[62:63], off offset:1536
	ds_read_b128 v[196:199], v124 offset:52240
	s_mul_i32 s20, s26, 7
	s_add_i32 s20, s20, 4
	global_load_dwordx2 v[84:85], v[66:67], off
	s_add_i32 s20, s20, s27
	s_add_i32 s20, s20, s100
	s_mulk_i32 s20, 0x600
	global_load_dwordx2 v[88:89], v[64:65], off offset:768
	s_waitcnt lgkmcnt(0)
; DI void scan_task(const Params& p, int l, int b, int h, int dir, int half, char* lds) {
;     ...
;   auto issue_loads = [&](int c) {
;     const int slo = chunk_lo(c);
;     const int s = slo + st_p;
;     const bool hasprev = (s != 0 && s != NCTX), hasnext = (s != NCTX - 1 && s != TB - 1);
;     const bf16_t* pa = p.PA + (size_t)(b * TB + s) * LDPA + hc + c4 * 4;
;     const int op = hasprev ? -LDPA : 0, on = hasnext ? LDPA : 0;
;     ...
;       for (int ii = 0; ii < 16; ++ii) {
;         f32x4 nw = cw, nkk = ckk, nbb = cbb, nkd = ckd, nrr = crr; f32x2 nvv = cvv;
;         if (ii < 15) {
;           ps += inc; pv += inc;
;           nw = *(const f32x4*)(ps + VW * CP); nkk = *(const f32x4*)(ps + VKK * CP); nbb = *(const f32x4*)(ps + VB * CP);
;           nkd = *(const f32x4*)(ps + VKD * CP); nrr = *(const f32x4*)(ps + VR * CP); nvv = *(const f32x2*)pv;
;         }
;         __builtin_amdgcn_sched_barrier(0x7);
;         const f32x2 kk0 = {ckk[0], ckk[1]}, kk1 = {ckk[2], ckk[3]}, w0 = {cw[0], cw[1]}, w1 = {cw[2], cw[3]};
;         const f32x2 b0 = {cbb[0], cbb[1]}, b1 = {cbb[2], cbb[3]}, kd0 = {ckd[0], ckd[1]}, kd1 = {ckd[2], ckd[3]};
;         const f32x2 r0 = {crr[0], crr[1]}, r1 = {crr[2], crr[3]};
;         const f32x2 p0 = S0[0] * kk0 + S0[1] * kk1, p1 = S1[0] * kk0 + S1[1] * kk1;
;         const f32x2 u00 = S0[0] * w0 + kd0 * cvv[0], u01 = S0[1] * w1 + kd1 * cvv[0];
;         const f32x2 u10 = S1[0] * w0 + kd0 * cvv[1], u11 = S1[1] * w1 + kd1 * cvv[1];
;         const float q0 = red16(p0[0] + p0[1]), q1 = red16(p1[0] + p1[1]);
;         S0[0] = u00 - b0 * q0; S0[1] = u01 - b1 * q0;
;         S1[0] = u10 - b0 * q1; S1[1] = u11 - b1 * q1;
;         const f32x2 y0 = S0[0] * r0 + S0[1] * r1, y1 = S1[0] * r0 + S1[1] * r1;
;         *(f32x2*)py = (f32x2){y0[0] + y0[1], y1[0] + y1[1]};
;         py += dir ? -512 : 512;
;         cw = nw; ckk = nkk; cbb = nbb; ckd = nkd; crr = nrr; cvv = nvv;
;       }
;     }
;     __syncthreads();
;     {
;       const int slo = chunk_lo(c);
;       const float* yp = ybuf + (st_p * 16 + c4) * 32;
;       f32x4 a = *(const f32x4*)(yp + 4 * (c4 & 7));
; #pragma unroll
;       for (int i = 1; i < 8; ++i) a += *(const f32x4*)(yp + 4 * ((i + c4) & 7));
;       *(f32x2*)(p.Y + (size_t)dir * T_TOK * 384 + (size_t)(b * TB + slo + st_p) * 384 + hc + half * 32 + c4 * 2) = (f32x2){a[0] + a[2], a[1] + a[3]};
	v_pk_add_f32 v[192:193], v[192:193], v[194:195]
	global_load_dwordx2 v[90:91], v[66:67], off offset:768
	v_pk_add_f32 v[196:197], v[196:197], v[198:199]
	v_add_u32_e32 v125, s20, v200
	v_pk_add_f32 v[192:193], v[192:193], v[196:197]
	global_load_dwordx2 v[92:93], v[64:65], off offset:1536
	s_nop 1
	v_add_f32_dpp v192, v192, v192 quad_perm:[1,0,3,2] row_mask:0xf bank_mask:0xf bound_ctrl:1
	v_add_f32_dpp v193, v193, v193 quad_perm:[1,0,3,2] row_mask:0xf bank_mask:0xf bound_ctrl:1
	global_load_dwordx2 v[94:95], v[66:67], off offset:1536
	s_nop 0
	v_add_f32_dpp v192, v192, v192 quad_perm:[2,3,0,1] row_mask:0xf bank_mask:0xf bound_ctrl:1
	v_add_f32_dpp v193, v193, v193 quad_perm:[2,3,0,1] row_mask:0xf bank_mask:0xf bound_ctrl:1
	v_add_u32_e32 v62, s28, v127
	global_store_dwordx2 v125, v[192:193], s[98:99]
	ds_read_b128 v[226:229], v244 offset:6800
	v_ashrrev_i32_e32 v63, 31, v62
	ds_read_b128 v[222:225], v244 offset:2448
	ds_read_b128 v[234:237], v244 offset:15504
	ds_read_b128 v[230:233], v244 offset:11152
	v_lshlrev_b64 v[62:63], 7, v[62:63]
	ds_read_b128 v[238:241], v244 offset:19856
	ds_read_b64 v[242:243], v245 offset:24208
	v_lshl_add_u64 v[66:67], v[106:107], 0, v[62:63]
	v_pk_mul_f32 v[128:129], v[116:117], v[164:165]
	v_pk_mul_f32 v[130:131], v[120:121], v[164:165]
	s_nop 0
	v_pk_fma_f32 v[128:129], v[118:119], v[166:167], v[128:129]
	v_pk_fma_f32 v[130:131], v[122:123], v[166:167], v[130:131]
	v_pk_mul_f32 v[136:137], v[172:173], v[180:181] op_sel_hi:[1,0]
	v_lshl_add_u64 v[74:75], v[108:109], 0, v[62:63]
	v_pk_mul_f32 v[182:183], v[174:175], v[180:181] op_sel_hi:[1,0]
	v_add_f32_e32 v132, v128, v129
	v_add_f32_e32 v134, v130, v131
	global_load_dwordx4 v[62:65], v[66:67], off
	v_pk_mul_f32 v[184:185], v[172:173], v[180:181] op_sel:[0,1]
	v_pk_mul_f32 v[186:187], v[174:175], v[180:181] op_sel:[0,1]
	v_add_f32_dpp v132, v132, v132 quad_perm:[1,0,3,2] row_mask:0xf bank_mask:0xf bound_ctrl:1
	s_nop 0
	v_add_f32_dpp v134, v134, v134 quad_perm:[1,0,3,2] row_mask:0xf bank_mask:0xf bound_ctrl:1
	v_pk_fma_f32 v[136:137], v[116:117], v[160:161], v[136:137]
	global_load_dwordx4 v[66:69], v[66:67], off offset:64
	v_add_f32_dpp v132, v132, v132 quad_perm:[2,3,0,1] row_mask:0xf bank_mask:0xf bound_ctrl:1
	v_add_f32_dpp v134, v134, v134 quad_perm:[2,3,0,1] row_mask:0xf bank_mask:0xf bound_ctrl:1
	v_pk_fma_f32 v[182:183], v[118:119], v[162:163], v[182:183]
	s_nop 0
	v_add_f32_dpp v132, v132, v132 row_half_mirror row_mask:0xf bank_mask:0xf bound_ctrl:1
	v_add_f32_dpp v134, v134, v134 row_half_mirror row_mask:0xf bank_mask:0xf bound_ctrl:1
	v_pk_fma_f32 v[184:185], v[120:121], v[160:161], v[184:185]
	global_load_dwordx4 v[70:73], v[74:75], off
	v_add_f32_dpp v132, v132, v132 row_mirror row_mask:0xf bank_mask:0xf bound_ctrl:1
	v_add_f32_dpp v134, v134, v134 row_mirror row_mask:0xf bank_mask:0xf bound_ctrl:1
	v_pk_fma_f32 v[186:187], v[122:123], v[162:163], v[186:187]
	s_nop 0
	v_pk_fma_f32 v[116:117], v[168:169], v[132:133], v[136:137] op_sel_hi:[1,0,1] neg_lo:[1,0,0] neg_hi:[1,0,0]
	v_pk_fma_f32 v[118:119], v[170:171], v[132:133], v[182:183] op_sel_hi:[1,0,1] neg_lo:[1,0,0] neg_hi:[1,0,0]
	global_load_dwordx4 v[74:77], v[74:75], off offset:64
	v_pk_fma_f32 v[120:121], v[168:169], v[134:135], v[184:185] op_sel_hi:[1,0,1] neg_lo:[1,0,0] neg_hi:[1,0,0]
	v_pk_fma_f32 v[122:123], v[170:171], v[134:135], v[186:187] op_sel_hi:[1,0,1] neg_lo:[1,0,0] neg_hi:[1,0,0]
	v_pk_mul_f32 v[188:189], v[116:117], v[176:177]
	v_cndmask_b32_e64 v96, 1.0, 0, vcc
	v_pk_mul_f32 v[190:191], v[120:121], v[176:177]
	v_pk_fma_f32 v[188:189], v[118:119], v[178:179], v[188:189]
	v_pk_fma_f32 v[190:191], v[122:123], v[178:179], v[190:191]
	v_cndmask_b32_e64 v98, 1.0, 0, s[0:1]
	v_add_f32_e32 v246, v188, v189
	v_add_f32_e32 v247, v190, v191
	v_add_f32_e32 v201, v51, v203
	ds_write_b64 v159, v[246:247] offset:52224
	ds_read_b128 v[164:167], v244 offset:7072
	ds_read_b128 v[160:163], v244 offset:2720
	v_mul_f32_e32 v201, 0xbfb8aa3b, v201
	ds_read_b128 v[172:175], v244 offset:15776
	ds_read_b128 v[168:171], v244 offset:11424
	ds_read_b128 v[176:179], v244 offset:20128
	v_exp_f32_e32 v201, v201
	ds_read_b64 v[180:181], v245 offset:24480
	s_waitcnt lgkmcnt(7)
	v_pk_mul_f32 v[128:129], v[116:117], v[226:227]
	v_add_f32_e32 v110, 1.0, v110
	v_pk_mul_f32 v[130:131], v[120:121], v[226:227]
	v_pk_fma_f32 v[128:129], v[118:119], v[228:229], v[128:129]
	v_rcp_f32_e32 v110, v110
	v_pk_fma_f32 v[130:131], v[122:123], v[228:229], v[130:131]
	v_pk_mul_f32 v[136:137], v[234:235], v[242:243] op_sel_hi:[1,0]
	v_pk_mul_f32 v[182:183], v[236:237], v[242:243] op_sel_hi:[1,0]
	s_nop 2
	v_add_f32_e32 v132, v128, v129
	v_add_f32_e32 v134, v130, v131
	v_pk_mul_f32 v[184:185], v[234:235], v[242:243] op_sel:[0,1]
	v_add_f32_e32 v202, v54, v206
	v_pk_mul_f32 v[186:187], v[236:237], v[242:243] op_sel:[0,1]
	v_add_f32_dpp v132, v132, v132 quad_perm:[1,0,3,2] row_mask:0xf bank_mask:0xf bound_ctrl:1
	v_mul_f32_e32 v202, 0xbfb8aa3b, v202
	v_add_f32_dpp v134, v134, v134 quad_perm:[1,0,3,2] row_mask:0xf bank_mask:0xf bound_ctrl:1
	v_pk_fma_f32 v[136:137], v[116:117], v[222:223], v[136:137]
	v_add_f32_dpp v132, v132, v132 quad_perm:[2,3,0,1] row_mask:0xf bank_mask:0xf bound_ctrl:1
	v_exp_f32_e32 v203, v202
	v_add_f32_dpp v134, v134, v134 quad_perm:[2,3,0,1] row_mask:0xf bank_mask:0xf bound_ctrl:1
	v_pk_fma_f32 v[182:183], v[118:119], v[224:225], v[182:183]
	v_add_f32_dpp v132, v132, v132 row_half_mirror row_mask:0xf bank_mask:0xf bound_ctrl:1
	v_add_f32_e32 v201, 1.0, v201
	v_add_f32_dpp v134, v134, v134 row_half_mirror row_mask:0xf bank_mask:0xf bound_ctrl:1
	v_pk_fma_f32 v[184:185], v[120:121], v[222:223], v[184:185]
; DI float sigmoidf_(float x) { return __builtin_amdgcn_rcpf(1.f + __expf(-x)); }
; DI float red16(float x) { x = red8(x); x += dppf<0x140>(x); return x; }
; DI void scan_task(const Params& p, int l, int b, int h, int dir, int half, char* lds) {
;     ...
; #pragma unroll
;       for (int j = 0; j < 4; ++j) {
;         wv[j] = __expf(-LOG_DECAY_SCALE * sigmoidf_(w0[j] + dw[j]));
;         const float a = sigmoidf_(a0[j] + da[j]);
;         kdv[j] = kv[j] * (1.f + (a - 1.f) * kag[j]);
;         bv[j] = kkv[j] * a;
;     ...
;       for (int ii = 0; ii < 16; ++ii) {
;         f32x4 nw = cw, nkk = ckk, nbb = cbb, nkd = ckd, nrr = crr; f32x2 nvv = cvv;
;         if (ii < 15) {
;           ps += inc; pv += inc;
;           nw = *(const f32x4*)(ps + VW * CP); nkk = *(const f32x4*)(ps + VKK * CP); nbb = *(const f32x4*)(ps + VB * CP);
;           nkd = *(const f32x4*)(ps + VKD * CP); nrr = *(const f32x4*)(ps + VR * CP); nvv = *(const f32x2*)pv;
;         }
;         __builtin_amdgcn_sched_barrier(0x7);
;         const f32x2 kk0 = {ckk[0], ckk[1]}, kk1 = {ckk[2], ckk[3]}, w0 = {cw[0], cw[1]}, w1 = {cw[2], cw[3]};
;         const f32x2 b0 = {cbb[0], cbb[1]}, b1 = {cbb[2], cbb[3]}, kd0 = {ckd[0], ckd[1]}, kd1 = {ckd[2], ckd[3]};
;         const f32x2 r0 = {crr[0], crr[1]}, r1 = {crr[2], crr[3]};
;         const f32x2 p0 = S0[0] * kk0 + S0[1] * kk1, p1 = S1[0] * kk0 + S1[1] * kk1;
;         const f32x2 u00 = S0[0] * w0 + kd0 * cvv[0], u01 = S0[1] * w1 + kd1 * cvv[0];
;         const f32x2 u10 = S1[0] * w0 + kd0 * cvv[1], u11 = S1[1] * w1 + kd1 * cvv[1];
;         const float q0 = red16(p0[0] + p0[1]), q1 = red16(p1[0] + p1[1]);
;         S0[0] = u00 - b0 * q0; S0[1] = u01 - b1 * q0;
;         S1[0] = u10 - b0 * q1; S1[1] = u11 - b1 * q1;
;         const f32x2 y0 = S0[0] * r0 + S0[1] * r1, y1 = S1[0] * r0 + S1[1] * r1;
;         *(f32x2*)py = (f32x2){y0[0] + y0[1], y1[0] + y1[1]};
;         py += dir ? -512 : 512;
;         cw = nw; ckk = nkk; cbb = nbb; ckd = nkd; crr = nrr; cvv = nvv;
;       }
	v_add_f32_dpp v132, v132, v132 row_mirror row_mask:0xf bank_mask:0xf bound_ctrl:1
	v_rcp_f32_e32 v201, v201
	v_add_f32_dpp v134, v134, v134 row_mirror row_mask:0xf bank_mask:0xf bound_ctrl:1
	v_pk_fma_f32 v[186:187], v[122:123], v[224:225], v[186:187]
	v_mul_f32_e32 v110, 0xbf1b459e, v110
	v_pk_fma_f32 v[116:117], v[230:231], v[132:133], v[136:137] op_sel_hi:[1,0,1] neg_lo:[1,0,0] neg_hi:[1,0,0]
	v_pk_fma_f32 v[118:119], v[232:233], v[132:133], v[182:183] op_sel_hi:[1,0,1] neg_lo:[1,0,0] neg_hi:[1,0,0]
	v_pk_fma_f32 v[120:121], v[230:231], v[134:135], v[184:185] op_sel_hi:[1,0,1] neg_lo:[1,0,0] neg_hi:[1,0,0]
	v_mul_f32_e32 v110, 0x3fb8aa3b, v110
	v_pk_fma_f32 v[122:123], v[232:233], v[134:135], v[186:187] op_sel_hi:[1,0,1] neg_lo:[1,0,0] neg_hi:[1,0,0]
	v_pk_mul_f32 v[188:189], v[116:117], v[238:239]
	v_pk_mul_f32 v[190:191], v[120:121], v[238:239]
	v_exp_f32_e32 v202, v110
	v_pk_fma_f32 v[188:189], v[118:119], v[240:241], v[188:189]
	v_pk_fma_f32 v[190:191], v[122:123], v[240:241], v[190:191]
	v_add_f32_e32 v110, 1.0, v203
	v_add_f32_e32 v246, v188, v189
	v_add_f32_e32 v247, v190, v191
	ds_write_b64 v159, v[246:247] offset:54272
	v_rcp_f32_e32 v218, v110
	ds_read_b128 v[226:229], v244 offset:7344
	ds_read_b128 v[222:225], v244 offset:2992
	ds_read_b128 v[234:237], v244 offset:16048
	v_mul_f32_e32 v110, 0xbf1b459e, v201
	ds_read_b128 v[230:233], v244 offset:11696
	ds_read_b128 v[238:241], v244 offset:20400
	ds_read_b64 v[242:243], v245 offset:24752
	v_add_f32_e32 v201, v52, v204
	s_waitcnt lgkmcnt(7)
	v_pk_mul_f32 v[128:129], v[116:117], v[164:165]
	v_mul_f32_e32 v201, 0xbfb8aa3b, v201
	v_pk_mul_f32 v[130:131], v[120:121], v[164:165]
	v_pk_fma_f32 v[128:129], v[118:119], v[166:167], v[128:129]
	v_pk_fma_f32 v[130:131], v[122:123], v[166:167], v[130:131]
	v_exp_f32_e32 v201, v201
	v_pk_mul_f32 v[136:137], v[172:173], v[180:181] op_sel_hi:[1,0]
	v_pk_mul_f32 v[182:183], v[174:175], v[180:181] op_sel_hi:[1,0]
	v_add_f32_e32 v132, v128, v129
	v_add_f32_e32 v203, v55, v207
	v_add_f32_e32 v134, v130, v131
	v_pk_mul_f32 v[184:185], v[172:173], v[180:181] op_sel:[0,1]
	v_mul_f32_e32 v203, 0xbfb8aa3b, v203
	v_pk_mul_f32 v[186:187], v[174:175], v[180:181] op_sel:[0,1]
	v_add_f32_dpp v132, v132, v132 quad_perm:[1,0,3,2] row_mask:0xf bank_mask:0xf bound_ctrl:1
	v_add_f32_dpp v134, v134, v134 quad_perm:[1,0,3,2] row_mask:0xf bank_mask:0xf bound_ctrl:1
	v_exp_f32_e32 v204, v203
	v_pk_fma_f32 v[136:137], v[116:117], v[160:161], v[136:137]
	v_add_f32_dpp v132, v132, v132 quad_perm:[2,3,0,1] row_mask:0xf bank_mask:0xf bound_ctrl:1
	v_add_f32_dpp v134, v134, v134 quad_perm:[2,3,0,1] row_mask:0xf bank_mask:0xf bound_ctrl:1
	v_add_f32_e32 v201, 1.0, v201
	v_pk_fma_f32 v[182:183], v[118:119], v[162:163], v[182:183]
	v_add_f32_dpp v132, v132, v132 row_half_mirror row_mask:0xf bank_mask:0xf bound_ctrl:1
	v_add_f32_dpp v134, v134, v134 row_half_mirror row_mask:0xf bank_mask:0xf bound_ctrl:1
	v_rcp_f32_e32 v201, v201
	v_pk_fma_f32 v[184:185], v[120:121], v[160:161], v[184:185]
	v_add_f32_dpp v132, v132, v132 row_mirror row_mask:0xf bank_mask:0xf bound_ctrl:1
	v_mul_f32_e32 v110, 0x3fb8aa3b, v110
	v_add_f32_dpp v134, v134, v134 row_mirror row_mask:0xf bank_mask:0xf bound_ctrl:1
	v_pk_fma_f32 v[186:187], v[122:123], v[162:163], v[186:187]
	v_pk_fma_f32 v[116:117], v[168:169], v[132:133], v[136:137] op_sel_hi:[1,0,1] neg_lo:[1,0,0] neg_hi:[1,0,0]
	v_exp_f32_e32 v203, v110
	v_pk_fma_f32 v[118:119], v[170:171], v[132:133], v[182:183] op_sel_hi:[1,0,1] neg_lo:[1,0,0] neg_hi:[1,0,0]
	v_pk_fma_f32 v[120:121], v[168:169], v[134:135], v[184:185] op_sel_hi:[1,0,1] neg_lo:[1,0,0] neg_hi:[1,0,0]
	v_pk_fma_f32 v[122:123], v[170:171], v[134:135], v[186:187] op_sel_hi:[1,0,1] neg_lo:[1,0,0] neg_hi:[1,0,0]
	v_add_f32_e32 v110, 1.0, v204
	v_pk_mul_f32 v[188:189], v[116:117], v[176:177]
	v_pk_mul_f32 v[190:191], v[120:121], v[176:177]
	v_rcp_f32_e32 v219, v110
	v_pk_fma_f32 v[188:189], v[118:119], v[178:179], v[188:189]
	v_pk_fma_f32 v[190:191], v[122:123], v[178:179], v[190:191]
	v_add_f32_e32 v246, v188, v189
	v_mul_f32_e32 v110, 0xbf1b459e, v201
	v_add_f32_e32 v247, v190, v191
	ds_write_b64 v159, v[246:247] offset:56320
	ds_read_b128 v[164:167], v244 offset:7616
	v_mul_f32_e32 v110, 0x3fb8aa3b, v110
	ds_read_b128 v[160:163], v244 offset:3264
	ds_read_b128 v[172:175], v244 offset:16320
	ds_read_b128 v[168:171], v244 offset:11968
	v_exp_f32_e32 v204, v110
	ds_read_b128 v[176:179], v244 offset:20672
	ds_read_b64 v[180:181], v245 offset:25024
	v_add_f32_e32 v110, v53, v205
	s_waitcnt lgkmcnt(7)
; DI void scan_task(const Params& p, int l, int b, int h, int dir, int half, char* lds) {
;     ...
; #pragma unroll
;       for (int j = 0; j < 4; ++j) {
;         wv[j] = __expf(-LOG_DECAY_SCALE * sigmoidf_(w0[j] + dw[j]));
;         const float a = sigmoidf_(a0[j] + da[j]);
;         kdv[j] = kv[j] * (1.f + (a - 1.f) * kag[j]);
;         bv[j] = kkv[j] * a;
;       }
;       *(f32x4*)(cb + VW * CP + fr * CS + colB) = wv;
;     ...
;       for (int ii = 0; ii < 16; ++ii) {
;         f32x4 nw = cw, nkk = ckk, nbb = cbb, nkd = ckd, nrr = crr; f32x2 nvv = cvv;
;         if (ii < 15) {
;           ps += inc; pv += inc;
;           nw = *(const f32x4*)(ps + VW * CP); nkk = *(const f32x4*)(ps + VKK * CP); nbb = *(const f32x4*)(ps + VB * CP);
;           nkd = *(const f32x4*)(ps + VKD * CP); nrr = *(const f32x4*)(ps + VR * CP); nvv = *(const f32x2*)pv;
;         }
;         __builtin_amdgcn_sched_barrier(0x7);
;         const f32x2 kk0 = {ckk[0], ckk[1]}, kk1 = {ckk[2], ckk[3]}, w0 = {cw[0], cw[1]}, w1 = {cw[2], cw[3]};
;         const f32x2 b0 = {cbb[0], cbb[1]}, b1 = {cbb[2], cbb[3]}, kd0 = {ckd[0], ckd[1]}, kd1 = {ckd[2], ckd[3]};
;         const f32x2 r0 = {crr[0], crr[1]}, r1 = {crr[2], crr[3]};
;         const f32x2 p0 = S0[0] * kk0 + S0[1] * kk1, p1 = S1[0] * kk0 + S1[1] * kk1;
;         const f32x2 u00 = S0[0] * w0 + kd0 * cvv[0], u01 = S0[1] * w1 + kd1 * cvv[0];
;         const f32x2 u10 = S1[0] * w0 + kd0 * cvv[1], u11 = S1[1] * w1 + kd1 * cvv[1];
;         const float q0 = red16(p0[0] + p0[1]), q1 = red16(p1[0] + p1[1]);
;         S0[0] = u00 - b0 * q0; S0[1] = u01 - b1 * q0;
;         S1[0] = u10 - b0 * q1; S1[1] = u11 - b1 * q1;
;         const f32x2 y0 = S0[0] * r0 + S0[1] * r1, y1 = S1[0] * r0 + S1[1] * r1;
;         *(f32x2*)py = (f32x2){y0[0] + y0[1], y1[0] + y1[1]};
;         py += dir ? -512 : 512;
;         cw = nw; ckk = nkk; cbb = nbb; ckd = nkd; crr = nrr; cvv = nvv;
;       }
;     }
;     __syncthreads();
;     {
;       const int slo = chunk_lo(c);
;       const float* yp = ybuf + (st_p * 16 + c4) * 32;
;       f32x4 a = *(const f32x4*)(yp + 4 * (c4 & 7));
; #pragma unroll
;       for (int i = 1; i < 8; ++i) a += *(const f32x4*)(yp + 4 * ((i + c4) & 7));
;       *(f32x2*)(p.Y + (size_t)dir * T_TOK * 384 + (size_t)(b * TB + slo + st_p) * 384 + hc + half * 32 + c4 * 2) = (f32x2){a[0] + a[2], a[1] + a[3]};
	v_pk_mul_f32 v[128:129], v[116:117], v[226:227]
	v_pk_mul_f32 v[130:131], v[120:121], v[226:227]
	v_mul_f32_e32 v110, 0xbfb8aa3b, v110
	v_pk_fma_f32 v[128:129], v[118:119], v[228:229], v[128:129]
	v_pk_fma_f32 v[130:131], v[122:123], v[228:229], v[130:131]
	v_pk_mul_f32 v[136:137], v[234:235], v[242:243] op_sel_hi:[1,0]
	v_exp_f32_e32 v110, v110
	v_pk_mul_f32 v[182:183], v[236:237], v[242:243] op_sel_hi:[1,0]
	v_add_f32_e32 v132, v128, v129
	v_add_f32_e32 v134, v130, v131
	v_add_f32_e32 v201, v56, v208
	v_pk_mul_f32 v[184:185], v[234:235], v[242:243] op_sel:[0,1]
	v_pk_mul_f32 v[186:187], v[236:237], v[242:243] op_sel:[0,1]
	v_mul_f32_e32 v201, 0xbfb8aa3b, v201
	v_add_f32_dpp v132, v132, v132 quad_perm:[1,0,3,2] row_mask:0xf bank_mask:0xf bound_ctrl:1
	v_add_f32_dpp v134, v134, v134 quad_perm:[1,0,3,2] row_mask:0xf bank_mask:0xf bound_ctrl:1
	v_pk_fma_f32 v[136:137], v[116:117], v[222:223], v[136:137]
	v_add_f32_e32 v205, v57, v209
	v_add_f32_dpp v132, v132, v132 quad_perm:[2,3,0,1] row_mask:0xf bank_mask:0xf bound_ctrl:1
	v_add_f32_dpp v134, v134, v134 quad_perm:[2,3,0,1] row_mask:0xf bank_mask:0xf bound_ctrl:1
	v_pk_fma_f32 v[182:183], v[118:119], v[224:225], v[182:183]
	v_exp_f32_e32 v201, v201
	v_add_f32_dpp v132, v132, v132 row_half_mirror row_mask:0xf bank_mask:0xf bound_ctrl:1
	v_add_f32_dpp v134, v134, v134 row_half_mirror row_mask:0xf bank_mask:0xf bound_ctrl:1
	v_mul_f32_e32 v205, 0xbfb8aa3b, v205
	v_pk_fma_f32 v[184:185], v[120:121], v[222:223], v[184:185]
	v_add_f32_dpp v132, v132, v132 row_mirror row_mask:0xf bank_mask:0xf bound_ctrl:1
	v_add_f32_dpp v134, v134, v134 row_mirror row_mask:0xf bank_mask:0xf bound_ctrl:1
	v_exp_f32_e32 v205, v205
	v_pk_fma_f32 v[186:187], v[122:123], v[224:225], v[186:187]
	v_pk_fma_f32 v[116:117], v[230:231], v[132:133], v[136:137] op_sel_hi:[1,0,1] neg_lo:[1,0,0] neg_hi:[1,0,0]
	v_pk_fma_f32 v[118:119], v[232:233], v[132:133], v[182:183] op_sel_hi:[1,0,1] neg_lo:[1,0,0] neg_hi:[1,0,0]
	v_add_f32_e32 v110, 1.0, v110
	v_pk_fma_f32 v[120:121], v[230:231], v[134:135], v[184:185] op_sel_hi:[1,0,1] neg_lo:[1,0,0] neg_hi:[1,0,0]
	v_pk_fma_f32 v[122:123], v[232:233], v[134:135], v[186:187] op_sel_hi:[1,0,1] neg_lo:[1,0,0] neg_hi:[1,0,0]
	v_pk_mul_f32 v[188:189], v[116:117], v[238:239]
	v_rcp_f32_e32 v110, v110
	v_pk_mul_f32 v[190:191], v[120:121], v[238:239]
	v_pk_fma_f32 v[188:189], v[118:119], v[240:241], v[188:189]
	v_add_f32_e32 v201, 1.0, v201
	v_pk_fma_f32 v[190:191], v[122:123], v[240:241], v[190:191]
	v_add_f32_e32 v246, v188, v189
	v_add_f32_e32 v247, v190, v191
	v_rcp_f32_e32 v220, v201
	ds_write_b64 v159, v[246:247] offset:58368
	ds_read_b128 v[192:195], v124 offset:52224
	ds_read_b128 v[196:199], v124 offset:52240
	v_add_f32_e32 v201, 1.0, v205
	s_mul_i32 s20, s26, -1
	s_add_i32 s20, s20, 8
	v_rcp_f32_e32 v221, v201
	s_add_i32 s20, s20, s27
	s_add_i32 s20, s20, s100
	s_mulk_i32 s20, 0x600
	v_mul_f32_e32 v110, 0xbf1b459e, v110
	s_waitcnt lgkmcnt(0)
	v_pk_add_f32 v[192:193], v[192:193], v[194:195]
	v_pk_add_f32 v[196:197], v[196:197], v[198:199]
	v_mul_f32_e32 v110, 0x3fb8aa3b, v110
	v_add_u32_e32 v125, s20, v200
	v_pk_add_f32 v[192:193], v[192:193], v[196:197]
	s_nop 1
	v_exp_f32_e32 v205, v110
	v_add_f32_dpp v192, v192, v192 quad_perm:[1,0,3,2] row_mask:0xf bank_mask:0xf bound_ctrl:1
	v_add_f32_dpp v193, v193, v193 quad_perm:[1,0,3,2] row_mask:0xf bank_mask:0xf bound_ctrl:1
	v_pk_add_f32 v[206:207], v[218:219], -1.0 op_sel_hi:[1,0]
	s_nop 0
	v_add_f32_dpp v192, v192, v192 quad_perm:[2,3,0,1] row_mask:0xf bank_mask:0xf bound_ctrl:1
	v_add_f32_dpp v193, v193, v193 quad_perm:[2,3,0,1] row_mask:0xf bank_mask:0xf bound_ctrl:1
	v_pk_add_f32 v[208:209], v[220:221], -1.0 op_sel_hi:[1,0]
	global_store_dwordx2 v125, v[192:193], s[98:99]
	ds_read_b128 v[226:229], v244 offset:7888
	ds_read_b128 v[222:225], v244 offset:3536
	v_pk_fma_f32 v[206:207], v[58:59], v[206:207], 1.0 op_sel_hi:[1,1,0]
	ds_read_b128 v[234:237], v244 offset:16592
	ds_read_b128 v[230:233], v244 offset:12240
	v_pk_fma_f32 v[208:209], v[60:61], v[208:209], 1.0 op_sel_hi:[1,1,0]
	ds_read_b128 v[238:241], v244 offset:20944
	ds_read_b64 v[242:243], v245 offset:25296
	v_pk_mul_f32 v[128:129], v[116:117], v[164:165]
	v_pk_mul_f32 v[130:131], v[120:121], v[164:165]
	v_pk_fma_f32 v[128:129], v[118:119], v[166:167], v[128:129]
	v_pk_mul_f32 v[206:207], v[210:211], v[206:207]
	v_pk_fma_f32 v[130:131], v[122:123], v[166:167], v[130:131]
	v_pk_mul_f32 v[136:137], v[172:173], v[180:181] op_sel_hi:[1,0]
	v_pk_mul_f32 v[182:183], v[174:175], v[180:181] op_sel_hi:[1,0]
	v_pk_mul_f32 v[208:209], v[212:213], v[208:209]
	v_add_f32_e32 v132, v128, v129
	v_add_f32_e32 v134, v130, v131
	v_pk_mul_f32 v[184:185], v[172:173], v[180:181] op_sel:[0,1]
	v_pk_mul_f32 v[186:187], v[174:175], v[180:181] op_sel:[0,1]
	v_add_f32_dpp v132, v132, v132 quad_perm:[1,0,3,2] row_mask:0xf bank_mask:0xf bound_ctrl:1
	v_pk_mul_f32 v[210:211], v[214:215], v[218:219]
	v_add_f32_dpp v134, v134, v134 quad_perm:[1,0,3,2] row_mask:0xf bank_mask:0xf bound_ctrl:1
	v_pk_fma_f32 v[136:137], v[116:117], v[160:161], v[136:137]
	v_add_f32_dpp v132, v132, v132 quad_perm:[2,3,0,1] row_mask:0xf bank_mask:0xf bound_ctrl:1
	v_pk_mul_f32 v[212:213], v[216:217], v[220:221]
	v_add_f32_dpp v134, v134, v134 quad_perm:[2,3,0,1] row_mask:0xf bank_mask:0xf bound_ctrl:1
	v_pk_fma_f32 v[182:183], v[118:119], v[162:163], v[182:183]
	ds_write_b128 v97, v[202:205]
	v_add_f32_dpp v132, v132, v132 row_half_mirror row_mask:0xf bank_mask:0xf bound_ctrl:1
	v_add_f32_dpp v134, v134, v134 row_half_mirror row_mask:0xf bank_mask:0xf bound_ctrl:1
	v_pk_fma_f32 v[184:185], v[120:121], v[160:161], v[184:185]
	ds_write_b128 v97, v[206:209] offset:13056
	v_add_f32_dpp v132, v132, v132 row_mirror row_mask:0xf bank_mask:0xf bound_ctrl:1
	v_add_f32_dpp v134, v134, v134 row_mirror row_mask:0xf bank_mask:0xf bound_ctrl:1
	v_pk_fma_f32 v[186:187], v[122:123], v[162:163], v[186:187]
	ds_write_b128 v97, v[210:213] offset:8704
	v_pk_fma_f32 v[116:117], v[168:169], v[132:133], v[136:137] op_sel_hi:[1,0,1] neg_lo:[1,0,0] neg_hi:[1,0,0]
	v_pk_fma_f32 v[118:119], v[170:171], v[132:133], v[182:183] op_sel_hi:[1,0,1] neg_lo:[1,0,0] neg_hi:[1,0,0]
	v_pk_fma_f32 v[120:121], v[168:169], v[134:135], v[184:185] op_sel_hi:[1,0,1] neg_lo:[1,0,0] neg_hi:[1,0,0]
	s_waitcnt lgkmcnt(0)
	s_barrier
; DI float red16(float x) { x = red8(x); x += dppf<0x140>(x); return x; }
; DI void scan_task(const Params& p, int l, int b, int h, int dir, int half, char* lds) {
;     ...
;     {
;       const f32x4 rv = *(const f32x4*)(cb + VR * CP + st_p * CS + c4 * 4);
;       const f32x4 kdv = *(const f32x4*)(cb + VKD * CP + st_p * CS + c4 * 4);
;       float bs = rv[0] * kdv[0] * rkg[0] + rv[1] * kdv[1] * rkg[1] + rv[2] * kdv[2] * rkg[2] + rv[3] * kdv[3] * rkg[3];
;       bs = red16(bs);
;       if (c4 == 0 && half == 0) p.BON[(size_t)dir * T_TOK * 6 + (size_t)(b * TB + slo + st_p) * 6 + h] = bs;
;     }
;     ...
;       for (int ii = 0; ii < 16; ++ii) {
;         f32x4 nw = cw, nkk = ckk, nbb = cbb, nkd = ckd, nrr = crr; f32x2 nvv = cvv;
;         if (ii < 15) {
;           ps += inc; pv += inc;
;           nw = *(const f32x4*)(ps + VW * CP); nkk = *(const f32x4*)(ps + VKK * CP); nbb = *(const f32x4*)(ps + VB * CP);
;           nkd = *(const f32x4*)(ps + VKD * CP); nrr = *(const f32x4*)(ps + VR * CP); nvv = *(const f32x2*)pv;
;         }
;         __builtin_amdgcn_sched_barrier(0x7);
;         const f32x2 kk0 = {ckk[0], ckk[1]}, kk1 = {ckk[2], ckk[3]}, w0 = {cw[0], cw[1]}, w1 = {cw[2], cw[3]};
;         const f32x2 b0 = {cbb[0], cbb[1]}, b1 = {cbb[2], cbb[3]}, kd0 = {ckd[0], ckd[1]}, kd1 = {ckd[2], ckd[3]};
;         const f32x2 r0 = {crr[0], crr[1]}, r1 = {crr[2], crr[3]};
;         const f32x2 p0 = S0[0] * kk0 + S0[1] * kk1, p1 = S1[0] * kk0 + S1[1] * kk1;
;         const f32x2 u00 = S0[0] * w0 + kd0 * cvv[0], u01 = S0[1] * w1 + kd1 * cvv[0];
;         const f32x2 u10 = S1[0] * w0 + kd0 * cvv[1], u11 = S1[1] * w1 + kd1 * cvv[1];
;         const float q0 = red16(p0[0] + p0[1]), q1 = red16(p1[0] + p1[1]);
;         S0[0] = u00 - b0 * q0; S0[1] = u01 - b1 * q0;
;         S1[0] = u10 - b0 * q1; S1[1] = u11 - b1 * q1;
;         const f32x2 y0 = S0[0] * r0 + S0[1] * r1, y1 = S1[0] * r0 + S1[1] * r1;
;         *(f32x2*)py = (f32x2){y0[0] + y0[1], y1[0] + y1[1]};
;         py += dir ? -512 : 512;
;         cw = nw; ckk = nkk; cbb = nbb; ckd = nkd; crr = nrr; cvv = nvv;
;       }
	v_pk_fma_f32 v[122:123], v[170:171], v[134:135], v[186:187] op_sel_hi:[1,0,1] neg_lo:[1,0,0] neg_hi:[1,0,0]
	v_pk_mul_f32 v[188:189], v[116:117], v[176:177]
	ds_read_b128 v[202:205], v100 offset:17408
	v_pk_mul_f32 v[190:191], v[120:121], v[176:177]
	v_pk_fma_f32 v[188:189], v[118:119], v[178:179], v[188:189]
	v_pk_fma_f32 v[190:191], v[122:123], v[178:179], v[190:191]
	ds_read_b128 v[206:209], v100 offset:13056
	v_add_f32_e32 v246, v188, v189
	v_add_f32_e32 v247, v190, v191
	ds_write_b64 v159, v[246:247] offset:52224
	s_waitcnt lgkmcnt(1)
	ds_read_b128 v[164:167], v244 offset:8160
	ds_read_b128 v[160:163], v244 offset:3808
	ds_read_b128 v[172:175], v244 offset:16864
	v_mul_f32_e32 v201, v203, v207
	ds_read_b128 v[168:171], v244 offset:12512
	ds_read_b128 v[176:179], v244 offset:21216
	v_mul_f32_e32 v110, v202, v206
	ds_read_b64 v[180:181], v245 offset:25568
	v_pk_mul_f32 v[128:129], v[116:117], v[226:227]
	v_mul_f32_e32 v201, v47, v201
	v_pk_mul_f32 v[130:131], v[120:121], v[226:227]
	v_pk_fma_f32 v[128:129], v[118:119], v[228:229], v[128:129]
	v_pk_fma_f32 v[130:131], v[122:123], v[228:229], v[130:131]
	v_fmac_f32_e32 v201, v46, v110
	v_pk_mul_f32 v[136:137], v[234:235], v[242:243] op_sel_hi:[1,0]
	v_pk_mul_f32 v[182:183], v[236:237], v[242:243] op_sel_hi:[1,0]
	v_mul_f32_e32 v110, v204, v208
	v_add_f32_e32 v132, v128, v129
	v_add_f32_e32 v134, v130, v131
	v_pk_mul_f32 v[184:185], v[234:235], v[242:243] op_sel:[0,1]
	v_fmac_f32_e32 v201, v48, v110
	v_pk_mul_f32 v[186:187], v[236:237], v[242:243] op_sel:[0,1]
	v_add_f32_dpp v132, v132, v132 quad_perm:[1,0,3,2] row_mask:0xf bank_mask:0xf bound_ctrl:1
	v_add_f32_dpp v134, v134, v134 quad_perm:[1,0,3,2] row_mask:0xf bank_mask:0xf bound_ctrl:1
	v_mul_f32_e32 v110, v205, v209
	v_pk_fma_f32 v[136:137], v[116:117], v[222:223], v[136:137]
	v_add_f32_dpp v132, v132, v132 quad_perm:[2,3,0,1] row_mask:0xf bank_mask:0xf bound_ctrl:1
	v_add_f32_dpp v134, v134, v134 quad_perm:[2,3,0,1] row_mask:0xf bank_mask:0xf bound_ctrl:1
	v_fmac_f32_e32 v201, v49, v110
	v_pk_fma_f32 v[182:183], v[118:119], v[224:225], v[182:183]
	v_add_f32_dpp v132, v132, v132 row_half_mirror row_mask:0xf bank_mask:0xf bound_ctrl:1
	s_nop 1
	v_add_f32_dpp v134, v134, v134 row_half_mirror row_mask:0xf bank_mask:0xf bound_ctrl:1
	v_pk_fma_f32 v[184:185], v[120:121], v[222:223], v[184:185]
	v_add_f32_dpp v132, v132, v132 row_mirror row_mask:0xf bank_mask:0xf bound_ctrl:1
	v_add_f32_dpp v110, v201, v201 quad_perm:[1,0,3,2] row_mask:0xf bank_mask:0xf bound_ctrl:1
	v_add_f32_dpp v134, v134, v134 row_mirror row_mask:0xf bank_mask:0xf bound_ctrl:1
	v_pk_fma_f32 v[186:187], v[122:123], v[224:225], v[186:187]
	v_pk_fma_f32 v[116:117], v[230:231], v[132:133], v[136:137] op_sel_hi:[1,0,1] neg_lo:[1,0,0] neg_hi:[1,0,0]
	s_nop 1
	v_pk_fma_f32 v[118:119], v[232:233], v[132:133], v[182:183] op_sel_hi:[1,0,1] neg_lo:[1,0,0] neg_hi:[1,0,0]
	v_pk_fma_f32 v[120:121], v[230:231], v[134:135], v[184:185] op_sel_hi:[1,0,1] neg_lo:[1,0,0] neg_hi:[1,0,0]
	v_add_f32_dpp v110, v110, v110 quad_perm:[2,3,0,1] row_mask:0xf bank_mask:0xf bound_ctrl:1
	v_pk_fma_f32 v[122:123], v[232:233], v[134:135], v[186:187] op_sel_hi:[1,0,1] neg_lo:[1,0,0] neg_hi:[1,0,0]
	v_pk_mul_f32 v[188:189], v[116:117], v[238:239]
	v_pk_mul_f32 v[190:191], v[120:121], v[238:239]
	s_nop 1
	v_pk_fma_f32 v[188:189], v[118:119], v[240:241], v[188:189]
	v_pk_fma_f32 v[190:191], v[122:123], v[240:241], v[190:191]
	v_add_f32_e32 v246, v188, v189
	v_add_f32_dpp v110, v110, v110 row_half_mirror row_mask:0xf bank_mask:0xf bound_ctrl:1
	v_add_f32_e32 v247, v190, v191
	ds_write_b64 v159, v[246:247] offset:54272
	ds_read_b128 v[226:229], v244 offset:8432
	s_nop 1
	ds_read_b128 v[222:225], v244 offset:4080
	ds_read_b128 v[234:237], v244 offset:17136
	v_mov_b32_dpp v201, v110 row_mirror row_mask:0xf bank_mask:0xf bound_ctrl:1
	ds_read_b128 v[230:233], v244 offset:12784
	ds_read_b128 v[238:241], v244 offset:21488
	ds_read_b64 v[242:243], v245 offset:25840
	s_mov_b32 s2, s29
	s_and_saveexec_b64 s[0:1], s[36:37]
	v_add_f32_e32 v110, v110, v201
	v_add_u32_e32 v201, s2, v126
	v_readlane_b32 s2, v252, 50
	v_readlane_b32 s3, v252, 51
	s_nop 1
	v_mad_i64_i32 v[202:203], s[2:3], v201, 24, s[2:3]
	global_store_dword v[202:203], v110, off
	s_or_b64 exec, exec, s[0:1]
	s_nop 1
	s_waitcnt lgkmcnt(7)
; DI void scan_task(const Params& p, int l, int b, int h, int dir, int half, char* lds) {
;     ...
;   for (int c = 0; c < NCH; ++c) {
;     if (c + 1 < NCH) issue_loads(c + 1);
;     {
;       const float* ps = cb + (dir ? 15 * CS : 0) + g * 4;
;       const float* pv = cb + VV * CP + (dir ? 15 * CS : 0) + rowl;
;       float* py = ybuf + (dir ? 15 * 512 : 0) + ((wid * 4 + rp) * 16 + g) * 2;
;       f32x4 cw = *(const f32x4*)(ps + VW * CP), ckk = *(const f32x4*)(ps + VKK * CP), cbb = *(const f32x4*)(ps + VB * CP),
;             ckd = *(const f32x4*)(ps + VKD * CP), crr = *(const f32x4*)(ps + VR * CP);
;       f32x2 cvv = *(const f32x2*)pv;
; #pragma unroll
;       for (int ii = 0; ii < 16; ++ii) {
;         f32x4 nw = cw, nkk = ckk, nbb = cbb, nkd = ckd, nrr = crr; f32x2 nvv = cvv;
;         if (ii < 15) {
;           ps += inc; pv += inc;
;           nw = *(const f32x4*)(ps + VW * CP); nkk = *(const f32x4*)(ps + VKK * CP); nbb = *(const f32x4*)(ps + VB * CP);
;           nkd = *(const f32x4*)(ps + VKD * CP); nrr = *(const f32x4*)(ps + VR * CP); nvv = *(const f32x2*)pv;
;         }
;         __builtin_amdgcn_sched_barrier(0x7);
;         const f32x2 kk0 = {ckk[0], ckk[1]}, kk1 = {ckk[2], ckk[3]}, w0 = {cw[0], cw[1]}, w1 = {cw[2], cw[3]};
;         const f32x2 b0 = {cbb[0], cbb[1]}, b1 = {cbb[2], cbb[3]}, kd0 = {ckd[0], ckd[1]}, kd1 = {ckd[2], ckd[3]};
;         const f32x2 r0 = {crr[0], crr[1]}, r1 = {crr[2], crr[3]};
;         const f32x2 p0 = S0[0] * kk0 + S0[1] * kk1, p1 = S1[0] * kk0 + S1[1] * kk1;
;         const f32x2 u00 = S0[0] * w0 + kd0 * cvv[0], u01 = S0[1] * w1 + kd1 * cvv[0];
;         const f32x2 u10 = S1[0] * w0 + kd0 * cvv[1], u11 = S1[1] * w1 + kd1 * cvv[1];
;         const float q0 = red16(p0[0] + p0[1]), q1 = red16(p1[0] + p1[1]);
;         S0[0] = u00 - b0 * q0; S0[1] = u01 - b1 * q0;
;         S1[0] = u10 - b0 * q1; S1[1] = u11 - b1 * q1;
;         const f32x2 y0 = S0[0] * r0 + S0[1] * r1, y1 = S1[0] * r0 + S1[1] * r1;
;         *(f32x2*)py = (f32x2){y0[0] + y0[1], y1[0] + y1[1]};
;         py += dir ? -512 : 512;
;         cw = nw; ckk = nkk; cbb = nbb; ckd = nkd; crr = nrr; cvv = nvv;
;       }
;     }
;     __syncthreads();
;     {
;       const int slo = chunk_lo(c);
;       const float* yp = ybuf + (st_p * 16 + c4) * 32;
;       f32x4 a = *(const f32x4*)(yp + 4 * (c4 & 7));
; #pragma unroll
	v_pk_mul_f32 v[128:129], v[116:117], v[164:165]
	v_pk_mul_f32 v[130:131], v[120:121], v[164:165]
	v_pk_fma_f32 v[128:129], v[118:119], v[166:167], v[128:129]
	v_pk_fma_f32 v[130:131], v[122:123], v[166:167], v[130:131]
	v_pk_mul_f32 v[136:137], v[172:173], v[180:181] op_sel_hi:[1,0]
	v_pk_mul_f32 v[182:183], v[174:175], v[180:181] op_sel_hi:[1,0]
	v_add_f32_e32 v132, v128, v129
	v_add_f32_e32 v134, v130, v131
	v_pk_mul_f32 v[184:185], v[172:173], v[180:181] op_sel:[0,1]
	v_pk_mul_f32 v[186:187], v[174:175], v[180:181] op_sel:[0,1]
	v_add_f32_dpp v132, v132, v132 quad_perm:[1,0,3,2] row_mask:0xf bank_mask:0xf bound_ctrl:1
	v_add_f32_dpp v134, v134, v134 quad_perm:[1,0,3,2] row_mask:0xf bank_mask:0xf bound_ctrl:1
	v_pk_fma_f32 v[136:137], v[116:117], v[160:161], v[136:137]
	v_add_f32_dpp v132, v132, v132 quad_perm:[2,3,0,1] row_mask:0xf bank_mask:0xf bound_ctrl:1
	v_add_f32_dpp v134, v134, v134 quad_perm:[2,3,0,1] row_mask:0xf bank_mask:0xf bound_ctrl:1
	v_pk_fma_f32 v[182:183], v[118:119], v[162:163], v[182:183]
	v_add_f32_dpp v132, v132, v132 row_half_mirror row_mask:0xf bank_mask:0xf bound_ctrl:1
	v_add_f32_dpp v134, v134, v134 row_half_mirror row_mask:0xf bank_mask:0xf bound_ctrl:1
	v_pk_fma_f32 v[184:185], v[120:121], v[160:161], v[184:185]
	v_add_f32_dpp v132, v132, v132 row_mirror row_mask:0xf bank_mask:0xf bound_ctrl:1
	v_add_f32_dpp v134, v134, v134 row_mirror row_mask:0xf bank_mask:0xf bound_ctrl:1
	v_pk_fma_f32 v[186:187], v[122:123], v[162:163], v[186:187]
	v_pk_fma_f32 v[116:117], v[168:169], v[132:133], v[136:137] op_sel_hi:[1,0,1] neg_lo:[1,0,0] neg_hi:[1,0,0]
	v_pk_fma_f32 v[118:119], v[170:171], v[132:133], v[182:183] op_sel_hi:[1,0,1] neg_lo:[1,0,0] neg_hi:[1,0,0]
	v_pk_fma_f32 v[120:121], v[168:169], v[134:135], v[184:185] op_sel_hi:[1,0,1] neg_lo:[1,0,0] neg_hi:[1,0,0]
	v_pk_fma_f32 v[122:123], v[170:171], v[134:135], v[186:187] op_sel_hi:[1,0,1] neg_lo:[1,0,0] neg_hi:[1,0,0]
	v_pk_mul_f32 v[188:189], v[116:117], v[176:177]
	v_pk_mul_f32 v[190:191], v[120:121], v[176:177]
	v_pk_fma_f32 v[188:189], v[118:119], v[178:179], v[188:189]
	v_pk_fma_f32 v[190:191], v[122:123], v[178:179], v[190:191]
	v_add_f32_e32 v246, v188, v189
	v_add_f32_e32 v247, v190, v191
	ds_write_b64 v159, v[246:247] offset:56320
	v_add_u32_e32 v244, s101, v244
	v_add_u32_e32 v245, s101, v245
	ds_read_b128 v[164:167], v244 offset:4352
	ds_read_b128 v[160:163], v244 offset:0
	ds_read_b128 v[172:175], v244 offset:13056
	ds_read_b128 v[168:171], v244 offset:8704
	ds_read_b128 v[176:179], v244 offset:17408
	ds_read_b64 v[180:181], v245 offset:21760
	s_waitcnt lgkmcnt(7)
	v_pk_mul_f32 v[128:129], v[116:117], v[226:227]
	v_pk_mul_f32 v[130:131], v[120:121], v[226:227]
	v_pk_fma_f32 v[128:129], v[118:119], v[228:229], v[128:129]
	v_pk_fma_f32 v[130:131], v[122:123], v[228:229], v[130:131]
	v_pk_mul_f32 v[136:137], v[234:235], v[242:243] op_sel_hi:[1,0]
	v_pk_mul_f32 v[182:183], v[236:237], v[242:243] op_sel_hi:[1,0]
	v_add_f32_e32 v132, v128, v129
	v_add_f32_e32 v134, v130, v131
	v_pk_mul_f32 v[184:185], v[234:235], v[242:243] op_sel:[0,1]
	v_pk_mul_f32 v[186:187], v[236:237], v[242:243] op_sel:[0,1]
	v_add_f32_dpp v132, v132, v132 quad_perm:[1,0,3,2] row_mask:0xf bank_mask:0xf bound_ctrl:1
	v_add_f32_dpp v134, v134, v134 quad_perm:[1,0,3,2] row_mask:0xf bank_mask:0xf bound_ctrl:1
	v_pk_fma_f32 v[136:137], v[116:117], v[222:223], v[136:137]
	v_add_f32_dpp v132, v132, v132 quad_perm:[2,3,0,1] row_mask:0xf bank_mask:0xf bound_ctrl:1
	v_add_f32_dpp v134, v134, v134 quad_perm:[2,3,0,1] row_mask:0xf bank_mask:0xf bound_ctrl:1
	v_pk_fma_f32 v[182:183], v[118:119], v[224:225], v[182:183]
	v_add_f32_dpp v132, v132, v132 row_half_mirror row_mask:0xf bank_mask:0xf bound_ctrl:1
	v_add_f32_dpp v134, v134, v134 row_half_mirror row_mask:0xf bank_mask:0xf bound_ctrl:1
	v_pk_fma_f32 v[184:185], v[120:121], v[222:223], v[184:185]
	v_add_f32_dpp v132, v132, v132 row_mirror row_mask:0xf bank_mask:0xf bound_ctrl:1
	v_add_f32_dpp v134, v134, v134 row_mirror row_mask:0xf bank_mask:0xf bound_ctrl:1
	v_pk_fma_f32 v[186:187], v[122:123], v[224:225], v[186:187]
	v_pk_fma_f32 v[116:117], v[230:231], v[132:133], v[136:137] op_sel_hi:[1,0,1] neg_lo:[1,0,0] neg_hi:[1,0,0]
	v_pk_fma_f32 v[118:119], v[232:233], v[132:133], v[182:183] op_sel_hi:[1,0,1] neg_lo:[1,0,0] neg_hi:[1,0,0]
	v_pk_fma_f32 v[120:121], v[230:231], v[134:135], v[184:185] op_sel_hi:[1,0,1] neg_lo:[1,0,0] neg_hi:[1,0,0]
	v_pk_fma_f32 v[122:123], v[232:233], v[134:135], v[186:187] op_sel_hi:[1,0,1] neg_lo:[1,0,0] neg_hi:[1,0,0]
	v_pk_mul_f32 v[188:189], v[116:117], v[238:239]
	v_pk_mul_f32 v[190:191], v[120:121], v[238:239]
	v_pk_fma_f32 v[188:189], v[118:119], v[240:241], v[188:189]
	v_pk_fma_f32 v[190:191], v[122:123], v[240:241], v[190:191]
	v_add_f32_e32 v246, v188, v189
	v_add_f32_e32 v247, v190, v191
	ds_write_b64 v159, v[246:247] offset:58368
	ds_read_b128 v[192:195], v124 offset:52224
	ds_read_b128 v[196:199], v124 offset:52240
	s_mul_i32 s20, s26, -9
	s_add_i32 s20, s20, 12
	s_add_i32 s20, s20, s27
	s_add_i32 s20, s20, s100
	s_mulk_i32 s20, 0x600
	s_waitcnt lgkmcnt(0)
	v_pk_add_f32 v[192:193], v[192:193], v[194:195]
	v_pk_add_f32 v[196:197], v[196:197], v[198:199]
	v_add_u32_e32 v125, s20, v200
	v_pk_add_f32 v[192:193], v[192:193], v[196:197]
	s_nop 1
	v_add_f32_dpp v192, v192, v192 quad_perm:[1,0,3,2] row_mask:0xf bank_mask:0xf bound_ctrl:1
	v_add_f32_dpp v193, v193, v193 quad_perm:[1,0,3,2] row_mask:0xf bank_mask:0xf bound_ctrl:1
	s_nop 0
	v_add_f32_dpp v192, v192, v192 quad_perm:[2,3,0,1] row_mask:0xf bank_mask:0xf bound_ctrl:1
	v_add_f32_dpp v193, v193, v193 quad_perm:[2,3,0,1] row_mask:0xf bank_mask:0xf bound_ctrl:1
	global_store_dwordx2 v125, v[192:193], s[98:99]
	s_barrier
	v_subrev_u32_e32 v100, s101, v100
	v_subrev_u32_e32 v97, s101, v97
	s_sub_i32 s101, 0, s101
	s_mov_b32 s100, s29
	s_mov_b32 s29, s28
	s_add_i32 s38, s38, 1
	s_cmpk_lg_i32 s38, 0x90
	s_cbranch_scc1 .Lscan_loop
	v_readlane_b32 s49, v250, 7
	s_nop 3
	s_branch .Lscan_joins_queue
.Ltramp_exit_mid:
	s_branch .LBB0_853
.Ltramp_latch_mid:
	s_branch .LBB0_7
.LBB0_440:
	s_mov_b64 s[0:1], 0

; DI void modnorm_rows(const Params& p, int l, int which  , bool from_inputs, bool skip_ctx, int w0, int wstride, int lane) {
;   const float* g = (which ? p.norm2_g : p.norm1_g) + l * DM;
;   f32x4 gg[4];
; #pragma unroll
;   for (int i = 0; i < 4; ++i) gg[i] = *(const f32x4*)(g + i * 256 + lane * 4);
;   const int nrows = skip_ctx ? 8 * NLAT : T_TOK;
;   auto rowof = [&](int i) -> int { return skip_ctx ? (i / NLAT) * TB + NCTX + (i % NLAT) : i; };
;   int i = w0;
;   if (i >= nrows) return;
;   f32x4 vn[4];
;   {
;     const int row = rowof(i); const float* src = xsrc_row(p, from_inputs, row / TB, row % TB);
; #pragma unroll
;     for (int q = 0; q < 4; ++q) vn[q] = *(const f32x4*)(src + q * 256 + lane * 4);
;   }
;   for (; i < nrows; i += wstride) {
;     const int row = rowof(i); const int b = row / TB, s = row % TB;
;     f32x4 v[4];
; #pragma unroll
;     for (int q = 0; q < 4; ++q) v[q] = vn[q];
;     if (i + wstride < nrows) {
;       const int rn = rowof(i + wstride); const float* src = xsrc_row(p, from_inputs, rn / TB, rn % TB);
; #pragma unroll
;       for (int q = 0; q < 4; ++q) vn[q] = *(const f32x4*)(src + q * 256 + lane * 4);
.LBB0_823:
	s_or_b64 exec, exec, s[0:1]
	v_readlane_b32 s0, v252, 9
	s_nop 1
	v_add_u32_e32 v50, s0, v158
	s_movk_i32 s0, 0x4800
	v_cmp_gt_i32_e32 vcc, s0, v50
	s_and_saveexec_b64 s[2:3], vcc
	s_cbranch_execz .LBB0_852
	v_readlane_b32 s0, v252, 9
	v_lshlrev_b32_e32 v244, 4, v115
	v_lshlrev_b32_e32 v245, 3, v115
	v_add_u32_e32 v1, s0, v158
	s_nop 1
	v_readfirstlane_b32 s20, v1
	v_readlane_b32 s4, v254, 40
	v_readlane_b32 s5, v254, 41
	v_readlane_b32 s12, v254, 28
	v_readlane_b32 s13, v254, 29
	v_readlane_b32 s14, v254, 32
	v_readlane_b32 s15, v254, 33
	v_readlane_b32 s16, v253, 40
	v_readlane_b32 s17, v253, 41
	v_readlane_b32 s18, v250, 4
	v_readlane_b32 s19, v250, 5
	s_nop 3
	s_lshl_b32 s0, s49, 12
	s_add_u32 s4, s4, s0
	s_addc_u32 s5, s5, 0
	global_load_dwordx4 v[2:5], v244, s[4:5]
	global_load_dwordx4 v[6:9], v244, s[4:5] offset:1024
	global_load_dwordx4 v[10:13], v244, s[4:5] offset:2048
	global_load_dwordx4 v[14:17], v244, s[4:5] offset:3072
	s_add_i32 s0, s77, 7
	s_cmp_gt_u32 s0, 16
	s_cselect_b32 s12, s56, s12
	s_cselect_b32 s13, s57, s13
	s_cselect_b32 s14, s64, s14
	s_cselect_b32 s15, s65, s15
	s_add_i32 s21, s20, 0
	s_mul_hi_u32 s7, s21, 0x38e38e39
	s_lshr_b32 s7, s7, 9
	s_mul_i32 s8, s7, 0x900
	s_sub_i32 s8, s21, s8
	s_lshl_b32 s9, s7, 11
	s_add_i32 s9, s9, s8
	s_add_i32 s9, s9, 0xffffff00
	s_lshl_b32 s10, s7, 8
	s_add_i32 s10, s10, s8
	s_cmpk_gt_i32 s8, 0xff
	s_cselect_b32 s9, s9, s10
	s_cselect_b32 s26, s12, s14
	s_cselect_b32 s27, s13, s15
	s_cselect_b32 s10, s7, 8
	s_lshl_b32 s9, s9, 12
	s_add_u32 s26, s26, s9
	s_addc_u32 s27, s27, 0
	s_add_i32 s10, s10, s82
	s_mul_i32 s10, s10, s24
	s_add_u32 s28, s58, s10
	s_addc_u32 s29, s59, 0
	s_add_u32 s28, s28, 0x0
	s_addc_u32 s29, s29, 0
	s_add_u32 s0, s28, 0x1000
	s_addc_u32 s1, s29, 0
	global_load_dwordx4 v[18:21], v244, s[26:27]
	global_load_dwordx4 v[22:25], v244, s[26:27] offset:1024
	global_load_dwordx4 v[26:29], v244, s[26:27] offset:2048
	global_load_dwordx4 v[30:33], v244, s[26:27] offset:3072
	global_load_dwordx4 v[34:37], v244, s[28:29]
	global_load_dwordx4 v[38:41], v244, s[28:29] offset:1024
	global_load_dwordx4 v[42:45], v244, s[28:29] offset:2048
	global_load_dwordx4 v[46:49], v244, s[28:29] offset:3072
	global_load_dwordx4 v[50:53], v244, s[0:1]
	global_load_dwordx4 v[54:57], v244, s[0:1] offset:1024
	global_load_dwordx4 v[58:61], v244, s[0:1] offset:2048
	global_load_dwordx4 v[62:65], v244, s[0:1] offset:3072
	s_add_i32 s21, s20, 2048
	s_mul_hi_u32 s7, s21, 0x38e38e39
	s_lshr_b32 s7, s7, 9
	s_mul_i32 s8, s7, 0x900
	s_sub_i32 s8, s21, s8
	s_lshl_b32 s9, s7, 11
	s_add_i32 s9, s9, s8
	s_add_i32 s9, s9, 0xffffff00
	s_lshl_b32 s10, s7, 8
	s_add_i32 s10, s10, s8
	s_cmpk_gt_i32 s8, 0xff
	s_cselect_b32 s9, s9, s10
	s_cselect_b32 s26, s12, s14
	s_cselect_b32 s27, s13, s15
	s_cselect_b32 s10, s7, 8
	s_lshl_b32 s9, s9, 12
	s_add_u32 s26, s26, s9
	s_addc_u32 s27, s27, 0
	s_add_i32 s10, s10, s82
	s_mul_i32 s10, s10, s24
	s_add_u32 s28, s58, s10
	s_addc_u32 s29, s59, 0
	s_add_u32 s28, s28, 0x0
	s_addc_u32 s29, s29, 0
	s_add_u32 s0, s28, 0x1000
	s_addc_u32 s1, s29, 0
	global_load_dwordx4 v[66:69], v244, s[26:27]
	global_load_dwordx4 v[70:73], v244, s[26:27] offset:1024
	global_load_dwordx4 v[74:77], v244, s[26:27] offset:2048
	global_load_dwordx4 v[78:81], v244, s[26:27] offset:3072
	global_load_dwordx4 v[82:85], v244, s[28:29]
	global_load_dwordx4 v[86:89], v244, s[28:29] offset:1024
	global_load_dwordx4 v[90:93], v244, s[28:29] offset:2048
	global_load_dwordx4 v[94:97], v244, s[28:29] offset:3072
	global_load_dwordx4 v[98:101], v244, s[0:1]
	global_load_dwordx4 v[102:105], v244, s[0:1] offset:1024
	global_load_dwordx4 v[106:109], v244, s[0:1] offset:2048
	global_load_dwordx4 v[118:121], v244, s[0:1] offset:3072
	s_add_i32 s21, s20, 4096
	s_mul_hi_u32 s7, s21, 0x38e38e39
	s_lshr_b32 s7, s7, 9
	s_mul_i32 s8, s7, 0x900
	s_sub_i32 s8, s21, s8
	s_lshl_b32 s9, s7, 11
	s_add_i32 s9, s9, s8
	s_add_i32 s9, s9, 0xffffff00
	s_lshl_b32 s10, s7, 8
	s_add_i32 s10, s10, s8
	s_cmpk_gt_i32 s8, 0xff
	s_cselect_b32 s9, s9, s10
	s_cselect_b32 s26, s12, s14
	s_cselect_b32 s27, s13, s15
	s_cselect_b32 s10, s7, 8
	s_lshl_b32 s9, s9, 12
	s_add_u32 s26, s26, s9
	s_addc_u32 s27, s27, 0
	s_add_i32 s10, s10, s82
	s_mul_i32 s10, s10, s24
	s_add_u32 s28, s58, s10
	s_addc_u32 s29, s59, 0
	s_add_u32 s28, s28, 0x0
	s_addc_u32 s29, s29, 0
	s_add_u32 s0, s28, 0x1000
	s_addc_u32 s1, s29, 0
	global_load_dwordx4 v[122:125], v244, s[26:27]
	global_load_dwordx4 v[126:129], v244, s[26:27] offset:1024
	global_load_dwordx4 v[130:133], v244, s[26:27] offset:2048
	global_load_dwordx4 v[134:137], v244, s[26:27] offset:3072
	global_load_dwordx4 v[160:163], v244, s[28:29]
	global_load_dwordx4 v[164:167], v244, s[28:29] offset:1024
	global_load_dwordx4 v[168:171], v244, s[28:29] offset:2048
	global_load_dwordx4 v[172:175], v244, s[28:29] offset:3072
	global_load_dwordx4 v[176:179], v244, s[0:1]
	global_load_dwordx4 v[180:183], v244, s[0:1] offset:1024
	global_load_dwordx4 v[184:187], v244, s[0:1] offset:2048
	global_load_dwordx4 v[188:191], v244, s[0:1] offset:3072
	s_waitcnt vmcnt(24)
; DI unsigned pk_bf16(float lo, float hi) { f32x2 v = {lo, hi}; bf16v2 b = __builtin_convertvector(v, bf16v2); return __builtin_bit_cast(unsigned, b); }
; DI float red64(float x) { for (int o = 32; o > 0; o >>= 1) x += __shfl_xor(x, o); return x; }
; DI void modnorm_rows(const Params& p, int l, int which  , bool from_inputs, bool skip_ctx, int w0, int wstride, int lane) {
;     ...
;   for (; i < nrows; i += wstride) {
;     const int row = rowof(i); const int b = row / TB, s = row % TB;
;     f32x4 v[4];
; #pragma unroll
;     for (int q = 0; q < 4; ++q) v[q] = vn[q];
;     if (i + wstride < nrows) {
;       const int rn = rowof(i + wstride); const float* src = xsrc_row(p, from_inputs, rn / TB, rn % TB);
; #pragma unroll
;       for (int q = 0; q < 4; ++q) vn[q] = *(const f32x4*)(src + q * 256 + lane * 4);
;     }
;     const float* mod = p.MOD + (size_t)(l * 9 + (s < NCTX ? 8 : b)) * 6144 + (which ? 3 * 1024 : 0);
;     f32x4 sh[4], sc[4];
; #pragma unroll
;     for (int q = 0; q < 4; ++q) { sh[q] = *(const f32x4*)(mod + q * 256 + lane * 4); sc[q] = *(const f32x4*)(mod + 1024 + q * 256 + lane * 4); }
;     float ss = 0.f;
; #pragma unroll
;     for (int q = 0; q < 4; ++q) ss += v[q][0] * v[q][0] + v[q][1] * v[q][1] + v[q][2] * v[q][2] + v[q][3] * v[q][3];
;     ss = red64(ss);
;     const float rs = rsqrtf(ss * (1.f / 1024.f) + EPSF);
;     bf16_t* dst = p.HY + (size_t)row * DM;
; #pragma unroll
;     for (int q = 0; q < 4; ++q) {
;       float o[4];
; #pragma unroll
;       for (int j = 0; j < 4; ++j) o[j] = (v[q][j] * rs * gg[q][j]) * (1.f + sc[q][j]) + sh[q][j];
;       u32x2 w = {pk_bf16(o[0], o[1]), pk_bf16(o[2], o[3])};
;       *(u32x2*)(dst + q * 256 + lane * 4) = w;
;     }
;   }
	v_pk_mul_f32 v[246:247], v[18:19], v[18:19]
	v_pk_fma_f32 v[246:247], v[20:21], v[20:21], v[246:247]
	v_pk_fma_f32 v[246:247], v[22:23], v[22:23], v[246:247]
	v_pk_fma_f32 v[246:247], v[24:25], v[24:25], v[246:247]
	v_pk_fma_f32 v[246:247], v[26:27], v[26:27], v[246:247]
	v_pk_fma_f32 v[246:247], v[28:29], v[28:29], v[246:247]
	v_pk_fma_f32 v[246:247], v[30:31], v[30:31], v[246:247]
	v_pk_fma_f32 v[246:247], v[32:33], v[32:33], v[246:247]
	s_nop 0
	v_add_f32_e32 v246, v246, v247
	s_nop 1
	v_add_f32_dpp v246, v246, v246 quad_perm:[1,0,3,2] row_mask:0xf bank_mask:0xf
	s_nop 1
	v_add_f32_dpp v246, v246, v246 quad_perm:[2,3,0,1] row_mask:0xf bank_mask:0xf
	s_nop 1
	v_add_f32_dpp v246, v246, v246 row_half_mirror row_mask:0xf bank_mask:0xf
	s_nop 1
	v_add_f32_dpp v246, v246, v246 row_mirror row_mask:0xf bank_mask:0xf
	s_nop 1
	v_add_f32_dpp v246, v246, v246 row_bcast:15 row_mask:0xa bank_mask:0xf
	s_nop 1
	v_add_f32_dpp v246, v246, v246 row_bcast:31 row_mask:0xc bank_mask:0xf
	s_nop 1
	v_readlane_b32 s0, v246, 63
	s_add_i32 s21, s20, 0
	s_lshl_b32 s21, s21, 11
	s_add_u32 s10, s16, s21
	s_addc_u32 s11, s17, 0
	v_mov_b32_e32 v248, s0
	v_fmamk_f32 v248, v248, 0x3a800000, v143
	v_rsq_f32_e32 v248, v248
	s_nop 0
	v_pk_mul_f32 v[18:19], v[18:19], v[248:249] op_sel_hi:[1,0]
	v_pk_add_f32 v[50:51], v[50:51], 1.0 op_sel_hi:[1,0]
	v_pk_mul_f32 v[18:19], v[2:3], v[18:19]
	v_pk_fma_f32 v[18:19], v[50:51], v[18:19], v[34:35]
	v_pk_mul_f32 v[20:21], v[20:21], v[248:249] op_sel_hi:[1,0]
	v_pk_add_f32 v[52:53], v[52:53], 1.0 op_sel_hi:[1,0]
	v_pk_mul_f32 v[20:21], v[4:5], v[20:21]
	v_pk_fma_f32 v[20:21], v[52:53], v[20:21], v[36:37]
	v_cvt_pk_bf16_f32 v34, v18, v19
	v_cvt_pk_bf16_f32 v35, v20, v21
	global_store_dwordx2 v245, v[34:35], s[10:11]
	v_pk_mul_f32 v[22:23], v[22:23], v[248:249] op_sel_hi:[1,0]
	v_pk_add_f32 v[54:55], v[54:55], 1.0 op_sel_hi:[1,0]
	v_pk_mul_f32 v[22:23], v[6:7], v[22:23]
	v_pk_fma_f32 v[22:23], v[54:55], v[22:23], v[38:39]
	v_pk_mul_f32 v[24:25], v[24:25], v[248:249] op_sel_hi:[1,0]
	v_pk_add_f32 v[56:57], v[56:57], 1.0 op_sel_hi:[1,0]
	v_pk_mul_f32 v[24:25], v[8:9], v[24:25]
	v_pk_fma_f32 v[24:25], v[56:57], v[24:25], v[40:41]
	v_cvt_pk_bf16_f32 v38, v22, v23
	v_cvt_pk_bf16_f32 v39, v24, v25
	global_store_dwordx2 v245, v[38:39], s[10:11] offset:512
	v_pk_mul_f32 v[26:27], v[26:27], v[248:249] op_sel_hi:[1,0]
	v_pk_add_f32 v[58:59], v[58:59], 1.0 op_sel_hi:[1,0]
	v_pk_mul_f32 v[26:27], v[10:11], v[26:27]
	v_pk_fma_f32 v[26:27], v[58:59], v[26:27], v[42:43]
	v_pk_mul_f32 v[28:29], v[28:29], v[248:249] op_sel_hi:[1,0]
	v_pk_add_f32 v[60:61], v[60:61], 1.0 op_sel_hi:[1,0]
	v_pk_mul_f32 v[28:29], v[12:13], v[28:29]
	v_pk_fma_f32 v[28:29], v[60:61], v[28:29], v[44:45]
	v_cvt_pk_bf16_f32 v42, v26, v27
	v_cvt_pk_bf16_f32 v43, v28, v29
	global_store_dwordx2 v245, v[42:43], s[10:11] offset:1024
	v_pk_mul_f32 v[30:31], v[30:31], v[248:249] op_sel_hi:[1,0]
	v_pk_add_f32 v[62:63], v[62:63], 1.0 op_sel_hi:[1,0]
	v_pk_mul_f32 v[30:31], v[14:15], v[30:31]
	v_pk_fma_f32 v[30:31], v[62:63], v[30:31], v[46:47]
	v_pk_mul_f32 v[32:33], v[32:33], v[248:249] op_sel_hi:[1,0]
	v_pk_add_f32 v[64:65], v[64:65], 1.0 op_sel_hi:[1,0]
	v_pk_mul_f32 v[32:33], v[16:17], v[32:33]
	v_pk_fma_f32 v[32:33], v[64:65], v[32:33], v[48:49]
	v_cvt_pk_bf16_f32 v46, v30, v31
	v_cvt_pk_bf16_f32 v47, v32, v33
	global_store_dwordx2 v245, v[46:47], s[10:11] offset:1536
	s_add_i32 s21, s20, 6144
	s_mul_hi_u32 s7, s21, 0x38e38e39
	s_lshr_b32 s7, s7, 9
	s_mul_i32 s8, s7, 0x900
	s_sub_i32 s8, s21, s8
	s_lshl_b32 s9, s7, 11
	s_add_i32 s9, s9, s8
	s_add_i32 s9, s9, 0xffffff00
	s_lshl_b32 s10, s7, 8
	s_add_i32 s10, s10, s8
	s_cmpk_gt_i32 s8, 0xff
	s_cselect_b32 s9, s9, s10
	s_cselect_b32 s26, s12, s14
	s_cselect_b32 s27, s13, s15
	s_cselect_b32 s10, s7, 8
	s_lshl_b32 s9, s9, 12
	s_add_u32 s26, s26, s9
	s_addc_u32 s27, s27, 0
	s_add_i32 s10, s10, s82
	s_mul_i32 s10, s10, s24
	s_add_u32 s28, s58, s10
	s_addc_u32 s29, s59, 0
	s_add_u32 s28, s28, 0x0
	s_addc_u32 s29, s29, 0
	s_add_u32 s0, s28, 0x1000
	s_addc_u32 s1, s29, 0
	global_load_dwordx4 v[18:21], v244, s[26:27]
	global_load_dwordx4 v[22:25], v244, s[26:27] offset:1024
	global_load_dwordx4 v[26:29], v244, s[26:27] offset:2048
	global_load_dwordx4 v[30:33], v244, s[26:27] offset:3072
	global_load_dwordx4 v[34:37], v244, s[28:29]
	global_load_dwordx4 v[38:41], v244, s[28:29] offset:1024
	global_load_dwordx4 v[42:45], v244, s[28:29] offset:2048
	global_load_dwordx4 v[46:49], v244, s[28:29] offset:3072
	global_load_dwordx4 v[50:53], v244, s[0:1]
	global_load_dwordx4 v[54:57], v244, s[0:1] offset:1024
	global_load_dwordx4 v[58:61], v244, s[0:1] offset:2048
	global_load_dwordx4 v[62:65], v244, s[0:1] offset:3072
	s_waitcnt vmcnt(28)
; DI unsigned pk_bf16(float lo, float hi) { f32x2 v = {lo, hi}; bf16v2 b = __builtin_convertvector(v, bf16v2); return __builtin_bit_cast(unsigned, b); }
; DI float red64(float x) { for (int o = 32; o > 0; o >>= 1) x += __shfl_xor(x, o); return x; }
; DI void modnorm_rows(const Params& p, int l, int which  , bool from_inputs, bool skip_ctx, int w0, int wstride, int lane) {
;     ...
;   for (; i < nrows; i += wstride) {
;     const int row = rowof(i); const int b = row / TB, s = row % TB;
;     f32x4 v[4];
; #pragma unroll
;     for (int q = 0; q < 4; ++q) v[q] = vn[q];
;     if (i + wstride < nrows) {
;       const int rn = rowof(i + wstride); const float* src = xsrc_row(p, from_inputs, rn / TB, rn % TB);
; #pragma unroll
;       for (int q = 0; q < 4; ++q) vn[q] = *(const f32x4*)(src + q * 256 + lane * 4);
;     }
;     const float* mod = p.MOD + (size_t)(l * 9 + (s < NCTX ? 8 : b)) * 6144 + (which ? 3 * 1024 : 0);
;     f32x4 sh[4], sc[4];
; #pragma unroll
;     for (int q = 0; q < 4; ++q) { sh[q] = *(const f32x4*)(mod + q * 256 + lane * 4); sc[q] = *(const f32x4*)(mod + 1024 + q * 256 + lane * 4); }
;     float ss = 0.f;
; #pragma unroll
;     for (int q = 0; q < 4; ++q) ss += v[q][0] * v[q][0] + v[q][1] * v[q][1] + v[q][2] * v[q][2] + v[q][3] * v[q][3];
;     ss = red64(ss);
;     const float rs = rsqrtf(ss * (1.f / 1024.f) + EPSF);
;     bf16_t* dst = p.HY + (size_t)row * DM;
; #pragma unroll
;     for (int q = 0; q < 4; ++q) {
;       float o[4];
; #pragma unroll
;       for (int j = 0; j < 4; ++j) o[j] = (v[q][j] * rs * gg[q][j]) * (1.f + sc[q][j]) + sh[q][j];
;       u32x2 w = {pk_bf16(o[0], o[1]), pk_bf16(o[2], o[3])};
;       *(u32x2*)(dst + q * 256 + lane * 4) = w;
;     }
;   }
	v_pk_mul_f32 v[246:247], v[66:67], v[66:67]
	v_pk_fma_f32 v[246:247], v[68:69], v[68:69], v[246:247]
	v_pk_fma_f32 v[246:247], v[70:71], v[70:71], v[246:247]
	v_pk_fma_f32 v[246:247], v[72:73], v[72:73], v[246:247]
	v_pk_fma_f32 v[246:247], v[74:75], v[74:75], v[246:247]
	v_pk_fma_f32 v[246:247], v[76:77], v[76:77], v[246:247]
	v_pk_fma_f32 v[246:247], v[78:79], v[78:79], v[246:247]
	v_pk_fma_f32 v[246:247], v[80:81], v[80:81], v[246:247]
	s_nop 0
	v_add_f32_e32 v246, v246, v247
	s_nop 1
	v_add_f32_dpp v246, v246, v246 quad_perm:[1,0,3,2] row_mask:0xf bank_mask:0xf
	s_nop 1
	v_add_f32_dpp v246, v246, v246 quad_perm:[2,3,0,1] row_mask:0xf bank_mask:0xf
	s_nop 1
	v_add_f32_dpp v246, v246, v246 row_half_mirror row_mask:0xf bank_mask:0xf
	s_nop 1
	v_add_f32_dpp v246, v246, v246 row_mirror row_mask:0xf bank_mask:0xf
	s_nop 1
	v_add_f32_dpp v246, v246, v246 row_bcast:15 row_mask:0xa bank_mask:0xf
	s_nop 1
	v_add_f32_dpp v246, v246, v246 row_bcast:31 row_mask:0xc bank_mask:0xf
	s_nop 1
	v_readlane_b32 s0, v246, 63
	s_add_i32 s21, s20, 2048
	s_lshl_b32 s21, s21, 11
	s_add_u32 s10, s16, s21
	s_addc_u32 s11, s17, 0
	v_mov_b32_e32 v248, s0
	v_fmamk_f32 v248, v248, 0x3a800000, v143
	v_rsq_f32_e32 v248, v248
	s_nop 0
	v_pk_mul_f32 v[66:67], v[66:67], v[248:249] op_sel_hi:[1,0]
	v_pk_add_f32 v[98:99], v[98:99], 1.0 op_sel_hi:[1,0]
	v_pk_mul_f32 v[66:67], v[2:3], v[66:67]
	v_pk_fma_f32 v[66:67], v[98:99], v[66:67], v[82:83]
	v_pk_mul_f32 v[68:69], v[68:69], v[248:249] op_sel_hi:[1,0]
	v_pk_add_f32 v[100:101], v[100:101], 1.0 op_sel_hi:[1,0]
	v_pk_mul_f32 v[68:69], v[4:5], v[68:69]
	v_pk_fma_f32 v[68:69], v[100:101], v[68:69], v[84:85]
	v_cvt_pk_bf16_f32 v82, v66, v67
	v_cvt_pk_bf16_f32 v83, v68, v69
	global_store_dwordx2 v245, v[82:83], s[10:11]
	v_pk_mul_f32 v[70:71], v[70:71], v[248:249] op_sel_hi:[1,0]
	v_pk_add_f32 v[102:103], v[102:103], 1.0 op_sel_hi:[1,0]
	v_pk_mul_f32 v[70:71], v[6:7], v[70:71]
	v_pk_fma_f32 v[70:71], v[102:103], v[70:71], v[86:87]
	v_pk_mul_f32 v[72:73], v[72:73], v[248:249] op_sel_hi:[1,0]
	v_pk_add_f32 v[104:105], v[104:105], 1.0 op_sel_hi:[1,0]
	v_pk_mul_f32 v[72:73], v[8:9], v[72:73]
	v_pk_fma_f32 v[72:73], v[104:105], v[72:73], v[88:89]
	v_cvt_pk_bf16_f32 v86, v70, v71
	v_cvt_pk_bf16_f32 v87, v72, v73
	global_store_dwordx2 v245, v[86:87], s[10:11] offset:512
	v_pk_mul_f32 v[74:75], v[74:75], v[248:249] op_sel_hi:[1,0]
	v_pk_add_f32 v[106:107], v[106:107], 1.0 op_sel_hi:[1,0]
	v_pk_mul_f32 v[74:75], v[10:11], v[74:75]
	v_pk_fma_f32 v[74:75], v[106:107], v[74:75], v[90:91]
	v_pk_mul_f32 v[76:77], v[76:77], v[248:249] op_sel_hi:[1,0]
	v_pk_add_f32 v[108:109], v[108:109], 1.0 op_sel_hi:[1,0]
	v_pk_mul_f32 v[76:77], v[12:13], v[76:77]
	v_pk_fma_f32 v[76:77], v[108:109], v[76:77], v[92:93]
	v_cvt_pk_bf16_f32 v90, v74, v75
	v_cvt_pk_bf16_f32 v91, v76, v77
	global_store_dwordx2 v245, v[90:91], s[10:11] offset:1024
	v_pk_mul_f32 v[78:79], v[78:79], v[248:249] op_sel_hi:[1,0]
	v_pk_add_f32 v[118:119], v[118:119], 1.0 op_sel_hi:[1,0]
	v_pk_mul_f32 v[78:79], v[14:15], v[78:79]
	v_pk_fma_f32 v[78:79], v[118:119], v[78:79], v[94:95]
	v_pk_mul_f32 v[80:81], v[80:81], v[248:249] op_sel_hi:[1,0]
	v_pk_add_f32 v[120:121], v[120:121], 1.0 op_sel_hi:[1,0]
	v_pk_mul_f32 v[80:81], v[16:17], v[80:81]
	v_pk_fma_f32 v[80:81], v[120:121], v[80:81], v[96:97]
	v_cvt_pk_bf16_f32 v94, v78, v79
	v_cvt_pk_bf16_f32 v95, v80, v81
	global_store_dwordx2 v245, v[94:95], s[10:11] offset:1536
	s_add_i32 s21, s20, 8192
	s_mul_hi_u32 s7, s21, 0x38e38e39
	s_lshr_b32 s7, s7, 9
	s_mul_i32 s8, s7, 0x900
	s_sub_i32 s8, s21, s8
	s_lshl_b32 s9, s7, 11
	s_add_i32 s9, s9, s8
	s_add_i32 s9, s9, 0xffffff00
	s_lshl_b32 s10, s7, 8
	s_add_i32 s10, s10, s8
	s_cmpk_gt_i32 s8, 0xff
	s_cselect_b32 s9, s9, s10
	s_cselect_b32 s26, s12, s14
	s_cselect_b32 s27, s13, s15
	s_cselect_b32 s10, s7, 8
	s_lshl_b32 s9, s9, 12
	s_add_u32 s26, s26, s9
	s_addc_u32 s27, s27, 0
	s_add_i32 s10, s10, s82
	s_mul_i32 s10, s10, s24
	s_add_u32 s28, s58, s10
	s_addc_u32 s29, s59, 0
	s_add_u32 s28, s28, 0x0
	s_addc_u32 s29, s29, 0
	s_add_u32 s0, s28, 0x1000
	s_addc_u32 s1, s29, 0
	global_load_dwordx4 v[66:69], v244, s[26:27]
	global_load_dwordx4 v[70:73], v244, s[26:27] offset:1024
	global_load_dwordx4 v[74:77], v244, s[26:27] offset:2048
	global_load_dwordx4 v[78:81], v244, s[26:27] offset:3072
	global_load_dwordx4 v[82:85], v244, s[28:29]
	global_load_dwordx4 v[86:89], v244, s[28:29] offset:1024
	global_load_dwordx4 v[90:93], v244, s[28:29] offset:2048
	global_load_dwordx4 v[94:97], v244, s[28:29] offset:3072
	global_load_dwordx4 v[98:101], v244, s[0:1]
	global_load_dwordx4 v[102:105], v244, s[0:1] offset:1024
	global_load_dwordx4 v[106:109], v244, s[0:1] offset:2048
	global_load_dwordx4 v[118:121], v244, s[0:1] offset:3072
	s_waitcnt vmcnt(32)
; DI unsigned pk_bf16(float lo, float hi) { f32x2 v = {lo, hi}; bf16v2 b = __builtin_convertvector(v, bf16v2); return __builtin_bit_cast(unsigned, b); }
; DI float red64(float x) { for (int o = 32; o > 0; o >>= 1) x += __shfl_xor(x, o); return x; }
; DI void modnorm_rows(const Params& p, int l, int which  , bool from_inputs, bool skip_ctx, int w0, int wstride, int lane) {
;     ...
;   for (; i < nrows; i += wstride) {
;     const int row = rowof(i); const int b = row / TB, s = row % TB;
;     f32x4 v[4];
; #pragma unroll
;     for (int q = 0; q < 4; ++q) v[q] = vn[q];
;     if (i + wstride < nrows) {
;       const int rn = rowof(i + wstride); const float* src = xsrc_row(p, from_inputs, rn / TB, rn % TB);
; #pragma unroll
;       for (int q = 0; q < 4; ++q) vn[q] = *(const f32x4*)(src + q * 256 + lane * 4);
;     }
;     const float* mod = p.MOD + (size_t)(l * 9 + (s < NCTX ? 8 : b)) * 6144 + (which ? 3 * 1024 : 0);
;     f32x4 sh[4], sc[4];
; #pragma unroll
;     for (int q = 0; q < 4; ++q) { sh[q] = *(const f32x4*)(mod + q * 256 + lane * 4); sc[q] = *(const f32x4*)(mod + 1024 + q * 256 + lane * 4); }
;     float ss = 0.f;
; #pragma unroll
;     for (int q = 0; q < 4; ++q) ss += v[q][0] * v[q][0] + v[q][1] * v[q][1] + v[q][2] * v[q][2] + v[q][3] * v[q][3];
;     ss = red64(ss);
;     const float rs = rsqrtf(ss * (1.f / 1024.f) + EPSF);
;     bf16_t* dst = p.HY + (size_t)row * DM;
; #pragma unroll
;     for (int q = 0; q < 4; ++q) {
;       float o[4];
; #pragma unroll
;       for (int j = 0; j < 4; ++j) o[j] = (v[q][j] * rs * gg[q][j]) * (1.f + sc[q][j]) + sh[q][j];
;       u32x2 w = {pk_bf16(o[0], o[1]), pk_bf16(o[2], o[3])};
;       *(u32x2*)(dst + q * 256 + lane * 4) = w;
;     }
;   }
	v_pk_mul_f32 v[246:247], v[122:123], v[122:123]
	v_pk_fma_f32 v[246:247], v[124:125], v[124:125], v[246:247]
	v_pk_fma_f32 v[246:247], v[126:127], v[126:127], v[246:247]
	v_pk_fma_f32 v[246:247], v[128:129], v[128:129], v[246:247]
	v_pk_fma_f32 v[246:247], v[130:131], v[130:131], v[246:247]
	v_pk_fma_f32 v[246:247], v[132:133], v[132:133], v[246:247]
	v_pk_fma_f32 v[246:247], v[134:135], v[134:135], v[246:247]
	v_pk_fma_f32 v[246:247], v[136:137], v[136:137], v[246:247]
	s_nop 0
	v_add_f32_e32 v246, v246, v247
	s_nop 1
	v_add_f32_dpp v246, v246, v246 quad_perm:[1,0,3,2] row_mask:0xf bank_mask:0xf
	s_nop 1
	v_add_f32_dpp v246, v246, v246 quad_perm:[2,3,0,1] row_mask:0xf bank_mask:0xf
	s_nop 1
	v_add_f32_dpp v246, v246, v246 row_half_mirror row_mask:0xf bank_mask:0xf
	s_nop 1
	v_add_f32_dpp v246, v246, v246 row_mirror row_mask:0xf bank_mask:0xf
	s_nop 1
	v_add_f32_dpp v246, v246, v246 row_bcast:15 row_mask:0xa bank_mask:0xf
	s_nop 1
	v_add_f32_dpp v246, v246, v246 row_bcast:31 row_mask:0xc bank_mask:0xf
	s_nop 1
	v_readlane_b32 s0, v246, 63
	s_add_i32 s21, s20, 4096
	s_lshl_b32 s21, s21, 11
	s_add_u32 s10, s16, s21
	s_addc_u32 s11, s17, 0
	v_mov_b32_e32 v248, s0
	v_fmamk_f32 v248, v248, 0x3a800000, v143
	v_rsq_f32_e32 v248, v248
	s_nop 0
	v_pk_mul_f32 v[122:123], v[122:123], v[248:249] op_sel_hi:[1,0]
	v_pk_add_f32 v[176:177], v[176:177], 1.0 op_sel_hi:[1,0]
	v_pk_mul_f32 v[122:123], v[2:3], v[122:123]
	v_pk_fma_f32 v[122:123], v[176:177], v[122:123], v[160:161]
	v_pk_mul_f32 v[124:125], v[124:125], v[248:249] op_sel_hi:[1,0]
	v_pk_add_f32 v[178:179], v[178:179], 1.0 op_sel_hi:[1,0]
	v_pk_mul_f32 v[124:125], v[4:5], v[124:125]
	v_pk_fma_f32 v[124:125], v[178:179], v[124:125], v[162:163]
	v_cvt_pk_bf16_f32 v160, v122, v123
	v_cvt_pk_bf16_f32 v161, v124, v125
	global_store_dwordx2 v245, v[160:161], s[10:11]
	v_pk_mul_f32 v[126:127], v[126:127], v[248:249] op_sel_hi:[1,0]
	v_pk_add_f32 v[180:181], v[180:181], 1.0 op_sel_hi:[1,0]
	v_pk_mul_f32 v[126:127], v[6:7], v[126:127]
	v_pk_fma_f32 v[126:127], v[180:181], v[126:127], v[164:165]
	v_pk_mul_f32 v[128:129], v[128:129], v[248:249] op_sel_hi:[1,0]
	v_pk_add_f32 v[182:183], v[182:183], 1.0 op_sel_hi:[1,0]
	v_pk_mul_f32 v[128:129], v[8:9], v[128:129]
	v_pk_fma_f32 v[128:129], v[182:183], v[128:129], v[166:167]
	v_cvt_pk_bf16_f32 v164, v126, v127
	v_cvt_pk_bf16_f32 v165, v128, v129
	global_store_dwordx2 v245, v[164:165], s[10:11] offset:512
	v_pk_mul_f32 v[130:131], v[130:131], v[248:249] op_sel_hi:[1,0]
	v_pk_add_f32 v[184:185], v[184:185], 1.0 op_sel_hi:[1,0]
	v_pk_mul_f32 v[130:131], v[10:11], v[130:131]
	v_pk_fma_f32 v[130:131], v[184:185], v[130:131], v[168:169]
	v_pk_mul_f32 v[132:133], v[132:133], v[248:249] op_sel_hi:[1,0]
	v_pk_add_f32 v[186:187], v[186:187], 1.0 op_sel_hi:[1,0]
	v_pk_mul_f32 v[132:133], v[12:13], v[132:133]
	v_pk_fma_f32 v[132:133], v[186:187], v[132:133], v[170:171]
	v_cvt_pk_bf16_f32 v168, v130, v131
	v_cvt_pk_bf16_f32 v169, v132, v133
	global_store_dwordx2 v245, v[168:169], s[10:11] offset:1024
	v_pk_mul_f32 v[134:135], v[134:135], v[248:249] op_sel_hi:[1,0]
	v_pk_add_f32 v[188:189], v[188:189], 1.0 op_sel_hi:[1,0]
	v_pk_mul_f32 v[134:135], v[14:15], v[134:135]
	v_pk_fma_f32 v[134:135], v[188:189], v[134:135], v[172:173]
	v_pk_mul_f32 v[136:137], v[136:137], v[248:249] op_sel_hi:[1,0]
	v_pk_add_f32 v[190:191], v[190:191], 1.0 op_sel_hi:[1,0]
	v_pk_mul_f32 v[136:137], v[16:17], v[136:137]
	v_pk_fma_f32 v[136:137], v[190:191], v[136:137], v[174:175]
	v_cvt_pk_bf16_f32 v172, v134, v135
	v_cvt_pk_bf16_f32 v173, v136, v137
	global_store_dwordx2 v245, v[172:173], s[10:11] offset:1536
	s_add_i32 s21, s20, 10240
	s_mul_hi_u32 s7, s21, 0x38e38e39
	s_lshr_b32 s7, s7, 9
	s_mul_i32 s8, s7, 0x900
	s_sub_i32 s8, s21, s8
	s_lshl_b32 s9, s7, 11
	s_add_i32 s9, s9, s8
	s_add_i32 s9, s9, 0xffffff00
	s_lshl_b32 s10, s7, 8
	s_add_i32 s10, s10, s8
	s_cmpk_gt_i32 s8, 0xff
	s_cselect_b32 s9, s9, s10
	s_cselect_b32 s26, s12, s14
	s_cselect_b32 s27, s13, s15
	s_cselect_b32 s10, s7, 8
	s_lshl_b32 s9, s9, 12
	s_add_u32 s26, s26, s9
	s_addc_u32 s27, s27, 0
	s_add_i32 s10, s10, s82
	s_mul_i32 s10, s10, s24
	s_add_u32 s28, s58, s10
	s_addc_u32 s29, s59, 0
	s_add_u32 s28, s28, 0x0
	s_addc_u32 s29, s29, 0
	s_add_u32 s0, s28, 0x1000
	s_addc_u32 s1, s29, 0
	global_load_dwordx4 v[122:125], v244, s[26:27]
	global_load_dwordx4 v[126:129], v244, s[26:27] offset:1024
	global_load_dwordx4 v[130:133], v244, s[26:27] offset:2048
	global_load_dwordx4 v[134:137], v244, s[26:27] offset:3072
	global_load_dwordx4 v[160:163], v244, s[28:29]
	global_load_dwordx4 v[164:167], v244, s[28:29] offset:1024
	global_load_dwordx4 v[168:171], v244, s[28:29] offset:2048
	global_load_dwordx4 v[172:175], v244, s[28:29] offset:3072
	global_load_dwordx4 v[176:179], v244, s[0:1]
	global_load_dwordx4 v[180:183], v244, s[0:1] offset:1024
	global_load_dwordx4 v[184:187], v244, s[0:1] offset:2048
	global_load_dwordx4 v[188:191], v244, s[0:1] offset:3072
	s_waitcnt vmcnt(32)
; DI unsigned pk_bf16(float lo, float hi) { f32x2 v = {lo, hi}; bf16v2 b = __builtin_convertvector(v, bf16v2); return __builtin_bit_cast(unsigned, b); }
; DI float red64(float x) { for (int o = 32; o > 0; o >>= 1) x += __shfl_xor(x, o); return x; }
; DI void modnorm_rows(const Params& p, int l, int which  , bool from_inputs, bool skip_ctx, int w0, int wstride, int lane) {
;     ...
;   for (; i < nrows; i += wstride) {
;     const int row = rowof(i); const int b = row / TB, s = row % TB;
;     f32x4 v[4];
; #pragma unroll
;     for (int q = 0; q < 4; ++q) v[q] = vn[q];
;     if (i + wstride < nrows) {
;       const int rn = rowof(i + wstride); const float* src = xsrc_row(p, from_inputs, rn / TB, rn % TB);
; #pragma unroll
;       for (int q = 0; q < 4; ++q) vn[q] = *(const f32x4*)(src + q * 256 + lane * 4);
;     }
;     const float* mod = p.MOD + (size_t)(l * 9 + (s < NCTX ? 8 : b)) * 6144 + (which ? 3 * 1024 : 0);
;     f32x4 sh[4], sc[4];
; #pragma unroll
;     for (int q = 0; q < 4; ++q) { sh[q] = *(const f32x4*)(mod + q * 256 + lane * 4); sc[q] = *(const f32x4*)(mod + 1024 + q * 256 + lane * 4); }
;     float ss = 0.f;
; #pragma unroll
;     for (int q = 0; q < 4; ++q) ss += v[q][0] * v[q][0] + v[q][1] * v[q][1] + v[q][2] * v[q][2] + v[q][3] * v[q][3];
;     ss = red64(ss);
;     const float rs = rsqrtf(ss * (1.f / 1024.f) + EPSF);
;     bf16_t* dst = p.HY + (size_t)row * DM;
; #pragma unroll
;     for (int q = 0; q < 4; ++q) {
;       float o[4];
; #pragma unroll
;       for (int j = 0; j < 4; ++j) o[j] = (v[q][j] * rs * gg[q][j]) * (1.f + sc[q][j]) + sh[q][j];
;       u32x2 w = {pk_bf16(o[0], o[1]), pk_bf16(o[2], o[3])};
;       *(u32x2*)(dst + q * 256 + lane * 4) = w;
;     }
;   }
	v_pk_mul_f32 v[246:247], v[18:19], v[18:19]
	v_pk_fma_f32 v[246:247], v[20:21], v[20:21], v[246:247]
	v_pk_fma_f32 v[246:247], v[22:23], v[22:23], v[246:247]
	v_pk_fma_f32 v[246:247], v[24:25], v[24:25], v[246:247]
	v_pk_fma_f32 v[246:247], v[26:27], v[26:27], v[246:247]
	v_pk_fma_f32 v[246:247], v[28:29], v[28:29], v[246:247]
	v_pk_fma_f32 v[246:247], v[30:31], v[30:31], v[246:247]
	v_pk_fma_f32 v[246:247], v[32:33], v[32:33], v[246:247]
	s_nop 0
	v_add_f32_e32 v246, v246, v247
	s_nop 1
	v_add_f32_dpp v246, v246, v246 quad_perm:[1,0,3,2] row_mask:0xf bank_mask:0xf
	s_nop 1
	v_add_f32_dpp v246, v246, v246 quad_perm:[2,3,0,1] row_mask:0xf bank_mask:0xf
	s_nop 1
	v_add_f32_dpp v246, v246, v246 row_half_mirror row_mask:0xf bank_mask:0xf
	s_nop 1
	v_add_f32_dpp v246, v246, v246 row_mirror row_mask:0xf bank_mask:0xf
	s_nop 1
	v_add_f32_dpp v246, v246, v246 row_bcast:15 row_mask:0xa bank_mask:0xf
	s_nop 1
	v_add_f32_dpp v246, v246, v246 row_bcast:31 row_mask:0xc bank_mask:0xf
	s_nop 1
	v_readlane_b32 s0, v246, 63
	s_add_i32 s21, s20, 6144
	s_lshl_b32 s21, s21, 11
	s_add_u32 s10, s16, s21
	s_addc_u32 s11, s17, 0
	v_mov_b32_e32 v248, s0
	v_fmamk_f32 v248, v248, 0x3a800000, v143
	v_rsq_f32_e32 v248, v248
	s_nop 0
	v_pk_mul_f32 v[18:19], v[18:19], v[248:249] op_sel_hi:[1,0]
	v_pk_add_f32 v[50:51], v[50:51], 1.0 op_sel_hi:[1,0]
	v_pk_mul_f32 v[18:19], v[2:3], v[18:19]
	v_pk_fma_f32 v[18:19], v[50:51], v[18:19], v[34:35]
	v_pk_mul_f32 v[20:21], v[20:21], v[248:249] op_sel_hi:[1,0]
	v_pk_add_f32 v[52:53], v[52:53], 1.0 op_sel_hi:[1,0]
	v_pk_mul_f32 v[20:21], v[4:5], v[20:21]
	v_pk_fma_f32 v[20:21], v[52:53], v[20:21], v[36:37]
	v_cvt_pk_bf16_f32 v34, v18, v19
	v_cvt_pk_bf16_f32 v35, v20, v21
	global_store_dwordx2 v245, v[34:35], s[10:11]
	v_pk_mul_f32 v[22:23], v[22:23], v[248:249] op_sel_hi:[1,0]
	v_pk_add_f32 v[54:55], v[54:55], 1.0 op_sel_hi:[1,0]
	v_pk_mul_f32 v[22:23], v[6:7], v[22:23]
	v_pk_fma_f32 v[22:23], v[54:55], v[22:23], v[38:39]
	v_pk_mul_f32 v[24:25], v[24:25], v[248:249] op_sel_hi:[1,0]
	v_pk_add_f32 v[56:57], v[56:57], 1.0 op_sel_hi:[1,0]
	v_pk_mul_f32 v[24:25], v[8:9], v[24:25]
	v_pk_fma_f32 v[24:25], v[56:57], v[24:25], v[40:41]
	v_cvt_pk_bf16_f32 v38, v22, v23
	v_cvt_pk_bf16_f32 v39, v24, v25
	global_store_dwordx2 v245, v[38:39], s[10:11] offset:512
	v_pk_mul_f32 v[26:27], v[26:27], v[248:249] op_sel_hi:[1,0]
	v_pk_add_f32 v[58:59], v[58:59], 1.0 op_sel_hi:[1,0]
	v_pk_mul_f32 v[26:27], v[10:11], v[26:27]
	v_pk_fma_f32 v[26:27], v[58:59], v[26:27], v[42:43]
	v_pk_mul_f32 v[28:29], v[28:29], v[248:249] op_sel_hi:[1,0]
	v_pk_add_f32 v[60:61], v[60:61], 1.0 op_sel_hi:[1,0]
	v_pk_mul_f32 v[28:29], v[12:13], v[28:29]
	v_pk_fma_f32 v[28:29], v[60:61], v[28:29], v[44:45]
	v_cvt_pk_bf16_f32 v42, v26, v27
	v_cvt_pk_bf16_f32 v43, v28, v29
	global_store_dwordx2 v245, v[42:43], s[10:11] offset:1024
	v_pk_mul_f32 v[30:31], v[30:31], v[248:249] op_sel_hi:[1,0]
	v_pk_add_f32 v[62:63], v[62:63], 1.0 op_sel_hi:[1,0]
	v_pk_mul_f32 v[30:31], v[14:15], v[30:31]
	v_pk_fma_f32 v[30:31], v[62:63], v[30:31], v[46:47]
	v_pk_mul_f32 v[32:33], v[32:33], v[248:249] op_sel_hi:[1,0]
	v_pk_add_f32 v[64:65], v[64:65], 1.0 op_sel_hi:[1,0]
	v_pk_mul_f32 v[32:33], v[16:17], v[32:33]
	v_pk_fma_f32 v[32:33], v[64:65], v[32:33], v[48:49]
	v_cvt_pk_bf16_f32 v46, v30, v31
	v_cvt_pk_bf16_f32 v47, v32, v33
	global_store_dwordx2 v245, v[46:47], s[10:11] offset:1536
	s_add_i32 s21, s20, 12288
	s_mul_hi_u32 s7, s21, 0x38e38e39
	s_lshr_b32 s7, s7, 9
	s_mul_i32 s8, s7, 0x900
	s_sub_i32 s8, s21, s8
	s_lshl_b32 s9, s7, 11
	s_add_i32 s9, s9, s8
	s_add_i32 s9, s9, 0xffffff00
	s_lshl_b32 s10, s7, 8
	s_add_i32 s10, s10, s8
	s_cmpk_gt_i32 s8, 0xff
	s_cselect_b32 s9, s9, s10
	s_cselect_b32 s26, s12, s14
	s_cselect_b32 s27, s13, s15
	s_cselect_b32 s10, s7, 8
	s_lshl_b32 s9, s9, 12
	s_add_u32 s26, s26, s9
	s_addc_u32 s27, s27, 0
	s_add_i32 s10, s10, s82
	s_mul_i32 s10, s10, s24
	s_add_u32 s28, s58, s10
	s_addc_u32 s29, s59, 0
	s_add_u32 s28, s28, 0x0
	s_addc_u32 s29, s29, 0
	s_add_u32 s0, s28, 0x1000
	s_addc_u32 s1, s29, 0
	global_load_dwordx4 v[18:21], v244, s[26:27]
	global_load_dwordx4 v[22:25], v244, s[26:27] offset:1024
	global_load_dwordx4 v[26:29], v244, s[26:27] offset:2048
	global_load_dwordx4 v[30:33], v244, s[26:27] offset:3072
	global_load_dwordx4 v[34:37], v244, s[28:29]
	global_load_dwordx4 v[38:41], v244, s[28:29] offset:1024
	global_load_dwordx4 v[42:45], v244, s[28:29] offset:2048
	global_load_dwordx4 v[46:49], v244, s[28:29] offset:3072
	global_load_dwordx4 v[50:53], v244, s[0:1]
	global_load_dwordx4 v[54:57], v244, s[0:1] offset:1024
	global_load_dwordx4 v[58:61], v244, s[0:1] offset:2048
	global_load_dwordx4 v[62:65], v244, s[0:1] offset:3072
	s_waitcnt vmcnt(32)
; DI unsigned pk_bf16(float lo, float hi) { f32x2 v = {lo, hi}; bf16v2 b = __builtin_convertvector(v, bf16v2); return __builtin_bit_cast(unsigned, b); }
; DI float red64(float x) { for (int o = 32; o > 0; o >>= 1) x += __shfl_xor(x, o); return x; }
; DI void modnorm_rows(const Params& p, int l, int which  , bool from_inputs, bool skip_ctx, int w0, int wstride, int lane) {
;     ...
;   for (; i < nrows; i += wstride) {
;     const int row = rowof(i); const int b = row / TB, s = row % TB;
;     f32x4 v[4];
; #pragma unroll
;     for (int q = 0; q < 4; ++q) v[q] = vn[q];
;     if (i + wstride < nrows) {
;       const int rn = rowof(i + wstride); const float* src = xsrc_row(p, from_inputs, rn / TB, rn % TB);
; #pragma unroll
;       for (int q = 0; q < 4; ++q) vn[q] = *(const f32x4*)(src + q * 256 + lane * 4);
;     }
;     const float* mod = p.MOD + (size_t)(l * 9 + (s < NCTX ? 8 : b)) * 6144 + (which ? 3 * 1024 : 0);
;     f32x4 sh[4], sc[4];
; #pragma unroll
;     for (int q = 0; q < 4; ++q) { sh[q] = *(const f32x4*)(mod + q * 256 + lane * 4); sc[q] = *(const f32x4*)(mod + 1024 + q * 256 + lane * 4); }
;     float ss = 0.f;
; #pragma unroll
;     for (int q = 0; q < 4; ++q) ss += v[q][0] * v[q][0] + v[q][1] * v[q][1] + v[q][2] * v[q][2] + v[q][3] * v[q][3];
;     ss = red64(ss);
;     const float rs = rsqrtf(ss * (1.f / 1024.f) + EPSF);
;     bf16_t* dst = p.HY + (size_t)row * DM;
; #pragma unroll
;     for (int q = 0; q < 4; ++q) {
;       float o[4];
; #pragma unroll
;       for (int j = 0; j < 4; ++j) o[j] = (v[q][j] * rs * gg[q][j]) * (1.f + sc[q][j]) + sh[q][j];
;       u32x2 w = {pk_bf16(o[0], o[1]), pk_bf16(o[2], o[3])};
;       *(u32x2*)(dst + q * 256 + lane * 4) = w;
;     }
;   }
	v_pk_mul_f32 v[246:247], v[66:67], v[66:67]
	v_pk_fma_f32 v[246:247], v[68:69], v[68:69], v[246:247]
	v_pk_fma_f32 v[246:247], v[70:71], v[70:71], v[246:247]
	v_pk_fma_f32 v[246:247], v[72:73], v[72:73], v[246:247]
	v_pk_fma_f32 v[246:247], v[74:75], v[74:75], v[246:247]
	v_pk_fma_f32 v[246:247], v[76:77], v[76:77], v[246:247]
	v_pk_fma_f32 v[246:247], v[78:79], v[78:79], v[246:247]
	v_pk_fma_f32 v[246:247], v[80:81], v[80:81], v[246:247]
	s_nop 0
	v_add_f32_e32 v246, v246, v247
	s_nop 1
	v_add_f32_dpp v246, v246, v246 quad_perm:[1,0,3,2] row_mask:0xf bank_mask:0xf
	s_nop 1
	v_add_f32_dpp v246, v246, v246 quad_perm:[2,3,0,1] row_mask:0xf bank_mask:0xf
	s_nop 1
	v_add_f32_dpp v246, v246, v246 row_half_mirror row_mask:0xf bank_mask:0xf
	s_nop 1
	v_add_f32_dpp v246, v246, v246 row_mirror row_mask:0xf bank_mask:0xf
	s_nop 1
	v_add_f32_dpp v246, v246, v246 row_bcast:15 row_mask:0xa bank_mask:0xf
	s_nop 1
	v_add_f32_dpp v246, v246, v246 row_bcast:31 row_mask:0xc bank_mask:0xf
	s_nop 1
	v_readlane_b32 s0, v246, 63
	s_add_i32 s21, s20, 8192
	s_lshl_b32 s21, s21, 11
	s_add_u32 s10, s16, s21
	s_addc_u32 s11, s17, 0
	v_mov_b32_e32 v248, s0
	v_fmamk_f32 v248, v248, 0x3a800000, v143
	v_rsq_f32_e32 v248, v248
	s_nop 0
	v_pk_mul_f32 v[66:67], v[66:67], v[248:249] op_sel_hi:[1,0]
	v_pk_add_f32 v[98:99], v[98:99], 1.0 op_sel_hi:[1,0]
	v_pk_mul_f32 v[66:67], v[2:3], v[66:67]
	v_pk_fma_f32 v[66:67], v[98:99], v[66:67], v[82:83]
	v_pk_mul_f32 v[68:69], v[68:69], v[248:249] op_sel_hi:[1,0]
	v_pk_add_f32 v[100:101], v[100:101], 1.0 op_sel_hi:[1,0]
	v_pk_mul_f32 v[68:69], v[4:5], v[68:69]
	v_pk_fma_f32 v[68:69], v[100:101], v[68:69], v[84:85]
	v_cvt_pk_bf16_f32 v82, v66, v67
	v_cvt_pk_bf16_f32 v83, v68, v69
	global_store_dwordx2 v245, v[82:83], s[10:11]
	v_pk_mul_f32 v[70:71], v[70:71], v[248:249] op_sel_hi:[1,0]
	v_pk_add_f32 v[102:103], v[102:103], 1.0 op_sel_hi:[1,0]
	v_pk_mul_f32 v[70:71], v[6:7], v[70:71]
	v_pk_fma_f32 v[70:71], v[102:103], v[70:71], v[86:87]
	v_pk_mul_f32 v[72:73], v[72:73], v[248:249] op_sel_hi:[1,0]
	v_pk_add_f32 v[104:105], v[104:105], 1.0 op_sel_hi:[1,0]
	v_pk_mul_f32 v[72:73], v[8:9], v[72:73]
	v_pk_fma_f32 v[72:73], v[104:105], v[72:73], v[88:89]
	v_cvt_pk_bf16_f32 v86, v70, v71
	v_cvt_pk_bf16_f32 v87, v72, v73
	global_store_dwordx2 v245, v[86:87], s[10:11] offset:512
	v_pk_mul_f32 v[74:75], v[74:75], v[248:249] op_sel_hi:[1,0]
	v_pk_add_f32 v[106:107], v[106:107], 1.0 op_sel_hi:[1,0]
	v_pk_mul_f32 v[74:75], v[10:11], v[74:75]
	v_pk_fma_f32 v[74:75], v[106:107], v[74:75], v[90:91]
	v_pk_mul_f32 v[76:77], v[76:77], v[248:249] op_sel_hi:[1,0]
	v_pk_add_f32 v[108:109], v[108:109], 1.0 op_sel_hi:[1,0]
	v_pk_mul_f32 v[76:77], v[12:13], v[76:77]
	v_pk_fma_f32 v[76:77], v[108:109], v[76:77], v[92:93]
	v_cvt_pk_bf16_f32 v90, v74, v75
	v_cvt_pk_bf16_f32 v91, v76, v77
	global_store_dwordx2 v245, v[90:91], s[10:11] offset:1024
	v_pk_mul_f32 v[78:79], v[78:79], v[248:249] op_sel_hi:[1,0]
	v_pk_add_f32 v[118:119], v[118:119], 1.0 op_sel_hi:[1,0]
	v_pk_mul_f32 v[78:79], v[14:15], v[78:79]
	v_pk_fma_f32 v[78:79], v[118:119], v[78:79], v[94:95]
	v_pk_mul_f32 v[80:81], v[80:81], v[248:249] op_sel_hi:[1,0]
	v_pk_add_f32 v[120:121], v[120:121], 1.0 op_sel_hi:[1,0]
	v_pk_mul_f32 v[80:81], v[16:17], v[80:81]
	v_pk_fma_f32 v[80:81], v[120:121], v[80:81], v[96:97]
	v_cvt_pk_bf16_f32 v94, v78, v79
	v_cvt_pk_bf16_f32 v95, v80, v81
	global_store_dwordx2 v245, v[94:95], s[10:11] offset:1536
	s_add_i32 s21, s20, 14336
	s_mul_hi_u32 s7, s21, 0x38e38e39
	s_lshr_b32 s7, s7, 9
	s_mul_i32 s8, s7, 0x900
	s_sub_i32 s8, s21, s8
	s_lshl_b32 s9, s7, 11
	s_add_i32 s9, s9, s8
	s_add_i32 s9, s9, 0xffffff00
	s_lshl_b32 s10, s7, 8
	s_add_i32 s10, s10, s8
	s_cmpk_gt_i32 s8, 0xff
	s_cselect_b32 s9, s9, s10
	s_cselect_b32 s26, s12, s14
	s_cselect_b32 s27, s13, s15
	s_cselect_b32 s10, s7, 8
	s_lshl_b32 s9, s9, 12
	s_add_u32 s26, s26, s9
	s_addc_u32 s27, s27, 0
	s_add_i32 s10, s10, s82
	s_mul_i32 s10, s10, s24
	s_add_u32 s28, s58, s10
	s_addc_u32 s29, s59, 0
	s_add_u32 s28, s28, 0x0
	s_addc_u32 s29, s29, 0
	s_add_u32 s0, s28, 0x1000
	s_addc_u32 s1, s29, 0
	global_load_dwordx4 v[66:69], v244, s[26:27]
	global_load_dwordx4 v[70:73], v244, s[26:27] offset:1024
	global_load_dwordx4 v[74:77], v244, s[26:27] offset:2048
	global_load_dwordx4 v[78:81], v244, s[26:27] offset:3072
	global_load_dwordx4 v[82:85], v244, s[28:29]
	global_load_dwordx4 v[86:89], v244, s[28:29] offset:1024
	global_load_dwordx4 v[90:93], v244, s[28:29] offset:2048
	global_load_dwordx4 v[94:97], v244, s[28:29] offset:3072
	global_load_dwordx4 v[98:101], v244, s[0:1]
	global_load_dwordx4 v[102:105], v244, s[0:1] offset:1024
	global_load_dwordx4 v[106:109], v244, s[0:1] offset:2048
	global_load_dwordx4 v[118:121], v244, s[0:1] offset:3072
	s_waitcnt vmcnt(32)
; DI unsigned pk_bf16(float lo, float hi) { f32x2 v = {lo, hi}; bf16v2 b = __builtin_convertvector(v, bf16v2); return __builtin_bit_cast(unsigned, b); }
; DI float red64(float x) { for (int o = 32; o > 0; o >>= 1) x += __shfl_xor(x, o); return x; }
; DI void modnorm_rows(const Params& p, int l, int which  , bool from_inputs, bool skip_ctx, int w0, int wstride, int lane) {
;     ...
;   for (; i < nrows; i += wstride) {
;     const int row = rowof(i); const int b = row / TB, s = row % TB;
;     f32x4 v[4];
; #pragma unroll
;     for (int q = 0; q < 4; ++q) v[q] = vn[q];
;     if (i + wstride < nrows) {
;       const int rn = rowof(i + wstride); const float* src = xsrc_row(p, from_inputs, rn / TB, rn % TB);
; #pragma unroll
;       for (int q = 0; q < 4; ++q) vn[q] = *(const f32x4*)(src + q * 256 + lane * 4);
;     }
;     const float* mod = p.MOD + (size_t)(l * 9 + (s < NCTX ? 8 : b)) * 6144 + (which ? 3 * 1024 : 0);
;     f32x4 sh[4], sc[4];
; #pragma unroll
;     for (int q = 0; q < 4; ++q) { sh[q] = *(const f32x4*)(mod + q * 256 + lane * 4); sc[q] = *(const f32x4*)(mod + 1024 + q * 256 + lane * 4); }
;     float ss = 0.f;
; #pragma unroll
;     for (int q = 0; q < 4; ++q) ss += v[q][0] * v[q][0] + v[q][1] * v[q][1] + v[q][2] * v[q][2] + v[q][3] * v[q][3];
;     ss = red64(ss);
;     const float rs = rsqrtf(ss * (1.f / 1024.f) + EPSF);
;     bf16_t* dst = p.HY + (size_t)row * DM;
; #pragma unroll
;     for (int q = 0; q < 4; ++q) {
;       float o[4];
; #pragma unroll
;       for (int j = 0; j < 4; ++j) o[j] = (v[q][j] * rs * gg[q][j]) * (1.f + sc[q][j]) + sh[q][j];
;       u32x2 w = {pk_bf16(o[0], o[1]), pk_bf16(o[2], o[3])};
;       *(u32x2*)(dst + q * 256 + lane * 4) = w;
;     }
;   }
	v_pk_mul_f32 v[246:247], v[122:123], v[122:123]
	v_pk_fma_f32 v[246:247], v[124:125], v[124:125], v[246:247]
	v_pk_fma_f32 v[246:247], v[126:127], v[126:127], v[246:247]
	v_pk_fma_f32 v[246:247], v[128:129], v[128:129], v[246:247]
	v_pk_fma_f32 v[246:247], v[130:131], v[130:131], v[246:247]
	v_pk_fma_f32 v[246:247], v[132:133], v[132:133], v[246:247]
	v_pk_fma_f32 v[246:247], v[134:135], v[134:135], v[246:247]
	v_pk_fma_f32 v[246:247], v[136:137], v[136:137], v[246:247]
	s_nop 0
	v_add_f32_e32 v246, v246, v247
	s_nop 1
	v_add_f32_dpp v246, v246, v246 quad_perm:[1,0,3,2] row_mask:0xf bank_mask:0xf
	s_nop 1
	v_add_f32_dpp v246, v246, v246 quad_perm:[2,3,0,1] row_mask:0xf bank_mask:0xf
	s_nop 1
	v_add_f32_dpp v246, v246, v246 row_half_mirror row_mask:0xf bank_mask:0xf
	s_nop 1
	v_add_f32_dpp v246, v246, v246 row_mirror row_mask:0xf bank_mask:0xf
	s_nop 1
	v_add_f32_dpp v246, v246, v246 row_bcast:15 row_mask:0xa bank_mask:0xf
	s_nop 1
	v_add_f32_dpp v246, v246, v246 row_bcast:31 row_mask:0xc bank_mask:0xf
	s_nop 1
	v_readlane_b32 s0, v246, 63
	s_add_i32 s21, s20, 10240
	s_lshl_b32 s21, s21, 11
	s_add_u32 s10, s16, s21
	s_addc_u32 s11, s17, 0
	v_mov_b32_e32 v248, s0
	v_fmamk_f32 v248, v248, 0x3a800000, v143
	v_rsq_f32_e32 v248, v248
	s_nop 0
	v_pk_mul_f32 v[122:123], v[122:123], v[248:249] op_sel_hi:[1,0]
	v_pk_add_f32 v[176:177], v[176:177], 1.0 op_sel_hi:[1,0]
	v_pk_mul_f32 v[122:123], v[2:3], v[122:123]
	v_pk_fma_f32 v[122:123], v[176:177], v[122:123], v[160:161]
	v_pk_mul_f32 v[124:125], v[124:125], v[248:249] op_sel_hi:[1,0]
	v_pk_add_f32 v[178:179], v[178:179], 1.0 op_sel_hi:[1,0]
	v_pk_mul_f32 v[124:125], v[4:5], v[124:125]
	v_pk_fma_f32 v[124:125], v[178:179], v[124:125], v[162:163]
	v_cvt_pk_bf16_f32 v160, v122, v123
	v_cvt_pk_bf16_f32 v161, v124, v125
	global_store_dwordx2 v245, v[160:161], s[10:11]
	v_pk_mul_f32 v[126:127], v[126:127], v[248:249] op_sel_hi:[1,0]
	v_pk_add_f32 v[180:181], v[180:181], 1.0 op_sel_hi:[1,0]
	v_pk_mul_f32 v[126:127], v[6:7], v[126:127]
	v_pk_fma_f32 v[126:127], v[180:181], v[126:127], v[164:165]
	v_pk_mul_f32 v[128:129], v[128:129], v[248:249] op_sel_hi:[1,0]
	v_pk_add_f32 v[182:183], v[182:183], 1.0 op_sel_hi:[1,0]
	v_pk_mul_f32 v[128:129], v[8:9], v[128:129]
	v_pk_fma_f32 v[128:129], v[182:183], v[128:129], v[166:167]
	v_cvt_pk_bf16_f32 v164, v126, v127
	v_cvt_pk_bf16_f32 v165, v128, v129
	global_store_dwordx2 v245, v[164:165], s[10:11] offset:512
	v_pk_mul_f32 v[130:131], v[130:131], v[248:249] op_sel_hi:[1,0]
	v_pk_add_f32 v[184:185], v[184:185], 1.0 op_sel_hi:[1,0]
	v_pk_mul_f32 v[130:131], v[10:11], v[130:131]
	v_pk_fma_f32 v[130:131], v[184:185], v[130:131], v[168:169]
	v_pk_mul_f32 v[132:133], v[132:133], v[248:249] op_sel_hi:[1,0]
	v_pk_add_f32 v[186:187], v[186:187], 1.0 op_sel_hi:[1,0]
	v_pk_mul_f32 v[132:133], v[12:13], v[132:133]
	v_pk_fma_f32 v[132:133], v[186:187], v[132:133], v[170:171]
	v_cvt_pk_bf16_f32 v168, v130, v131
	v_cvt_pk_bf16_f32 v169, v132, v133
	global_store_dwordx2 v245, v[168:169], s[10:11] offset:1024
	v_pk_mul_f32 v[134:135], v[134:135], v[248:249] op_sel_hi:[1,0]
	v_pk_add_f32 v[188:189], v[188:189], 1.0 op_sel_hi:[1,0]
	v_pk_mul_f32 v[134:135], v[14:15], v[134:135]
	v_pk_fma_f32 v[134:135], v[188:189], v[134:135], v[172:173]
	v_pk_mul_f32 v[136:137], v[136:137], v[248:249] op_sel_hi:[1,0]
	v_pk_add_f32 v[190:191], v[190:191], 1.0 op_sel_hi:[1,0]
	v_pk_mul_f32 v[136:137], v[16:17], v[136:137]
	v_pk_fma_f32 v[136:137], v[190:191], v[136:137], v[174:175]
	v_cvt_pk_bf16_f32 v172, v134, v135
	v_cvt_pk_bf16_f32 v173, v136, v137
	global_store_dwordx2 v245, v[172:173], s[10:11] offset:1536
	s_add_i32 s21, s20, 16384
	s_mul_hi_u32 s7, s21, 0x38e38e39
	s_lshr_b32 s7, s7, 9
	s_mul_i32 s8, s7, 0x900
	s_sub_i32 s8, s21, s8
	s_lshl_b32 s9, s7, 11
	s_add_i32 s9, s9, s8
	s_add_i32 s9, s9, 0xffffff00
	s_lshl_b32 s10, s7, 8
	s_add_i32 s10, s10, s8
	s_cmpk_gt_i32 s8, 0xff
	s_cselect_b32 s9, s9, s10
	s_cselect_b32 s26, s12, s14
	s_cselect_b32 s27, s13, s15
	s_cselect_b32 s10, s7, 8
	s_lshl_b32 s9, s9, 12
	s_add_u32 s26, s26, s9
	s_addc_u32 s27, s27, 0
	s_add_i32 s10, s10, s82
	s_mul_i32 s10, s10, s24
	s_add_u32 s28, s58, s10
	s_addc_u32 s29, s59, 0
	s_add_u32 s28, s28, 0x0
	s_addc_u32 s29, s29, 0
	s_add_u32 s0, s28, 0x1000
	s_addc_u32 s1, s29, 0
	global_load_dwordx4 v[122:125], v244, s[26:27]
	global_load_dwordx4 v[126:129], v244, s[26:27] offset:1024
	global_load_dwordx4 v[130:133], v244, s[26:27] offset:2048
	global_load_dwordx4 v[134:137], v244, s[26:27] offset:3072
	global_load_dwordx4 v[160:163], v244, s[28:29]
	global_load_dwordx4 v[164:167], v244, s[28:29] offset:1024
	global_load_dwordx4 v[168:171], v244, s[28:29] offset:2048
	global_load_dwordx4 v[172:175], v244, s[28:29] offset:3072
	global_load_dwordx4 v[176:179], v244, s[0:1]
	global_load_dwordx4 v[180:183], v244, s[0:1] offset:1024
	global_load_dwordx4 v[184:187], v244, s[0:1] offset:2048
	global_load_dwordx4 v[188:191], v244, s[0:1] offset:3072
	s_waitcnt vmcnt(32)
; DI unsigned pk_bf16(float lo, float hi) { f32x2 v = {lo, hi}; bf16v2 b = __builtin_convertvector(v, bf16v2); return __builtin_bit_cast(unsigned, b); }
; DI float red64(float x) { for (int o = 32; o > 0; o >>= 1) x += __shfl_xor(x, o); return x; }
; DI void modnorm_rows(const Params& p, int l, int which  , bool from_inputs, bool skip_ctx, int w0, int wstride, int lane) {
;     ...
;   for (; i < nrows; i += wstride) {
;     const int row = rowof(i); const int b = row / TB, s = row % TB;
;     f32x4 v[4];
; #pragma unroll
;     for (int q = 0; q < 4; ++q) v[q] = vn[q];
;     if (i + wstride < nrows) {
;       const int rn = rowof(i + wstride); const float* src = xsrc_row(p, from_inputs, rn / TB, rn % TB);
; #pragma unroll
;       for (int q = 0; q < 4; ++q) vn[q] = *(const f32x4*)(src + q * 256 + lane * 4);
;     }
;     const float* mod = p.MOD + (size_t)(l * 9 + (s < NCTX ? 8 : b)) * 6144 + (which ? 3 * 1024 : 0);
;     f32x4 sh[4], sc[4];
; #pragma unroll
;     for (int q = 0; q < 4; ++q) { sh[q] = *(const f32x4*)(mod + q * 256 + lane * 4); sc[q] = *(const f32x4*)(mod + 1024 + q * 256 + lane * 4); }
;     float ss = 0.f;
; #pragma unroll
;     for (int q = 0; q < 4; ++q) ss += v[q][0] * v[q][0] + v[q][1] * v[q][1] + v[q][2] * v[q][2] + v[q][3] * v[q][3];
;     ss = red64(ss);
;     const float rs = rsqrtf(ss * (1.f / 1024.f) + EPSF);
;     bf16_t* dst = p.HY + (size_t)row * DM;
; #pragma unroll
;     for (int q = 0; q < 4; ++q) {
;       float o[4];
; #pragma unroll
;       for (int j = 0; j < 4; ++j) o[j] = (v[q][j] * rs * gg[q][j]) * (1.f + sc[q][j]) + sh[q][j];
;       u32x2 w = {pk_bf16(o[0], o[1]), pk_bf16(o[2], o[3])};
;       *(u32x2*)(dst + q * 256 + lane * 4) = w;
;     }
;   }
	v_pk_mul_f32 v[246:247], v[18:19], v[18:19]
	v_pk_fma_f32 v[246:247], v[20:21], v[20:21], v[246:247]
	v_pk_fma_f32 v[246:247], v[22:23], v[22:23], v[246:247]
	v_pk_fma_f32 v[246:247], v[24:25], v[24:25], v[246:247]
	v_pk_fma_f32 v[246:247], v[26:27], v[26:27], v[246:247]
	v_pk_fma_f32 v[246:247], v[28:29], v[28:29], v[246:247]
	v_pk_fma_f32 v[246:247], v[30:31], v[30:31], v[246:247]
	v_pk_fma_f32 v[246:247], v[32:33], v[32:33], v[246:247]
	s_nop 0
	v_add_f32_e32 v246, v246, v247
	s_nop 1
	v_add_f32_dpp v246, v246, v246 quad_perm:[1,0,3,2] row_mask:0xf bank_mask:0xf
	s_nop 1
	v_add_f32_dpp v246, v246, v246 quad_perm:[2,3,0,1] row_mask:0xf bank_mask:0xf
	s_nop 1
	v_add_f32_dpp v246, v246, v246 row_half_mirror row_mask:0xf bank_mask:0xf
	s_nop 1
	v_add_f32_dpp v246, v246, v246 row_mirror row_mask:0xf bank_mask:0xf
	s_nop 1
	v_add_f32_dpp v246, v246, v246 row_bcast:15 row_mask:0xa bank_mask:0xf
	s_nop 1
	v_add_f32_dpp v246, v246, v246 row_bcast:31 row_mask:0xc bank_mask:0xf
	s_nop 1
	v_readlane_b32 s0, v246, 63
	s_add_i32 s21, s20, 12288
	s_lshl_b32 s21, s21, 11
	s_add_u32 s10, s16, s21
	s_addc_u32 s11, s17, 0
	v_mov_b32_e32 v248, s0
	v_fmamk_f32 v248, v248, 0x3a800000, v143
	v_rsq_f32_e32 v248, v248
	s_nop 0
	v_pk_mul_f32 v[18:19], v[18:19], v[248:249] op_sel_hi:[1,0]
	v_pk_add_f32 v[50:51], v[50:51], 1.0 op_sel_hi:[1,0]
	v_pk_mul_f32 v[18:19], v[2:3], v[18:19]
	v_pk_fma_f32 v[18:19], v[50:51], v[18:19], v[34:35]
	v_pk_mul_f32 v[20:21], v[20:21], v[248:249] op_sel_hi:[1,0]
	v_pk_add_f32 v[52:53], v[52:53], 1.0 op_sel_hi:[1,0]
	v_pk_mul_f32 v[20:21], v[4:5], v[20:21]
	v_pk_fma_f32 v[20:21], v[52:53], v[20:21], v[36:37]
	v_cvt_pk_bf16_f32 v34, v18, v19
	v_cvt_pk_bf16_f32 v35, v20, v21
	global_store_dwordx2 v245, v[34:35], s[10:11]
	v_pk_mul_f32 v[22:23], v[22:23], v[248:249] op_sel_hi:[1,0]
	v_pk_add_f32 v[54:55], v[54:55], 1.0 op_sel_hi:[1,0]
	v_pk_mul_f32 v[22:23], v[6:7], v[22:23]
	v_pk_fma_f32 v[22:23], v[54:55], v[22:23], v[38:39]
	v_pk_mul_f32 v[24:25], v[24:25], v[248:249] op_sel_hi:[1,0]
	v_pk_add_f32 v[56:57], v[56:57], 1.0 op_sel_hi:[1,0]
	v_pk_mul_f32 v[24:25], v[8:9], v[24:25]
	v_pk_fma_f32 v[24:25], v[56:57], v[24:25], v[40:41]
	v_cvt_pk_bf16_f32 v38, v22, v23
	v_cvt_pk_bf16_f32 v39, v24, v25
	global_store_dwordx2 v245, v[38:39], s[10:11] offset:512
	v_pk_mul_f32 v[26:27], v[26:27], v[248:249] op_sel_hi:[1,0]
	v_pk_add_f32 v[58:59], v[58:59], 1.0 op_sel_hi:[1,0]
	v_pk_mul_f32 v[26:27], v[10:11], v[26:27]
	v_pk_fma_f32 v[26:27], v[58:59], v[26:27], v[42:43]
	v_pk_mul_f32 v[28:29], v[28:29], v[248:249] op_sel_hi:[1,0]
	v_pk_add_f32 v[60:61], v[60:61], 1.0 op_sel_hi:[1,0]
	v_pk_mul_f32 v[28:29], v[12:13], v[28:29]
	v_pk_fma_f32 v[28:29], v[60:61], v[28:29], v[44:45]
	v_cvt_pk_bf16_f32 v42, v26, v27
	v_cvt_pk_bf16_f32 v43, v28, v29
	global_store_dwordx2 v245, v[42:43], s[10:11] offset:1024
	v_pk_mul_f32 v[30:31], v[30:31], v[248:249] op_sel_hi:[1,0]
	v_pk_add_f32 v[62:63], v[62:63], 1.0 op_sel_hi:[1,0]
	v_pk_mul_f32 v[30:31], v[14:15], v[30:31]
	v_pk_fma_f32 v[30:31], v[62:63], v[30:31], v[46:47]
	v_pk_mul_f32 v[32:33], v[32:33], v[248:249] op_sel_hi:[1,0]
	v_pk_add_f32 v[64:65], v[64:65], 1.0 op_sel_hi:[1,0]
	v_pk_mul_f32 v[32:33], v[16:17], v[32:33]
	v_pk_fma_f32 v[32:33], v[64:65], v[32:33], v[48:49]
	v_cvt_pk_bf16_f32 v46, v30, v31
	v_cvt_pk_bf16_f32 v47, v32, v33
	global_store_dwordx2 v245, v[46:47], s[10:11] offset:1536
	s_waitcnt vmcnt(20)
	v_pk_mul_f32 v[246:247], v[66:67], v[66:67]
	v_pk_fma_f32 v[246:247], v[68:69], v[68:69], v[246:247]
	v_pk_fma_f32 v[246:247], v[70:71], v[70:71], v[246:247]
	v_pk_fma_f32 v[246:247], v[72:73], v[72:73], v[246:247]
	v_pk_fma_f32 v[246:247], v[74:75], v[74:75], v[246:247]
	v_pk_fma_f32 v[246:247], v[76:77], v[76:77], v[246:247]
	v_pk_fma_f32 v[246:247], v[78:79], v[78:79], v[246:247]
	v_pk_fma_f32 v[246:247], v[80:81], v[80:81], v[246:247]
	s_nop 0
	v_add_f32_e32 v246, v246, v247
	s_nop 1
	v_add_f32_dpp v246, v246, v246 quad_perm:[1,0,3,2] row_mask:0xf bank_mask:0xf
	s_nop 1
	v_add_f32_dpp v246, v246, v246 quad_perm:[2,3,0,1] row_mask:0xf bank_mask:0xf
	s_nop 1
	v_add_f32_dpp v246, v246, v246 row_half_mirror row_mask:0xf bank_mask:0xf
	s_nop 1
	v_add_f32_dpp v246, v246, v246 row_mirror row_mask:0xf bank_mask:0xf
	s_nop 1
	v_add_f32_dpp v246, v246, v246 row_bcast:15 row_mask:0xa bank_mask:0xf
	s_nop 1
	v_add_f32_dpp v246, v246, v246 row_bcast:31 row_mask:0xc bank_mask:0xf
	s_nop 1
	v_readlane_b32 s0, v246, 63
	s_add_i32 s21, s20, 14336
	s_lshl_b32 s21, s21, 11
	s_add_u32 s10, s16, s21
	s_addc_u32 s11, s17, 0
	v_mov_b32_e32 v248, s0
	v_fmamk_f32 v248, v248, 0x3a800000, v143
	v_rsq_f32_e32 v248, v248
	s_nop 0
	v_pk_mul_f32 v[66:67], v[66:67], v[248:249] op_sel_hi:[1,0]
	v_pk_add_f32 v[98:99], v[98:99], 1.0 op_sel_hi:[1,0]
	v_pk_mul_f32 v[66:67], v[2:3], v[66:67]
	v_pk_fma_f32 v[66:67], v[98:99], v[66:67], v[82:83]
	v_pk_mul_f32 v[68:69], v[68:69], v[248:249] op_sel_hi:[1,0]
	v_pk_add_f32 v[100:101], v[100:101], 1.0 op_sel_hi:[1,0]
	v_pk_mul_f32 v[68:69], v[4:5], v[68:69]
	v_pk_fma_f32 v[68:69], v[100:101], v[68:69], v[84:85]
	v_cvt_pk_bf16_f32 v82, v66, v67
	v_cvt_pk_bf16_f32 v83, v68, v69
	global_store_dwordx2 v245, v[82:83], s[10:11]
	v_pk_mul_f32 v[70:71], v[70:71], v[248:249] op_sel_hi:[1,0]
	v_pk_add_f32 v[102:103], v[102:103], 1.0 op_sel_hi:[1,0]
	v_pk_mul_f32 v[70:71], v[6:7], v[70:71]
	v_pk_fma_f32 v[70:71], v[102:103], v[70:71], v[86:87]
	v_pk_mul_f32 v[72:73], v[72:73], v[248:249] op_sel_hi:[1,0]
	v_pk_add_f32 v[104:105], v[104:105], 1.0 op_sel_hi:[1,0]
	v_pk_mul_f32 v[72:73], v[8:9], v[72:73]
	v_pk_fma_f32 v[72:73], v[104:105], v[72:73], v[88:89]
	v_cvt_pk_bf16_f32 v86, v70, v71
	v_cvt_pk_bf16_f32 v87, v72, v73
	global_store_dwordx2 v245, v[86:87], s[10:11] offset:512
	v_pk_mul_f32 v[74:75], v[74:75], v[248:249] op_sel_hi:[1,0]
	v_pk_add_f32 v[106:107], v[106:107], 1.0 op_sel_hi:[1,0]
	v_pk_mul_f32 v[74:75], v[10:11], v[74:75]
	v_pk_fma_f32 v[74:75], v[106:107], v[74:75], v[90:91]
	v_pk_mul_f32 v[76:77], v[76:77], v[248:249] op_sel_hi:[1,0]
	v_pk_add_f32 v[108:109], v[108:109], 1.0 op_sel_hi:[1,0]
	v_pk_mul_f32 v[76:77], v[12:13], v[76:77]
	v_pk_fma_f32 v[76:77], v[108:109], v[76:77], v[92:93]
	v_cvt_pk_bf16_f32 v90, v74, v75
	v_cvt_pk_bf16_f32 v91, v76, v77
	global_store_dwordx2 v245, v[90:91], s[10:11] offset:1024
	v_pk_mul_f32 v[78:79], v[78:79], v[248:249] op_sel_hi:[1,0]
	v_pk_add_f32 v[118:119], v[118:119], 1.0 op_sel_hi:[1,0]
	v_pk_mul_f32 v[78:79], v[14:15], v[78:79]
	v_pk_fma_f32 v[78:79], v[118:119], v[78:79], v[94:95]
	v_pk_mul_f32 v[80:81], v[80:81], v[248:249] op_sel_hi:[1,0]
	v_pk_add_f32 v[120:121], v[120:121], 1.0 op_sel_hi:[1,0]
	v_pk_mul_f32 v[80:81], v[16:17], v[80:81]
	v_pk_fma_f32 v[80:81], v[120:121], v[80:81], v[96:97]
	v_cvt_pk_bf16_f32 v94, v78, v79
	v_cvt_pk_bf16_f32 v95, v80, v81
	global_store_dwordx2 v245, v[94:95], s[10:11] offset:1536
	s_waitcnt vmcnt(8)
; DI unsigned pk_bf16(float lo, float hi) { f32x2 v = {lo, hi}; bf16v2 b = __builtin_convertvector(v, bf16v2); return __builtin_bit_cast(unsigned, b); }
; DI float red64(float x) { for (int o = 32; o > 0; o >>= 1) x += __shfl_xor(x, o); return x; }
; DI void modnorm_rows(const Params& p, int l, int which  , bool from_inputs, bool skip_ctx, int w0, int wstride, int lane) {
;     ...
;     float ss = 0.f;
; #pragma unroll
;     for (int q = 0; q < 4; ++q) ss += v[q][0] * v[q][0] + v[q][1] * v[q][1] + v[q][2] * v[q][2] + v[q][3] * v[q][3];
;     ss = red64(ss);
;     const float rs = rsqrtf(ss * (1.f / 1024.f) + EPSF);
;     bf16_t* dst = p.HY + (size_t)row * DM;
; #pragma unroll
;     for (int q = 0; q < 4; ++q) {
;       float o[4];
; #pragma unroll
;       for (int j = 0; j < 4; ++j) o[j] = (v[q][j] * rs * gg[q][j]) * (1.f + sc[q][j]) + sh[q][j];
;       u32x2 w = {pk_bf16(o[0], o[1]), pk_bf16(o[2], o[3])};
;       *(u32x2*)(dst + q * 256 + lane * 4) = w;
;     }
	v_pk_mul_f32 v[246:247], v[122:123], v[122:123]
	v_pk_fma_f32 v[246:247], v[124:125], v[124:125], v[246:247]
	v_pk_fma_f32 v[246:247], v[126:127], v[126:127], v[246:247]
	v_pk_fma_f32 v[246:247], v[128:129], v[128:129], v[246:247]
	v_pk_fma_f32 v[246:247], v[130:131], v[130:131], v[246:247]
	v_pk_fma_f32 v[246:247], v[132:133], v[132:133], v[246:247]
	v_pk_fma_f32 v[246:247], v[134:135], v[134:135], v[246:247]
	v_pk_fma_f32 v[246:247], v[136:137], v[136:137], v[246:247]
	s_nop 0
	v_add_f32_e32 v246, v246, v247
	s_nop 1
	v_add_f32_dpp v246, v246, v246 quad_perm:[1,0,3,2] row_mask:0xf bank_mask:0xf
	s_nop 1
	v_add_f32_dpp v246, v246, v246 quad_perm:[2,3,0,1] row_mask:0xf bank_mask:0xf
	s_nop 1
	v_add_f32_dpp v246, v246, v246 row_half_mirror row_mask:0xf bank_mask:0xf
	s_nop 1
	v_add_f32_dpp v246, v246, v246 row_mirror row_mask:0xf bank_mask:0xf
	s_nop 1
	v_add_f32_dpp v246, v246, v246 row_bcast:15 row_mask:0xa bank_mask:0xf
	s_nop 1
	v_add_f32_dpp v246, v246, v246 row_bcast:31 row_mask:0xc bank_mask:0xf
	s_nop 1
	v_readlane_b32 s0, v246, 63
	s_add_i32 s21, s20, 16384
	s_lshl_b32 s21, s21, 11
	s_add_u32 s10, s16, s21
	s_addc_u32 s11, s17, 0
	v_mov_b32_e32 v248, s0
	v_fmamk_f32 v248, v248, 0x3a800000, v143
	v_rsq_f32_e32 v248, v248
	s_nop 0
	v_pk_mul_f32 v[122:123], v[122:123], v[248:249] op_sel_hi:[1,0]
	v_pk_add_f32 v[176:177], v[176:177], 1.0 op_sel_hi:[1,0]
	v_pk_mul_f32 v[122:123], v[2:3], v[122:123]
	v_pk_fma_f32 v[122:123], v[176:177], v[122:123], v[160:161]
	v_pk_mul_f32 v[124:125], v[124:125], v[248:249] op_sel_hi:[1,0]
	v_pk_add_f32 v[178:179], v[178:179], 1.0 op_sel_hi:[1,0]
	v_pk_mul_f32 v[124:125], v[4:5], v[124:125]
	v_pk_fma_f32 v[124:125], v[178:179], v[124:125], v[162:163]
	v_cvt_pk_bf16_f32 v160, v122, v123
	v_cvt_pk_bf16_f32 v161, v124, v125
	global_store_dwordx2 v245, v[160:161], s[10:11]
	v_pk_mul_f32 v[126:127], v[126:127], v[248:249] op_sel_hi:[1,0]
	v_pk_add_f32 v[180:181], v[180:181], 1.0 op_sel_hi:[1,0]
	v_pk_mul_f32 v[126:127], v[6:7], v[126:127]
	v_pk_fma_f32 v[126:127], v[180:181], v[126:127], v[164:165]
	v_pk_mul_f32 v[128:129], v[128:129], v[248:249] op_sel_hi:[1,0]
	v_pk_add_f32 v[182:183], v[182:183], 1.0 op_sel_hi:[1,0]
	v_pk_mul_f32 v[128:129], v[8:9], v[128:129]
	v_pk_fma_f32 v[128:129], v[182:183], v[128:129], v[166:167]
	v_cvt_pk_bf16_f32 v164, v126, v127
	v_cvt_pk_bf16_f32 v165, v128, v129
	global_store_dwordx2 v245, v[164:165], s[10:11] offset:512
	v_pk_mul_f32 v[130:131], v[130:131], v[248:249] op_sel_hi:[1,0]
	v_pk_add_f32 v[184:185], v[184:185], 1.0 op_sel_hi:[1,0]
	v_pk_mul_f32 v[130:131], v[10:11], v[130:131]
	v_pk_fma_f32 v[130:131], v[184:185], v[130:131], v[168:169]
	v_pk_mul_f32 v[132:133], v[132:133], v[248:249] op_sel_hi:[1,0]
	v_pk_add_f32 v[186:187], v[186:187], 1.0 op_sel_hi:[1,0]
	v_pk_mul_f32 v[132:133], v[12:13], v[132:133]
	v_pk_fma_f32 v[132:133], v[186:187], v[132:133], v[170:171]
	v_cvt_pk_bf16_f32 v168, v130, v131
	v_cvt_pk_bf16_f32 v169, v132, v133
	global_store_dwordx2 v245, v[168:169], s[10:11] offset:1024
	v_pk_mul_f32 v[134:135], v[134:135], v[248:249] op_sel_hi:[1,0]
	v_pk_add_f32 v[188:189], v[188:189], 1.0 op_sel_hi:[1,0]
	v_pk_mul_f32 v[134:135], v[14:15], v[134:135]
	v_pk_fma_f32 v[134:135], v[188:189], v[134:135], v[172:173]
	v_pk_mul_f32 v[136:137], v[136:137], v[248:249] op_sel_hi:[1,0]
	v_pk_add_f32 v[190:191], v[190:191], 1.0 op_sel_hi:[1,0]
	v_pk_mul_f32 v[136:137], v[16:17], v[136:137]
	v_pk_fma_f32 v[136:137], v[190:191], v[136:137], v[174:175]
	v_cvt_pk_bf16_f32 v172, v134, v135
	v_cvt_pk_bf16_f32 v173, v136, v137
	global_store_dwordx2 v245, v[172:173], s[10:11] offset:1536
	s_branch .Lnorm1_done
.Lnorm1_done:
.LBB0_852:
	s_or_b64 exec, exec, s[2:3]
	s_mov_b64 s[80:81], s[54:55]
	s_branch .Ltramp_latch_mid
